# v29 with each staging load issued 4 MFMA slots (instead of 2) after the LDS write that frees its registers
# speedup vs baseline: 1.0065x; 1.0037x over previous
; DI f32x4 mfma16(bf16x8 a, bf16x8 b, f32x4 c) { return __builtin_amdgcn_mfma_f32_16x16x32_bf16(a, b, c, 0, 0, 0); }
; template <int MI, int NJ, bool SWAP, class AP, class BP>
; DI void gemm_main(f32x4 (&acc)[MI][NJ], const AP& ap, int a_kstep, const BP& bp, int b_kstep, int nk, bf16_t* smem) {
;     ...
;   auto gload = [&](int kt) {
;     const bf16_t* ab = ap.base + (size_t)kt * a_kstep; const bf16_t* bb = bp.base + (size_t)kt * b_kstep;
; #pragma unroll
;     for (int i = 0; i < CA; ++i) ra[i] = *(const u32x4*)(ab + pa[i]);
; #pragma unroll
;     for (int i = 0; i < CB; ++i) rb[i] = *(const u32x4*)(bb + pb[i]);
;   };
;   auto sstore = [&](int buf) {
;     bf16_t* As = smem + buf * L::STAGE; bf16_t* Bs = As + L::A_ELEMS;
; #pragma unroll
;     for (int i = 0; i < CA; ++i) { const int c = tid + NTHR * i; *(u32x4*)(As + (c >> 3) * LDT + (c & 7) * 8) = oka[i] ? ra[i] : (u32x4){0u, 0u, 0u, 0u}; }
; #pragma unroll
;     for (int i = 0; i < CB; ++i) { const int c = tid + NTHR * i; *(u32x4*)(Bs + (c >> 3) * LDT + (c & 7) * 8) = rb[i]; }
;   };
;   gload(0); sstore(0); gload(nk > 1 ? 1 : 0); __syncthreads();
; #pragma unroll 1
;   for (int kt = 0; kt < nk; ++kt) {
;     const int buf = kt & 1;
;     sstore(buf ^ 1);
;     gload(kt + 2 < nk ? kt + 2 : nk - 1);
;     __builtin_amdgcn_sched_barrier(0);
;     const bf16_t* As = smem + buf * L::STAGE + (wm * 16 * MI + l15) * LDT + quad * 8;
;     const bf16_t* Bs = smem + buf * L::STAGE + L::A_ELEMS + (wn * 16 * NJ + l15) * LDT + quad * 8;
; #pragma unroll
;     for (int ks = 0; ks < 2; ++ks) {
;       if (MI * NJ >= 32 && ks == 1) asm volatile("" ::: "memory");
;       bf16x8 b[NJ];
; #pragma unroll
;       for (int j = 0; j < NJ; ++j) b[j] = *(const bf16x8*)(Bs + j * 16 * LDT + ks * 32);
; #pragma unroll
;       for (int i = 0; i < MI; ++i) {
;         const bf16x8 a = *(const bf16x8*)(As + i * 16 * LDT + ks * 32);
; #pragma unroll
;         for (int j = 0; j < NJ; ++j) acc[i][j] = SWAP ? mfma16(b[j], a, acc[i][j]) : mfma16(a, b[j], acc[i][j]);
;       }
;     }
;     __syncthreads();
;   }
.Lgm0_main:
	ds_read_b128 v[242:245], v176 offset:4608
	s_waitcnt lgkmcnt(4)
	v_mfma_f32_16x16x32_bf16 v[124:127], v[178:181], v[212:215], v[124:127]
	s_waitcnt lgkmcnt(3)
	v_mfma_f32_16x16x32_bf16 v[120:123], v[200:203], v[212:215], v[120:123]
	s_waitcnt lgkmcnt(2)
	v_mfma_f32_16x16x32_bf16 v[116:119], v[204:207], v[212:215], v[116:119]
	s_and_b32 s5, s4, 1
	s_min_u32 s6, s4, 13
	s_xor_b32 s7, s5, 1
	s_mul_i32 s7, s7, 0x12000
	v_add3_u32 v250, s7, v171, v169
	s_waitcnt vmcnt(7)
	ds_write_b128 v250, v[128:131]
	s_waitcnt lgkmcnt(2)
	v_mfma_f32_16x16x32_bf16 v[112:115], v[208:211], v[212:215], v[112:115]
	ds_read_b128 v[246:249], v176 offset:6912
	v_mfma_f32_16x16x32_bf16 v[108:111], v[178:181], v[216:219], v[108:111]
	v_mfma_f32_16x16x32_bf16 v[104:107], v[200:203], v[216:219], v[104:107]
	v_mfma_f32_16x16x32_bf16 v[100:103], v[204:207], v[216:219], v[100:103]
	s_lshl_b32 s33, s6, 7
	s_add_u32 s6, s0, s33
	v_add3_u32 v251, s7, v173, v169
	v_add3_u32 v252, s7, v174, v169
	v_add3_u32 v253, s7, v175, v169
	s_addc_u32 s7, s1, 0
	v_lshl_add_u64 v[128:129], s[6:7], 0, v[160:161]
	s_nop 0
	global_load_dwordx4 v[128:131], v[128:129], off offset:256
	v_mfma_f32_16x16x32_bf16 v[96:99], v[208:211], v[216:219], v[96:99]
	ds_read_b128 v[212:215], v176 offset:9216
	s_waitcnt lgkmcnt(3)
	v_mfma_f32_16x16x32_bf16 v[92:95], v[178:181], v[242:245], v[92:95]
	s_waitcnt vmcnt(7)
	ds_write_b128 v251, v[132:135]
	v_mfma_f32_16x16x32_bf16 v[88:91], v[200:203], v[242:245], v[88:91]
	v_mfma_f32_16x16x32_bf16 v[84:87], v[204:207], v[242:245], v[84:87]
	v_mfma_f32_16x16x32_bf16 v[80:83], v[208:211], v[242:245], v[80:83]
	ds_read_b128 v[216:219], v176 offset:11520
	s_waitcnt lgkmcnt(3)
	v_mfma_f32_16x16x32_bf16 v[76:79], v[178:181], v[246:249], v[76:79]
	v_lshl_add_u64 v[132:133], s[6:7], 0, v[162:163]
	s_nop 0
	global_load_dwordx4 v[132:135], v[132:133], off offset:256
	v_mfma_f32_16x16x32_bf16 v[72:75], v[200:203], v[246:249], v[72:75]
	v_mfma_f32_16x16x32_bf16 v[68:71], v[204:207], v[246:249], v[68:71]
	s_waitcnt vmcnt(7)
	ds_write_b128 v252, v[136:139]
	v_mfma_f32_16x16x32_bf16 v[64:67], v[208:211], v[246:249], v[64:67]
	ds_read_b128 v[242:245], v176 offset:13824
	s_waitcnt lgkmcnt(4)
	v_mfma_f32_16x16x32_bf16 v[60:63], v[178:181], v[212:215], v[60:63]
	v_mfma_f32_16x16x32_bf16 v[56:59], v[200:203], v[212:215], v[56:59]
	v_mfma_f32_16x16x32_bf16 v[52:55], v[204:207], v[212:215], v[52:55]
	v_lshl_add_u64 v[136:137], s[6:7], 0, v[164:165]
	s_nop 0
	global_load_dwordx4 v[136:139], v[136:137], off offset:256
	v_mfma_f32_16x16x32_bf16 v[48:51], v[208:211], v[212:215], v[48:51]
	ds_read_b128 v[246:249], v176 offset:16128
	s_waitcnt lgkmcnt(3)
	v_mfma_f32_16x16x32_bf16 v[44:47], v[178:181], v[216:219], v[44:47]
	s_waitcnt vmcnt(7)
	ds_write_b128 v253, v[140:143]
	v_mfma_f32_16x16x32_bf16 v[40:43], v[200:203], v[216:219], v[40:43]
	v_mfma_f32_16x16x32_bf16 v[36:39], v[204:207], v[216:219], v[36:39]
	v_mfma_f32_16x16x32_bf16 v[32:35], v[208:211], v[216:219], v[32:35]
	ds_read_b128 v[212:215], v176 offset:64
	s_waitcnt lgkmcnt(3)
	v_mfma_f32_16x16x32_bf16 v[28:31], v[178:181], v[242:245], v[28:31]
	v_lshl_add_u64 v[140:141], s[6:7], 0, v[166:167]
	s_nop 0
	global_load_dwordx4 v[140:143], v[140:141], off offset:256
	v_mfma_f32_16x16x32_bf16 v[24:27], v[200:203], v[242:245], v[24:27]
	v_mfma_f32_16x16x32_bf16 v[20:23], v[204:207], v[242:245], v[20:23]
	s_waitcnt vmcnt(7)
	ds_write_b128 v250, v[144:147] offset:36864
	v_mfma_f32_16x16x32_bf16 v[16:19], v[208:211], v[242:245], v[16:19]
	ds_read_b128 v[216:219], v176 offset:2368
	s_waitcnt lgkmcnt(4)
	v_mfma_f32_16x16x32_bf16 v[12:15], v[178:181], v[246:249], v[12:15]
	ds_read_b128 v[178:181], v182 offset:36928
	v_mfma_f32_16x16x32_bf16 v[8:11], v[200:203], v[246:249], v[8:11]
	ds_read_b128 v[200:203], v182 offset:39232
	v_mfma_f32_16x16x32_bf16 v[0:3], v[204:207], v[246:249], v[0:3]
	ds_read_b128 v[204:207], v182 offset:41536
	s_add_u32 s6, s2, s33
	s_addc_u32 s7, s3, 0
	v_lshl_add_u64 v[144:145], s[6:7], 0, v[160:161]
	s_nop 0
	global_load_dwordx4 v[144:147], v[144:145], off offset:256
	v_mfma_f32_16x16x32_bf16 v[4:7], v[208:211], v[246:249], v[4:7]
	ds_read_b128 v[208:211], v182 offset:43840
	ds_read_b128 v[242:245], v176 offset:4672
	s_waitcnt lgkmcnt(4)
	v_mfma_f32_16x16x32_bf16 v[124:127], v[178:181], v[212:215], v[124:127]
	s_waitcnt vmcnt(7)
	ds_write_b128 v251, v[148:151] offset:36864
	s_waitcnt lgkmcnt(4)
	v_mfma_f32_16x16x32_bf16 v[120:123], v[200:203], v[212:215], v[120:123]
	s_waitcnt lgkmcnt(3)
	v_mfma_f32_16x16x32_bf16 v[116:119], v[204:207], v[212:215], v[116:119]
	s_waitcnt lgkmcnt(2)
	v_mfma_f32_16x16x32_bf16 v[112:115], v[208:211], v[212:215], v[112:115]
	ds_read_b128 v[246:249], v176 offset:6976
	v_mfma_f32_16x16x32_bf16 v[108:111], v[178:181], v[216:219], v[108:111]
	v_lshl_add_u64 v[148:149], s[6:7], 0, v[162:163]
	s_nop 0
	global_load_dwordx4 v[148:151], v[148:149], off offset:256
	v_mfma_f32_16x16x32_bf16 v[104:107], v[200:203], v[216:219], v[104:107]
	v_mfma_f32_16x16x32_bf16 v[100:103], v[204:207], v[216:219], v[100:103]
	s_waitcnt vmcnt(7)
	ds_write_b128 v252, v[152:155] offset:36864
	v_mfma_f32_16x16x32_bf16 v[96:99], v[208:211], v[216:219], v[96:99]
	ds_read_b128 v[212:215], v176 offset:9280
	s_waitcnt lgkmcnt(4)
	v_mfma_f32_16x16x32_bf16 v[92:95], v[178:181], v[242:245], v[92:95]
	v_mfma_f32_16x16x32_bf16 v[88:91], v[200:203], v[242:245], v[88:91]
	v_mfma_f32_16x16x32_bf16 v[84:87], v[204:207], v[242:245], v[84:87]
	v_lshl_add_u64 v[152:153], s[6:7], 0, v[164:165]
	s_nop 0
	global_load_dwordx4 v[152:155], v[152:153], off offset:256
	v_mfma_f32_16x16x32_bf16 v[80:83], v[208:211], v[242:245], v[80:83]
	ds_read_b128 v[216:219], v176 offset:11584
	s_waitcnt lgkmcnt(3)
	v_mfma_f32_16x16x32_bf16 v[76:79], v[178:181], v[246:249], v[76:79]
	s_waitcnt vmcnt(7)
	ds_write_b128 v253, v[156:159] offset:36864
	v_mfma_f32_16x16x32_bf16 v[72:75], v[200:203], v[246:249], v[72:75]
	v_mfma_f32_16x16x32_bf16 v[68:71], v[204:207], v[246:249], v[68:71]
	v_mfma_f32_16x16x32_bf16 v[64:67], v[208:211], v[246:249], v[64:67]
	ds_read_b128 v[242:245], v176 offset:13888
	s_waitcnt lgkmcnt(3)
	v_mfma_f32_16x16x32_bf16 v[60:63], v[178:181], v[212:215], v[60:63]
	v_lshl_add_u64 v[156:157], s[6:7], 0, v[166:167]
	s_nop 0
	global_load_dwordx4 v[156:159], v[156:157], off offset:256
	v_mfma_f32_16x16x32_bf16 v[56:59], v[200:203], v[212:215], v[56:59]
	v_mfma_f32_16x16x32_bf16 v[52:55], v[204:207], v[212:215], v[52:55]
	v_mfma_f32_16x16x32_bf16 v[48:51], v[208:211], v[212:215], v[48:51]
	ds_read_b128 v[246:249], v176 offset:16192
	s_waitcnt lgkmcnt(3)
	v_mfma_f32_16x16x32_bf16 v[44:47], v[178:181], v[216:219], v[44:47]
	v_mfma_f32_16x16x32_bf16 v[40:43], v[200:203], v[216:219], v[40:43]
	v_mfma_f32_16x16x32_bf16 v[36:39], v[204:207], v[216:219], v[36:39]
	v_mfma_f32_16x16x32_bf16 v[32:35], v[208:211], v[216:219], v[32:35]
	s_add_i32 s4, s4, 1
	s_and_b32 s98, s4, 1
	s_mul_i32 s98, s98, 0x12000
	v_add3_u32 v182, s98, v168, v172
	v_add3_u32 v176, s98, v170, v172
	s_cmp_lg_u32 s4, 16
	s_waitcnt lgkmcnt(0)
	s_barrier
; DI f32x4 mfma16(bf16x8 a, bf16x8 b, f32x4 c) { return __builtin_amdgcn_mfma_f32_16x16x32_bf16(a, b, c, 0, 0, 0); }
; template <int MI, int NJ, bool SWAP, class AP, class BP>
; DI void gemm_main(f32x4 (&acc)[MI][NJ], const AP& ap, int a_kstep, const BP& bp, int b_kstep, int nk, bf16_t* smem) {
;     ...
;   for (int kt = 0; kt < nk; ++kt) {
;     const int buf = kt & 1;
;     sstore(buf ^ 1);
;     gload(kt + 2 < nk ? kt + 2 : nk - 1);
;     __builtin_amdgcn_sched_barrier(0);
;     const bf16_t* As = smem + buf * L::STAGE + (wm * 16 * MI + l15) * LDT + quad * 8;
;     const bf16_t* Bs = smem + buf * L::STAGE + L::A_ELEMS + (wn * 16 * NJ + l15) * LDT + quad * 8;
; #pragma unroll
;     for (int ks = 0; ks < 2; ++ks) {
;       if (MI * NJ >= 32 && ks == 1) asm volatile("" ::: "memory");
;       bf16x8 b[NJ];
; #pragma unroll
;       for (int j = 0; j < NJ; ++j) b[j] = *(const bf16x8*)(Bs + j * 16 * LDT + ks * 32);
; #pragma unroll
;       for (int i = 0; i < MI; ++i) {
;         const bf16x8 a = *(const bf16x8*)(As + i * 16 * LDT + ks * 32);
; #pragma unroll
;         for (int j = 0; j < NJ; ++j) acc[i][j] = SWAP ? mfma16(b[j], a, acc[i][j]) : mfma16(a, b[j], acc[i][j]);
;       }
;     }
;     __syncthreads();
;   }
	s_cbranch_scc0 .Lgm0_exit
	ds_read_b128 v[212:215], v176
	ds_read_b128 v[216:219], v176 offset:2304
	v_mfma_f32_16x16x32_bf16 v[28:31], v[178:181], v[242:245], v[28:31]
	v_mfma_f32_16x16x32_bf16 v[12:15], v[178:181], v[246:249], v[12:15]
	ds_read_b128 v[178:181], v182 offset:36864
	v_mfma_f32_16x16x32_bf16 v[24:27], v[200:203], v[242:245], v[24:27]
	v_mfma_f32_16x16x32_bf16 v[8:11], v[200:203], v[246:249], v[8:11]
	ds_read_b128 v[200:203], v182 offset:39168
	v_mfma_f32_16x16x32_bf16 v[20:23], v[204:207], v[242:245], v[20:23]
	v_mfma_f32_16x16x32_bf16 v[0:3], v[204:207], v[246:249], v[0:3]
	ds_read_b128 v[204:207], v182 offset:41472
	v_mfma_f32_16x16x32_bf16 v[16:19], v[208:211], v[242:245], v[16:19]
	v_mfma_f32_16x16x32_bf16 v[4:7], v[208:211], v[246:249], v[4:7]
	ds_read_b128 v[208:211], v182 offset:43776
	s_branch .Lgm0_main

; DI f32x4 mfma16(bf16x8 a, bf16x8 b, f32x4 c) { return __builtin_amdgcn_mfma_f32_16x16x32_bf16(a, b, c, 0, 0, 0); }
; template <int MI, int NJ, bool SWAP, class AP, class BP>
; DI void gemm_main(f32x4 (&acc)[MI][NJ], const AP& ap, int a_kstep, const BP& bp, int b_kstep, int nk, bf16_t* smem) {
;     ...
;   auto gload = [&](int kt) {
;     const bf16_t* ab = ap.base + (size_t)kt * a_kstep; const bf16_t* bb = bp.base + (size_t)kt * b_kstep;
; #pragma unroll
;     for (int i = 0; i < CA; ++i) ra[i] = *(const u32x4*)(ab + pa[i]);
; #pragma unroll
;     for (int i = 0; i < CB; ++i) rb[i] = *(const u32x4*)(bb + pb[i]);
;   };
;   auto sstore = [&](int buf) {
;     bf16_t* As = smem + buf * L::STAGE; bf16_t* Bs = As + L::A_ELEMS;
; #pragma unroll
;     for (int i = 0; i < CA; ++i) { const int c = tid + NTHR * i; *(u32x4*)(As + (c >> 3) * LDT + (c & 7) * 8) = oka[i] ? ra[i] : (u32x4){0u, 0u, 0u, 0u}; }
; #pragma unroll
;     for (int i = 0; i < CB; ++i) { const int c = tid + NTHR * i; *(u32x4*)(Bs + (c >> 3) * LDT + (c & 7) * 8) = rb[i]; }
;   };
;   gload(0); sstore(0); gload(nk > 1 ? 1 : 0); __syncthreads();
; #pragma unroll 1
;   for (int kt = 0; kt < nk; ++kt) {
;     const int buf = kt & 1;
;     sstore(buf ^ 1);
;     gload(kt + 2 < nk ? kt + 2 : nk - 1);
;     __builtin_amdgcn_sched_barrier(0);
;     const bf16_t* As = smem + buf * L::STAGE + (wm * 16 * MI + l15) * LDT + quad * 8;
;     const bf16_t* Bs = smem + buf * L::STAGE + L::A_ELEMS + (wn * 16 * NJ + l15) * LDT + quad * 8;
; #pragma unroll
;     for (int ks = 0; ks < 2; ++ks) {
;       if (MI * NJ >= 32 && ks == 1) asm volatile("" ::: "memory");
;       bf16x8 b[NJ];
; #pragma unroll
;       for (int j = 0; j < NJ; ++j) b[j] = *(const bf16x8*)(Bs + j * 16 * LDT + ks * 32);
; #pragma unroll
;       for (int i = 0; i < MI; ++i) {
;         const bf16x8 a = *(const bf16x8*)(As + i * 16 * LDT + ks * 32);
; #pragma unroll
;         for (int j = 0; j < NJ; ++j) acc[i][j] = SWAP ? mfma16(b[j], a, acc[i][j]) : mfma16(a, b[j], acc[i][j]);
;       }
;     }
;     __syncthreads();
;   }
.Lgm1_main:
	ds_read_b128 v[242:245], v176 offset:4608
	s_waitcnt lgkmcnt(4)
	v_mfma_f32_16x16x32_bf16 v[124:127], v[212:215], v[178:181], v[124:127]
	s_waitcnt lgkmcnt(3)
	v_mfma_f32_16x16x32_bf16 v[120:123], v[212:215], v[200:203], v[120:123]
	s_waitcnt lgkmcnt(2)
	v_mfma_f32_16x16x32_bf16 v[116:119], v[212:215], v[204:207], v[116:119]
	v_lshlrev_b32_e32 v250, 1, v168
	s_and_b32 s5, s4, 1
	s_min_u32 s6, s4, 13
	s_xor_b32 s7, s5, 1
	s_mul_i32 s7, s7, 0x12000
	v_add3_u32 v250, s7, v250, v170
	s_waitcnt vmcnt(7)
	ds_write_b128 v250, v[128:131]
	s_waitcnt lgkmcnt(2)
	v_mfma_f32_16x16x32_bf16 v[112:115], v[212:215], v[208:211], v[112:115]
	ds_read_b128 v[246:249], v176 offset:6912
	v_mfma_f32_16x16x32_bf16 v[108:111], v[216:219], v[178:181], v[108:111]
	v_mfma_f32_16x16x32_bf16 v[104:107], v[216:219], v[200:203], v[104:107]
	v_mfma_f32_16x16x32_bf16 v[100:103], v[216:219], v[204:207], v[100:103]
	s_lshl_b32 s33, s6, 7
	s_add_u32 s6, s0, s33
	v_lshlrev_b32_e32 v251, 1, v171
	v_add3_u32 v251, s7, v251, v170
	v_lshlrev_b32_e32 v252, 1, v172
	v_add3_u32 v252, s7, v252, v170
	v_lshlrev_b32_e32 v253, 1, v173
	v_add3_u32 v253, s7, v253, v170
	s_addc_u32 s7, s1, 0
	v_lshl_add_u64 v[128:129], s[6:7], 0, v[160:161]
	s_nop 0
	global_load_dwordx4 v[128:131], v[128:129], off offset:256
	v_mfma_f32_16x16x32_bf16 v[96:99], v[216:219], v[208:211], v[96:99]
	ds_read_b128 v[212:215], v176 offset:9216
	s_waitcnt lgkmcnt(3)
	v_mfma_f32_16x16x32_bf16 v[92:95], v[242:245], v[178:181], v[92:95]
	s_waitcnt vmcnt(7)
	ds_write_b128 v251, v[132:135]
	v_mfma_f32_16x16x32_bf16 v[88:91], v[242:245], v[200:203], v[88:91]
	v_mfma_f32_16x16x32_bf16 v[84:87], v[242:245], v[204:207], v[84:87]
	v_mfma_f32_16x16x32_bf16 v[80:83], v[242:245], v[208:211], v[80:83]
	ds_read_b128 v[216:219], v176 offset:11520
	s_waitcnt lgkmcnt(3)
	v_mfma_f32_16x16x32_bf16 v[76:79], v[246:249], v[178:181], v[76:79]
	v_lshl_add_u64 v[132:133], s[6:7], 0, v[162:163]
	s_nop 0
	global_load_dwordx4 v[132:135], v[132:133], off offset:256
	v_mfma_f32_16x16x32_bf16 v[72:75], v[246:249], v[200:203], v[72:75]
	v_mfma_f32_16x16x32_bf16 v[68:71], v[246:249], v[204:207], v[68:71]
	s_waitcnt vmcnt(7)
	ds_write_b128 v252, v[136:139]
	v_mfma_f32_16x16x32_bf16 v[64:67], v[246:249], v[208:211], v[64:67]
	ds_read_b128 v[242:245], v176 offset:13824
	s_waitcnt lgkmcnt(4)
	v_mfma_f32_16x16x32_bf16 v[60:63], v[212:215], v[178:181], v[60:63]
	v_mfma_f32_16x16x32_bf16 v[56:59], v[212:215], v[200:203], v[56:59]
	v_mfma_f32_16x16x32_bf16 v[52:55], v[212:215], v[204:207], v[52:55]
	v_lshl_add_u64 v[136:137], s[6:7], 0, v[164:165]
	s_nop 0
	global_load_dwordx4 v[136:139], v[136:137], off offset:256
	v_mfma_f32_16x16x32_bf16 v[48:51], v[212:215], v[208:211], v[48:51]
	ds_read_b128 v[246:249], v176 offset:16128
	s_waitcnt lgkmcnt(3)
	v_mfma_f32_16x16x32_bf16 v[44:47], v[216:219], v[178:181], v[44:47]
	s_waitcnt vmcnt(7)
	ds_write_b128 v253, v[140:143]
	v_mfma_f32_16x16x32_bf16 v[40:43], v[216:219], v[200:203], v[40:43]
	v_mfma_f32_16x16x32_bf16 v[36:39], v[216:219], v[204:207], v[36:39]
	v_mfma_f32_16x16x32_bf16 v[32:35], v[216:219], v[208:211], v[32:35]
	ds_read_b128 v[212:215], v176 offset:64
	s_waitcnt lgkmcnt(3)
	v_mfma_f32_16x16x32_bf16 v[28:31], v[242:245], v[178:181], v[28:31]
	v_lshl_add_u64 v[140:141], s[6:7], 0, v[166:167]
	s_nop 0
	global_load_dwordx4 v[140:143], v[140:141], off offset:256
	v_mfma_f32_16x16x32_bf16 v[24:27], v[242:245], v[200:203], v[24:27]
	v_mfma_f32_16x16x32_bf16 v[20:23], v[242:245], v[204:207], v[20:23]
	s_waitcnt vmcnt(7)
	ds_write_b128 v250, v[144:147] offset:36864
	v_mfma_f32_16x16x32_bf16 v[16:19], v[242:245], v[208:211], v[16:19]
	ds_read_b128 v[216:219], v176 offset:2368
	s_waitcnt lgkmcnt(4)
; DI f32x4 mfma16(bf16x8 a, bf16x8 b, f32x4 c) { return __builtin_amdgcn_mfma_f32_16x16x32_bf16(a, b, c, 0, 0, 0); }
; template <int MI, int NJ, bool SWAP, class AP, class BP>
; DI void gemm_main(f32x4 (&acc)[MI][NJ], const AP& ap, int a_kstep, const BP& bp, int b_kstep, int nk, bf16_t* smem) {
;     ...
;   auto gload = [&](int kt) {
;     const bf16_t* ab = ap.base + (size_t)kt * a_kstep; const bf16_t* bb = bp.base + (size_t)kt * b_kstep;
; #pragma unroll
;     for (int i = 0; i < CA; ++i) ra[i] = *(const u32x4*)(ab + pa[i]);
; #pragma unroll
;     for (int i = 0; i < CB; ++i) rb[i] = *(const u32x4*)(bb + pb[i]);
;   };
;   auto sstore = [&](int buf) {
;     bf16_t* As = smem + buf * L::STAGE; bf16_t* Bs = As + L::A_ELEMS;
; #pragma unroll
;     for (int i = 0; i < CA; ++i) { const int c = tid + NTHR * i; *(u32x4*)(As + (c >> 3) * LDT + (c & 7) * 8) = oka[i] ? ra[i] : (u32x4){0u, 0u, 0u, 0u}; }
; #pragma unroll
;     for (int i = 0; i < CB; ++i) { const int c = tid + NTHR * i; *(u32x4*)(Bs + (c >> 3) * LDT + (c & 7) * 8) = rb[i]; }
;   };
;   gload(0); sstore(0); gload(nk > 1 ? 1 : 0); __syncthreads();
; #pragma unroll 1
;   for (int kt = 0; kt < nk; ++kt) {
;     const int buf = kt & 1;
;     sstore(buf ^ 1);
;     gload(kt + 2 < nk ? kt + 2 : nk - 1);
;     __builtin_amdgcn_sched_barrier(0);
;     const bf16_t* As = smem + buf * L::STAGE + (wm * 16 * MI + l15) * LDT + quad * 8;
;     const bf16_t* Bs = smem + buf * L::STAGE + L::A_ELEMS + (wn * 16 * NJ + l15) * LDT + quad * 8;
; #pragma unroll
;     for (int ks = 0; ks < 2; ++ks) {
;       if (MI * NJ >= 32 && ks == 1) asm volatile("" ::: "memory");
;       bf16x8 b[NJ];
; #pragma unroll
;       for (int j = 0; j < NJ; ++j) b[j] = *(const bf16x8*)(Bs + j * 16 * LDT + ks * 32);
; #pragma unroll
;       for (int i = 0; i < MI; ++i) {
;         const bf16x8 a = *(const bf16x8*)(As + i * 16 * LDT + ks * 32);
; #pragma unroll
;         for (int j = 0; j < NJ; ++j) acc[i][j] = SWAP ? mfma16(b[j], a, acc[i][j]) : mfma16(a, b[j], acc[i][j]);
;       }
;     }
;     __syncthreads();
;   }
	v_mfma_f32_16x16x32_bf16 v[8:11], v[246:249], v[178:181], v[8:11]
	ds_read_b128 v[178:181], v182 offset:36928
	v_mfma_f32_16x16x32_bf16 v[4:7], v[246:249], v[200:203], v[4:7]
	ds_read_b128 v[200:203], v182 offset:39232
	v_mfma_f32_16x16x32_bf16 v[0:3], v[246:249], v[204:207], v[0:3]
	ds_read_b128 v[204:207], v182 offset:41536
	s_add_u32 s6, s2, s33
	s_addc_u32 s7, s3, 0
	v_lshl_add_u64 v[144:145], s[6:7], 0, v[160:161]
	s_nop 0
	global_load_dwordx4 v[144:147], v[144:145], off offset:256
	v_mfma_f32_16x16x32_bf16 v[12:15], v[246:249], v[208:211], v[12:15]
	ds_read_b128 v[208:211], v182 offset:43840
	ds_read_b128 v[242:245], v176 offset:4672
	s_waitcnt lgkmcnt(4)
	v_mfma_f32_16x16x32_bf16 v[124:127], v[212:215], v[178:181], v[124:127]
	s_waitcnt vmcnt(7)
	ds_write_b128 v251, v[148:151] offset:36864
	s_waitcnt lgkmcnt(4)
	v_mfma_f32_16x16x32_bf16 v[120:123], v[212:215], v[200:203], v[120:123]
	s_waitcnt lgkmcnt(3)
	v_mfma_f32_16x16x32_bf16 v[116:119], v[212:215], v[204:207], v[116:119]
	s_waitcnt lgkmcnt(2)
	v_mfma_f32_16x16x32_bf16 v[112:115], v[212:215], v[208:211], v[112:115]
	ds_read_b128 v[246:249], v176 offset:6976
	v_mfma_f32_16x16x32_bf16 v[108:111], v[216:219], v[178:181], v[108:111]
	v_lshl_add_u64 v[148:149], s[6:7], 0, v[162:163]
	s_nop 0
	global_load_dwordx4 v[148:151], v[148:149], off offset:256
	v_mfma_f32_16x16x32_bf16 v[104:107], v[216:219], v[200:203], v[104:107]
	v_mfma_f32_16x16x32_bf16 v[100:103], v[216:219], v[204:207], v[100:103]
	s_waitcnt vmcnt(7)
	ds_write_b128 v252, v[152:155] offset:36864
	v_mfma_f32_16x16x32_bf16 v[96:99], v[216:219], v[208:211], v[96:99]
	ds_read_b128 v[212:215], v176 offset:9280
	s_waitcnt lgkmcnt(4)
	v_mfma_f32_16x16x32_bf16 v[92:95], v[242:245], v[178:181], v[92:95]
	v_mfma_f32_16x16x32_bf16 v[88:91], v[242:245], v[200:203], v[88:91]
	v_mfma_f32_16x16x32_bf16 v[84:87], v[242:245], v[204:207], v[84:87]
	v_lshl_add_u64 v[152:153], s[6:7], 0, v[164:165]
	s_nop 0
	global_load_dwordx4 v[152:155], v[152:153], off offset:256
	v_mfma_f32_16x16x32_bf16 v[80:83], v[242:245], v[208:211], v[80:83]
	ds_read_b128 v[216:219], v176 offset:11584
	s_waitcnt lgkmcnt(3)
	v_mfma_f32_16x16x32_bf16 v[76:79], v[246:249], v[178:181], v[76:79]
	s_waitcnt vmcnt(7)
	ds_write_b128 v253, v[156:159] offset:36864
	v_mfma_f32_16x16x32_bf16 v[72:75], v[246:249], v[200:203], v[72:75]
	v_mfma_f32_16x16x32_bf16 v[68:71], v[246:249], v[204:207], v[68:71]
	v_mfma_f32_16x16x32_bf16 v[64:67], v[246:249], v[208:211], v[64:67]
	ds_read_b128 v[242:245], v176 offset:13888
	s_waitcnt lgkmcnt(3)
	v_mfma_f32_16x16x32_bf16 v[60:63], v[212:215], v[178:181], v[60:63]
	v_lshl_add_u64 v[156:157], s[6:7], 0, v[166:167]
	s_nop 0
	global_load_dwordx4 v[156:159], v[156:157], off offset:256
	v_mfma_f32_16x16x32_bf16 v[56:59], v[212:215], v[200:203], v[56:59]
	v_mfma_f32_16x16x32_bf16 v[52:55], v[212:215], v[204:207], v[52:55]
	v_mfma_f32_16x16x32_bf16 v[48:51], v[212:215], v[208:211], v[48:51]
	ds_read_b128 v[246:249], v176 offset:16192
	s_waitcnt lgkmcnt(3)
	v_mfma_f32_16x16x32_bf16 v[44:47], v[216:219], v[178:181], v[44:47]
	v_mfma_f32_16x16x32_bf16 v[40:43], v[216:219], v[200:203], v[40:43]
	v_mfma_f32_16x16x32_bf16 v[36:39], v[216:219], v[204:207], v[36:39]
	v_mfma_f32_16x16x32_bf16 v[32:35], v[216:219], v[208:211], v[32:35]
	s_add_i32 s4, s4, 1
	s_and_b32 s98, s4, 1
	s_mul_i32 s98, s98, 0x12000
	v_add3_u32 v176, s98, v174, v175
	v_add3_u32 v182, s98, v169, v175
	s_cmp_lg_u32 s4, 16
	s_waitcnt lgkmcnt(0)
	s_barrier
	s_cbranch_scc0 .Lgm1_exit
	ds_read_b128 v[212:215], v176
	ds_read_b128 v[216:219], v176 offset:2304
	v_mfma_f32_16x16x32_bf16 v[28:31], v[242:245], v[178:181], v[28:31]
	v_mfma_f32_16x16x32_bf16 v[8:11], v[246:249], v[178:181], v[8:11]
	ds_read_b128 v[178:181], v182 offset:36864
	v_mfma_f32_16x16x32_bf16 v[24:27], v[242:245], v[200:203], v[24:27]
	v_mfma_f32_16x16x32_bf16 v[4:7], v[246:249], v[200:203], v[4:7]
	ds_read_b128 v[200:203], v182 offset:39168
	v_mfma_f32_16x16x32_bf16 v[20:23], v[242:245], v[204:207], v[20:23]
	v_mfma_f32_16x16x32_bf16 v[0:3], v[246:249], v[204:207], v[0:3]
	ds_read_b128 v[204:207], v182 offset:41472
	v_mfma_f32_16x16x32_bf16 v[16:19], v[242:245], v[208:211], v[16:19]
	v_mfma_f32_16x16x32_bf16 v[12:15], v[246:249], v[208:211], v[12:15]
	ds_read_b128 v[208:211], v182 offset:43776
	s_branch .Lgm1_main

; DI f32x4 mfma16(bf16x8 a, bf16x8 b, f32x4 c) { return __builtin_amdgcn_mfma_f32_16x16x32_bf16(a, b, c, 0, 0, 0); }
; template <int MI, int NJ, bool SWAP, class AP, class BP>
; DI void gemm_main(f32x4 (&acc)[MI][NJ], const AP& ap, int a_kstep, const BP& bp, int b_kstep, int nk, bf16_t* smem) {
;     ...
;   auto gload = [&](int kt) {
;     const bf16_t* ab = ap.base + (size_t)kt * a_kstep; const bf16_t* bb = bp.base + (size_t)kt * b_kstep;
; #pragma unroll
;     for (int i = 0; i < CA; ++i) ra[i] = *(const u32x4*)(ab + pa[i]);
; #pragma unroll
;     for (int i = 0; i < CB; ++i) rb[i] = *(const u32x4*)(bb + pb[i]);
;   };
;   auto sstore = [&](int buf) {
;     bf16_t* As = smem + buf * L::STAGE; bf16_t* Bs = As + L::A_ELEMS;
; #pragma unroll
;     for (int i = 0; i < CA; ++i) { const int c = tid + NTHR * i; *(u32x4*)(As + (c >> 3) * LDT + (c & 7) * 8) = oka[i] ? ra[i] : (u32x4){0u, 0u, 0u, 0u}; }
; #pragma unroll
;     for (int i = 0; i < CB; ++i) { const int c = tid + NTHR * i; *(u32x4*)(Bs + (c >> 3) * LDT + (c & 7) * 8) = rb[i]; }
;   };
;   gload(0); sstore(0); gload(nk > 1 ? 1 : 0); __syncthreads();
; #pragma unroll 1
;   for (int kt = 0; kt < nk; ++kt) {
;     const int buf = kt & 1;
;     sstore(buf ^ 1);
;     gload(kt + 2 < nk ? kt + 2 : nk - 1);
;     __builtin_amdgcn_sched_barrier(0);
;     const bf16_t* As = smem + buf * L::STAGE + (wm * 16 * MI + l15) * LDT + quad * 8;
;     const bf16_t* Bs = smem + buf * L::STAGE + L::A_ELEMS + (wn * 16 * NJ + l15) * LDT + quad * 8;
; #pragma unroll
;     for (int ks = 0; ks < 2; ++ks) {
;       if (MI * NJ >= 32 && ks == 1) asm volatile("" ::: "memory");
;       bf16x8 b[NJ];
; #pragma unroll
;       for (int j = 0; j < NJ; ++j) b[j] = *(const bf16x8*)(Bs + j * 16 * LDT + ks * 32);
; #pragma unroll
;       for (int i = 0; i < MI; ++i) {
;         const bf16x8 a = *(const bf16x8*)(As + i * 16 * LDT + ks * 32);
; #pragma unroll
;         for (int j = 0; j < NJ; ++j) acc[i][j] = SWAP ? mfma16(b[j], a, acc[i][j]) : mfma16(a, b[j], acc[i][j]);
;       }
;     }
;     __syncthreads();
;   }
.Lgm2_main:
	ds_read_b128 v[242:245], v182 offset:4608
	s_waitcnt lgkmcnt(4)
	v_mfma_f32_16x16x32_bf16 v[156:159], v[178:181], v[198:201], v[156:159]
	s_waitcnt lgkmcnt(3)
	v_mfma_f32_16x16x32_bf16 v[152:155], v[186:189], v[198:201], v[152:155]
	s_waitcnt lgkmcnt(2)
	v_mfma_f32_16x16x32_bf16 v[148:151], v[190:193], v[198:201], v[148:151]
	s_and_b32 s33, s16, 1
	s_min_u32 s52, s16, 3
	s_xor_b32 s53, s33, 1
	s_mul_i32 s53, s53, 0x12000
	v_add3_u32 v250, s53, v173, v171
	s_waitcnt vmcnt(7)
	ds_write_b128 v250, v[112:115]
	s_waitcnt lgkmcnt(2)
	v_mfma_f32_16x16x32_bf16 v[144:147], v[194:197], v[198:201], v[144:147]
	ds_read_b128 v[246:249], v182 offset:6912
	v_mfma_f32_16x16x32_bf16 v[108:111], v[178:181], v[202:205], v[108:111]
	v_mfma_f32_16x16x32_bf16 v[104:107], v[186:189], v[202:205], v[104:107]
	v_mfma_f32_16x16x32_bf16 v[100:103], v[190:193], v[202:205], v[100:103]
	s_lshl_b32 s54, s52, 7
	s_add_u32 s52, s0, s54
	v_add3_u32 v251, s53, v174, v171
	v_add3_u32 v252, s53, v175, v171
	v_add3_u32 v253, s53, v176, v171
	s_addc_u32 s53, s1, 0
	v_lshl_add_u64 v[112:113], s[52:53], 0, v[162:163]
	s_nop 0
	global_load_dwordx4 v[112:115], v[112:113], off offset:256
	v_mfma_f32_16x16x32_bf16 v[96:99], v[194:197], v[202:205], v[96:99]
	ds_read_b128 v[198:201], v182 offset:9216
	s_waitcnt lgkmcnt(3)
	v_mfma_f32_16x16x32_bf16 v[92:95], v[178:181], v[242:245], v[92:95]
	s_waitcnt vmcnt(6)
	ds_write_b128 v251, v[116:119]
	v_mfma_f32_16x16x32_bf16 v[88:91], v[186:189], v[242:245], v[88:91]
	v_mfma_f32_16x16x32_bf16 v[84:87], v[190:193], v[242:245], v[84:87]
	v_mfma_f32_16x16x32_bf16 v[80:83], v[194:197], v[242:245], v[80:83]
	ds_read_b128 v[202:205], v182 offset:11520
	s_waitcnt lgkmcnt(3)
	v_mfma_f32_16x16x32_bf16 v[76:79], v[178:181], v[246:249], v[76:79]
	v_lshl_add_u64 v[116:117], s[52:53], 0, v[164:165]
	s_nop 0
	global_load_dwordx4 v[116:119], v[116:117], off offset:256
	v_mfma_f32_16x16x32_bf16 v[72:75], v[186:189], v[246:249], v[72:75]
	v_mfma_f32_16x16x32_bf16 v[68:71], v[190:193], v[246:249], v[68:71]
	s_waitcnt vmcnt(6)
	ds_write_b128 v252, v[120:123]
	v_mfma_f32_16x16x32_bf16 v[64:67], v[194:197], v[246:249], v[64:67]
	ds_read_b128 v[242:245], v182 offset:13824
	s_waitcnt lgkmcnt(4)
	v_mfma_f32_16x16x32_bf16 v[60:63], v[178:181], v[198:201], v[60:63]
	v_mfma_f32_16x16x32_bf16 v[56:59], v[186:189], v[198:201], v[56:59]
	v_mfma_f32_16x16x32_bf16 v[52:55], v[190:193], v[198:201], v[52:55]
	v_lshl_add_u64 v[120:121], s[52:53], 0, v[166:167]
	s_nop 0
	global_load_dwordx4 v[120:123], v[120:121], off offset:256
	v_mfma_f32_16x16x32_bf16 v[48:51], v[194:197], v[198:201], v[48:51]
	ds_read_b128 v[246:249], v182 offset:16128
	s_waitcnt lgkmcnt(3)
	v_mfma_f32_16x16x32_bf16 v[44:47], v[178:181], v[202:205], v[44:47]
	s_waitcnt vmcnt(6)
	ds_write_b128 v253, v[124:127]
	v_mfma_f32_16x16x32_bf16 v[40:43], v[186:189], v[202:205], v[40:43]
	v_mfma_f32_16x16x32_bf16 v[36:39], v[190:193], v[202:205], v[36:39]
	v_mfma_f32_16x16x32_bf16 v[32:35], v[194:197], v[202:205], v[32:35]
	ds_read_b128 v[198:201], v182 offset:64
	s_waitcnt lgkmcnt(3)
	v_mfma_f32_16x16x32_bf16 v[28:31], v[178:181], v[242:245], v[28:31]
	v_lshl_add_u64 v[124:125], s[52:53], 0, v[168:169]
	s_nop 0
	global_load_dwordx4 v[124:127], v[124:125], off offset:256
	v_mfma_f32_16x16x32_bf16 v[24:27], v[186:189], v[242:245], v[24:27]
	v_mfma_f32_16x16x32_bf16 v[20:23], v[190:193], v[242:245], v[20:23]
	ds_write_b128 v250, v[128:131] offset:36864
	v_mfma_f32_16x16x32_bf16 v[16:19], v[194:197], v[242:245], v[16:19]
	ds_read_b128 v[202:205], v182 offset:2368
	s_waitcnt lgkmcnt(4)
	v_mfma_f32_16x16x32_bf16 v[8:11], v[178:181], v[246:249], v[8:11]
	ds_read_b128 v[178:181], v183 offset:36928
	v_mfma_f32_16x16x32_bf16 v[4:7], v[186:189], v[246:249], v[4:7]
	ds_read_b128 v[186:189], v183 offset:39232
	v_mfma_f32_16x16x32_bf16 v[0:3], v[190:193], v[246:249], v[0:3]
	ds_read_b128 v[190:193], v183 offset:41536
	s_add_u32 s52, s2, s54
	s_addc_u32 s53, s3, 0
	v_lshl_add_u64 v[128:129], s[52:53], 0, v[162:163]
	s_nop 0
	global_load_dwordx4 v[128:131], v[128:129], off offset:256
	v_mfma_f32_16x16x32_bf16 v[12:15], v[194:197], v[246:249], v[12:15]
	ds_read_b128 v[194:197], v183 offset:43840
	ds_read_b128 v[242:245], v182 offset:4672
	s_waitcnt lgkmcnt(4)
; DI f32x4 mfma16(bf16x8 a, bf16x8 b, f32x4 c) { return __builtin_amdgcn_mfma_f32_16x16x32_bf16(a, b, c, 0, 0, 0); }
; template <int MI, int NJ, bool SWAP, class AP, class BP>
; DI void gemm_main(f32x4 (&acc)[MI][NJ], const AP& ap, int a_kstep, const BP& bp, int b_kstep, int nk, bf16_t* smem) {
;     ...
;   auto gload = [&](int kt) {
;     const bf16_t* ab = ap.base + (size_t)kt * a_kstep; const bf16_t* bb = bp.base + (size_t)kt * b_kstep;
; #pragma unroll
;     for (int i = 0; i < CA; ++i) ra[i] = *(const u32x4*)(ab + pa[i]);
; #pragma unroll
;     for (int i = 0; i < CB; ++i) rb[i] = *(const u32x4*)(bb + pb[i]);
;   };
;   auto sstore = [&](int buf) {
;     bf16_t* As = smem + buf * L::STAGE; bf16_t* Bs = As + L::A_ELEMS;
; #pragma unroll
;     for (int i = 0; i < CA; ++i) { const int c = tid + NTHR * i; *(u32x4*)(As + (c >> 3) * LDT + (c & 7) * 8) = oka[i] ? ra[i] : (u32x4){0u, 0u, 0u, 0u}; }
; #pragma unroll
;     for (int i = 0; i < CB; ++i) { const int c = tid + NTHR * i; *(u32x4*)(Bs + (c >> 3) * LDT + (c & 7) * 8) = rb[i]; }
;   };
;   gload(0); sstore(0); gload(nk > 1 ? 1 : 0); __syncthreads();
; #pragma unroll 1
;   for (int kt = 0; kt < nk; ++kt) {
;     const int buf = kt & 1;
;     sstore(buf ^ 1);
;     gload(kt + 2 < nk ? kt + 2 : nk - 1);
;     __builtin_amdgcn_sched_barrier(0);
;     const bf16_t* As = smem + buf * L::STAGE + (wm * 16 * MI + l15) * LDT + quad * 8;
;     const bf16_t* Bs = smem + buf * L::STAGE + L::A_ELEMS + (wn * 16 * NJ + l15) * LDT + quad * 8;
; #pragma unroll
;     for (int ks = 0; ks < 2; ++ks) {
;       if (MI * NJ >= 32 && ks == 1) asm volatile("" ::: "memory");
;       bf16x8 b[NJ];
; #pragma unroll
;       for (int j = 0; j < NJ; ++j) b[j] = *(const bf16x8*)(Bs + j * 16 * LDT + ks * 32);
; #pragma unroll
;       for (int i = 0; i < MI; ++i) {
;         const bf16x8 a = *(const bf16x8*)(As + i * 16 * LDT + ks * 32);
; #pragma unroll
;         for (int j = 0; j < NJ; ++j) acc[i][j] = SWAP ? mfma16(b[j], a, acc[i][j]) : mfma16(a, b[j], acc[i][j]);
;       }
;     }
;     __syncthreads();
;   }
	v_mfma_f32_16x16x32_bf16 v[156:159], v[178:181], v[198:201], v[156:159]
	s_waitcnt vmcnt(7)
	ds_write_b128 v251, v[132:135] offset:36864
	s_waitcnt lgkmcnt(4)
	v_mfma_f32_16x16x32_bf16 v[152:155], v[186:189], v[198:201], v[152:155]
	s_waitcnt lgkmcnt(3)
	v_mfma_f32_16x16x32_bf16 v[148:151], v[190:193], v[198:201], v[148:151]
	s_waitcnt lgkmcnt(2)
	v_mfma_f32_16x16x32_bf16 v[144:147], v[194:197], v[198:201], v[144:147]
	ds_read_b128 v[246:249], v182 offset:6976
	v_mfma_f32_16x16x32_bf16 v[108:111], v[178:181], v[202:205], v[108:111]
	v_lshl_add_u64 v[132:133], s[52:53], 0, v[164:165]
	s_nop 0
	global_load_dwordx4 v[132:135], v[132:133], off offset:256
	v_mfma_f32_16x16x32_bf16 v[104:107], v[186:189], v[202:205], v[104:107]
	v_mfma_f32_16x16x32_bf16 v[100:103], v[190:193], v[202:205], v[100:103]
	s_waitcnt vmcnt(7)
	ds_write_b128 v252, v[136:139] offset:36864
	v_mfma_f32_16x16x32_bf16 v[96:99], v[194:197], v[202:205], v[96:99]
	ds_read_b128 v[198:201], v182 offset:9280
	s_waitcnt lgkmcnt(4)
	v_mfma_f32_16x16x32_bf16 v[92:95], v[178:181], v[242:245], v[92:95]
	v_mfma_f32_16x16x32_bf16 v[88:91], v[186:189], v[242:245], v[88:91]
	v_mfma_f32_16x16x32_bf16 v[84:87], v[190:193], v[242:245], v[84:87]
	v_lshl_add_u64 v[136:137], s[52:53], 0, v[166:167]
	s_nop 0
	global_load_dwordx4 v[136:139], v[136:137], off offset:256
	v_mfma_f32_16x16x32_bf16 v[80:83], v[194:197], v[242:245], v[80:83]
	ds_read_b128 v[202:205], v182 offset:11584
	s_waitcnt lgkmcnt(3)
	v_mfma_f32_16x16x32_bf16 v[76:79], v[178:181], v[246:249], v[76:79]
	s_waitcnt vmcnt(7)
	ds_write_b128 v253, v[140:143] offset:36864
	v_mfma_f32_16x16x32_bf16 v[72:75], v[186:189], v[246:249], v[72:75]
	v_mfma_f32_16x16x32_bf16 v[68:71], v[190:193], v[246:249], v[68:71]
	v_mfma_f32_16x16x32_bf16 v[64:67], v[194:197], v[246:249], v[64:67]
	ds_read_b128 v[242:245], v182 offset:13888
	s_waitcnt lgkmcnt(3)
	v_mfma_f32_16x16x32_bf16 v[60:63], v[178:181], v[198:201], v[60:63]
	v_lshl_add_u64 v[140:141], s[52:53], 0, v[168:169]
	s_nop 0
	global_load_dwordx4 v[140:143], v[140:141], off offset:256
	v_mfma_f32_16x16x32_bf16 v[56:59], v[186:189], v[198:201], v[56:59]
	v_mfma_f32_16x16x32_bf16 v[52:55], v[190:193], v[198:201], v[52:55]
	v_mfma_f32_16x16x32_bf16 v[48:51], v[194:197], v[198:201], v[48:51]
	ds_read_b128 v[246:249], v182 offset:16192
	s_waitcnt lgkmcnt(3)
	v_mfma_f32_16x16x32_bf16 v[44:47], v[178:181], v[202:205], v[44:47]
	v_mfma_f32_16x16x32_bf16 v[40:43], v[186:189], v[202:205], v[40:43]
	v_mfma_f32_16x16x32_bf16 v[36:39], v[190:193], v[202:205], v[36:39]
	v_mfma_f32_16x16x32_bf16 v[32:35], v[194:197], v[202:205], v[32:35]
	s_add_i32 s16, s16, 1
	s_and_b32 s98, s16, 1
	s_mul_i32 s98, s98, 0x12000
	v_add3_u32 v183, s98, v160, v177
	v_add3_u32 v182, s98, v172, v177
	s_cmp_lg_u32 s16, 6
	s_waitcnt lgkmcnt(0)
	s_barrier
	s_cbranch_scc0 .Lgm2_exit
	ds_read_b128 v[198:201], v182
	ds_read_b128 v[202:205], v182 offset:2304
	v_mfma_f32_16x16x32_bf16 v[28:31], v[178:181], v[242:245], v[28:31]
	v_mfma_f32_16x16x32_bf16 v[8:11], v[178:181], v[246:249], v[8:11]
	ds_read_b128 v[178:181], v183 offset:36864
	v_mfma_f32_16x16x32_bf16 v[24:27], v[186:189], v[242:245], v[24:27]
	v_mfma_f32_16x16x32_bf16 v[4:7], v[186:189], v[246:249], v[4:7]
	ds_read_b128 v[186:189], v183 offset:39168
	v_mfma_f32_16x16x32_bf16 v[20:23], v[190:193], v[242:245], v[20:23]
	v_mfma_f32_16x16x32_bf16 v[0:3], v[190:193], v[246:249], v[0:3]
	ds_read_b128 v[190:193], v183 offset:41472
	v_mfma_f32_16x16x32_bf16 v[16:19], v[194:197], v[242:245], v[16:19]
	v_mfma_f32_16x16x32_bf16 v[12:15], v[194:197], v[246:249], v[12:15]
	ds_read_b128 v[194:197], v183 offset:43776
	s_branch .Lgm2_main

; DI f32x4 mfma16(bf16x8 a, bf16x8 b, f32x4 c) { return __builtin_amdgcn_mfma_f32_16x16x32_bf16(a, b, c, 0, 0, 0); }
; template <int MI, int NJ, bool SWAP, class AP, class BP>
; DI void gemm_main(f32x4 (&acc)[MI][NJ], const AP& ap, int a_kstep, const BP& bp, int b_kstep, int nk, bf16_t* smem) {
;     ...
;   auto gload = [&](int kt) {
;     const bf16_t* ab = ap.base + (size_t)kt * a_kstep; const bf16_t* bb = bp.base + (size_t)kt * b_kstep;
; #pragma unroll
;     for (int i = 0; i < CA; ++i) ra[i] = *(const u32x4*)(ab + pa[i]);
; #pragma unroll
;     for (int i = 0; i < CB; ++i) rb[i] = *(const u32x4*)(bb + pb[i]);
;   };
;   auto sstore = [&](int buf) {
;     bf16_t* As = smem + buf * L::STAGE; bf16_t* Bs = As + L::A_ELEMS;
; #pragma unroll
;     for (int i = 0; i < CA; ++i) { const int c = tid + NTHR * i; *(u32x4*)(As + (c >> 3) * LDT + (c & 7) * 8) = oka[i] ? ra[i] : (u32x4){0u, 0u, 0u, 0u}; }
; #pragma unroll
;     for (int i = 0; i < CB; ++i) { const int c = tid + NTHR * i; *(u32x4*)(Bs + (c >> 3) * LDT + (c & 7) * 8) = rb[i]; }
;   };
;   gload(0); sstore(0); gload(nk > 1 ? 1 : 0); __syncthreads();
; #pragma unroll 1
;   for (int kt = 0; kt < nk; ++kt) {
;     const int buf = kt & 1;
;     sstore(buf ^ 1);
;     gload(kt + 2 < nk ? kt + 2 : nk - 1);
;     __builtin_amdgcn_sched_barrier(0);
;     const bf16_t* As = smem + buf * L::STAGE + (wm * 16 * MI + l15) * LDT + quad * 8;
;     const bf16_t* Bs = smem + buf * L::STAGE + L::A_ELEMS + (wn * 16 * NJ + l15) * LDT + quad * 8;
; #pragma unroll
;     for (int ks = 0; ks < 2; ++ks) {
;       if (MI * NJ >= 32 && ks == 1) asm volatile("" ::: "memory");
;       bf16x8 b[NJ];
; #pragma unroll
;       for (int j = 0; j < NJ; ++j) b[j] = *(const bf16x8*)(Bs + j * 16 * LDT + ks * 32);
; #pragma unroll
;       for (int i = 0; i < MI; ++i) {
;         const bf16x8 a = *(const bf16x8*)(As + i * 16 * LDT + ks * 32);
; #pragma unroll
;         for (int j = 0; j < NJ; ++j) acc[i][j] = SWAP ? mfma16(b[j], a, acc[i][j]) : mfma16(a, b[j], acc[i][j]);
;       }
;     }
;     __syncthreads();
;   }
.Lgm3_main:
	ds_read_b128 v[242:245], v182 offset:4608
	s_waitcnt lgkmcnt(4)
	v_mfma_f32_16x16x32_bf16 v[156:159], v[178:181], v[198:201], v[156:159]
	s_waitcnt lgkmcnt(3)
	v_mfma_f32_16x16x32_bf16 v[152:155], v[186:189], v[198:201], v[152:155]
	s_waitcnt lgkmcnt(2)
	v_mfma_f32_16x16x32_bf16 v[148:151], v[190:193], v[198:201], v[148:151]
	v_lshlrev_b32_e32 v250, 1, v160
	s_and_b32 s54, s33, 1
	s_xor_b32 s52, s54, 1
	s_mul_i32 s52, s52, 0x12000
	v_add3_u32 v250, s52, v250, v172
	s_waitcnt vmcnt(7)
	ds_write_b128 v250, v[112:115]
	s_waitcnt lgkmcnt(2)
	v_mfma_f32_16x16x32_bf16 v[144:147], v[194:197], v[198:201], v[144:147]
	ds_read_b128 v[246:249], v182 offset:6912
	v_mfma_f32_16x16x32_bf16 v[108:111], v[178:181], v[202:205], v[108:111]
	v_mfma_f32_16x16x32_bf16 v[104:107], v[186:189], v[202:205], v[104:107]
	v_mfma_f32_16x16x32_bf16 v[100:103], v[190:193], v[202:205], v[100:103]
	s_cmp_eq_u32 s33, 0
	s_cselect_b32 s55, s48, 0x180
	v_lshlrev_b32_e32 v251, 1, v173
	v_add3_u32 v251, s52, v251, v172
	v_lshlrev_b32_e32 v252, 1, v174
	v_add3_u32 v252, s52, v252, v172
	v_lshlrev_b32_e32 v253, 1, v175
	v_add3_u32 v253, s52, v253, v172
	s_add_u32 s52, s0, s55
	s_addc_u32 s53, s1, 0
	v_lshl_add_u64 v[112:113], s[52:53], 0, v[162:163]
	s_nop 0
	global_load_dwordx4 v[112:115], v[112:113], off
	v_mfma_f32_16x16x32_bf16 v[96:99], v[194:197], v[202:205], v[96:99]
	ds_read_b128 v[198:201], v182 offset:9216
	s_waitcnt lgkmcnt(3)
	v_mfma_f32_16x16x32_bf16 v[92:95], v[178:181], v[242:245], v[92:95]
	s_waitcnt vmcnt(7)
	ds_write_b128 v251, v[116:119]
	v_mfma_f32_16x16x32_bf16 v[88:91], v[186:189], v[242:245], v[88:91]
	v_mfma_f32_16x16x32_bf16 v[84:87], v[190:193], v[242:245], v[84:87]
	v_mfma_f32_16x16x32_bf16 v[80:83], v[194:197], v[242:245], v[80:83]
	ds_read_b128 v[202:205], v182 offset:11520
	s_waitcnt lgkmcnt(3)
	v_mfma_f32_16x16x32_bf16 v[76:79], v[178:181], v[246:249], v[76:79]
	v_lshl_add_u64 v[116:117], s[52:53], 0, v[164:165]
	s_nop 0
	global_load_dwordx4 v[116:119], v[116:117], off
	v_mfma_f32_16x16x32_bf16 v[72:75], v[186:189], v[246:249], v[72:75]
	v_mfma_f32_16x16x32_bf16 v[68:71], v[190:193], v[246:249], v[68:71]
	s_waitcnt vmcnt(7)
	ds_write_b128 v252, v[120:123]
	v_mfma_f32_16x16x32_bf16 v[64:67], v[194:197], v[246:249], v[64:67]
	ds_read_b128 v[242:245], v182 offset:13824
	s_waitcnt lgkmcnt(4)
	v_mfma_f32_16x16x32_bf16 v[60:63], v[178:181], v[198:201], v[60:63]
	v_mfma_f32_16x16x32_bf16 v[56:59], v[186:189], v[198:201], v[56:59]
	v_mfma_f32_16x16x32_bf16 v[52:55], v[190:193], v[198:201], v[52:55]
	v_lshl_add_u64 v[120:121], s[52:53], 0, v[166:167]
	s_nop 0
	global_load_dwordx4 v[120:123], v[120:121], off
	v_mfma_f32_16x16x32_bf16 v[48:51], v[194:197], v[198:201], v[48:51]
	ds_read_b128 v[246:249], v182 offset:16128
	s_waitcnt lgkmcnt(3)
	v_mfma_f32_16x16x32_bf16 v[44:47], v[178:181], v[202:205], v[44:47]
	s_waitcnt vmcnt(7)
	ds_write_b128 v253, v[124:127]
	v_mfma_f32_16x16x32_bf16 v[40:43], v[186:189], v[202:205], v[40:43]
	v_mfma_f32_16x16x32_bf16 v[36:39], v[190:193], v[202:205], v[36:39]
	v_mfma_f32_16x16x32_bf16 v[32:35], v[194:197], v[202:205], v[32:35]
	ds_read_b128 v[198:201], v182 offset:64
	s_waitcnt lgkmcnt(3)
	v_mfma_f32_16x16x32_bf16 v[28:31], v[178:181], v[242:245], v[28:31]
	v_lshl_add_u64 v[124:125], s[52:53], 0, v[168:169]
	s_nop 0
	global_load_dwordx4 v[124:127], v[124:125], off
	v_mfma_f32_16x16x32_bf16 v[24:27], v[186:189], v[242:245], v[24:27]
	v_mfma_f32_16x16x32_bf16 v[20:23], v[190:193], v[242:245], v[20:23]
	s_waitcnt vmcnt(7)
	ds_write_b128 v250, v[128:131] offset:36864
	v_mfma_f32_16x16x32_bf16 v[16:19], v[194:197], v[242:245], v[16:19]
	ds_read_b128 v[202:205], v182 offset:2368
	s_waitcnt lgkmcnt(4)
; DI f32x4 mfma16(bf16x8 a, bf16x8 b, f32x4 c) { return __builtin_amdgcn_mfma_f32_16x16x32_bf16(a, b, c, 0, 0, 0); }
; template <int MI, int NJ, bool SWAP, class AP, class BP>
; DI void gemm_main(f32x4 (&acc)[MI][NJ], const AP& ap, int a_kstep, const BP& bp, int b_kstep, int nk, bf16_t* smem) {
;     ...
;   auto gload = [&](int kt) {
;     const bf16_t* ab = ap.base + (size_t)kt * a_kstep; const bf16_t* bb = bp.base + (size_t)kt * b_kstep;
; #pragma unroll
;     for (int i = 0; i < CA; ++i) ra[i] = *(const u32x4*)(ab + pa[i]);
; #pragma unroll
;     for (int i = 0; i < CB; ++i) rb[i] = *(const u32x4*)(bb + pb[i]);
;   };
;   auto sstore = [&](int buf) {
;     bf16_t* As = smem + buf * L::STAGE; bf16_t* Bs = As + L::A_ELEMS;
; #pragma unroll
;     for (int i = 0; i < CA; ++i) { const int c = tid + NTHR * i; *(u32x4*)(As + (c >> 3) * LDT + (c & 7) * 8) = oka[i] ? ra[i] : (u32x4){0u, 0u, 0u, 0u}; }
; #pragma unroll
;     for (int i = 0; i < CB; ++i) { const int c = tid + NTHR * i; *(u32x4*)(Bs + (c >> 3) * LDT + (c & 7) * 8) = rb[i]; }
;   };
;   gload(0); sstore(0); gload(nk > 1 ? 1 : 0); __syncthreads();
; #pragma unroll 1
;   for (int kt = 0; kt < nk; ++kt) {
;     const int buf = kt & 1;
;     sstore(buf ^ 1);
;     gload(kt + 2 < nk ? kt + 2 : nk - 1);
;     __builtin_amdgcn_sched_barrier(0);
;     const bf16_t* As = smem + buf * L::STAGE + (wm * 16 * MI + l15) * LDT + quad * 8;
;     const bf16_t* Bs = smem + buf * L::STAGE + L::A_ELEMS + (wn * 16 * NJ + l15) * LDT + quad * 8;
; #pragma unroll
;     for (int ks = 0; ks < 2; ++ks) {
;       if (MI * NJ >= 32 && ks == 1) asm volatile("" ::: "memory");
;       bf16x8 b[NJ];
; #pragma unroll
;       for (int j = 0; j < NJ; ++j) b[j] = *(const bf16x8*)(Bs + j * 16 * LDT + ks * 32);
; #pragma unroll
;       for (int i = 0; i < MI; ++i) {
;         const bf16x8 a = *(const bf16x8*)(As + i * 16 * LDT + ks * 32);
; #pragma unroll
;         for (int j = 0; j < NJ; ++j) acc[i][j] = SWAP ? mfma16(b[j], a, acc[i][j]) : mfma16(a, b[j], acc[i][j]);
;       }
;     }
;     __syncthreads();
;   }
	v_mfma_f32_16x16x32_bf16 v[8:11], v[178:181], v[246:249], v[8:11]
	ds_read_b128 v[178:181], v183 offset:36928
	v_mfma_f32_16x16x32_bf16 v[4:7], v[186:189], v[246:249], v[4:7]
	ds_read_b128 v[186:189], v183 offset:39232
	v_mfma_f32_16x16x32_bf16 v[0:3], v[190:193], v[246:249], v[0:3]
	ds_read_b128 v[190:193], v183 offset:41536
	s_add_u32 s52, s2, s55
	s_addc_u32 s53, s3, 0
	v_lshl_add_u64 v[128:129], s[52:53], 0, v[162:163]
	s_nop 0
	global_load_dwordx4 v[128:131], v[128:129], off
	v_mfma_f32_16x16x32_bf16 v[12:15], v[194:197], v[246:249], v[12:15]
	ds_read_b128 v[194:197], v183 offset:43840
	ds_read_b128 v[242:245], v182 offset:4672
	s_waitcnt lgkmcnt(4)
	v_mfma_f32_16x16x32_bf16 v[156:159], v[178:181], v[198:201], v[156:159]
	s_waitcnt vmcnt(7)
	ds_write_b128 v251, v[132:135] offset:36864
	s_waitcnt lgkmcnt(4)
	v_mfma_f32_16x16x32_bf16 v[152:155], v[186:189], v[198:201], v[152:155]
	s_waitcnt lgkmcnt(3)
	v_mfma_f32_16x16x32_bf16 v[148:151], v[190:193], v[198:201], v[148:151]
	s_waitcnt lgkmcnt(2)
	v_mfma_f32_16x16x32_bf16 v[144:147], v[194:197], v[198:201], v[144:147]
	ds_read_b128 v[246:249], v182 offset:6976
	v_mfma_f32_16x16x32_bf16 v[108:111], v[178:181], v[202:205], v[108:111]
	v_lshl_add_u64 v[132:133], s[52:53], 0, v[164:165]
	s_nop 0
	global_load_dwordx4 v[132:135], v[132:133], off
	v_mfma_f32_16x16x32_bf16 v[104:107], v[186:189], v[202:205], v[104:107]
	v_mfma_f32_16x16x32_bf16 v[100:103], v[190:193], v[202:205], v[100:103]
	s_waitcnt vmcnt(7)
	ds_write_b128 v252, v[136:139] offset:36864
	v_mfma_f32_16x16x32_bf16 v[96:99], v[194:197], v[202:205], v[96:99]
	ds_read_b128 v[198:201], v182 offset:9280
	s_waitcnt lgkmcnt(4)
	v_mfma_f32_16x16x32_bf16 v[92:95], v[178:181], v[242:245], v[92:95]
	v_mfma_f32_16x16x32_bf16 v[88:91], v[186:189], v[242:245], v[88:91]
	v_mfma_f32_16x16x32_bf16 v[84:87], v[190:193], v[242:245], v[84:87]
	v_lshl_add_u64 v[136:137], s[52:53], 0, v[166:167]
	s_nop 0
	global_load_dwordx4 v[136:139], v[136:137], off
	v_mfma_f32_16x16x32_bf16 v[80:83], v[194:197], v[242:245], v[80:83]
	ds_read_b128 v[202:205], v182 offset:11584
	s_waitcnt lgkmcnt(3)
	v_mfma_f32_16x16x32_bf16 v[76:79], v[178:181], v[246:249], v[76:79]
	s_waitcnt vmcnt(7)
	ds_write_b128 v253, v[140:143] offset:36864
	v_mfma_f32_16x16x32_bf16 v[72:75], v[186:189], v[246:249], v[72:75]
	v_mfma_f32_16x16x32_bf16 v[68:71], v[190:193], v[246:249], v[68:71]
	v_mfma_f32_16x16x32_bf16 v[64:67], v[194:197], v[246:249], v[64:67]
	ds_read_b128 v[242:245], v182 offset:13888
	s_waitcnt lgkmcnt(3)
	v_mfma_f32_16x16x32_bf16 v[60:63], v[178:181], v[198:201], v[60:63]
	v_lshl_add_u64 v[140:141], s[52:53], 0, v[168:169]
	s_nop 0
	global_load_dwordx4 v[140:143], v[140:141], off
	v_mfma_f32_16x16x32_bf16 v[56:59], v[186:189], v[198:201], v[56:59]
	v_mfma_f32_16x16x32_bf16 v[52:55], v[190:193], v[198:201], v[52:55]
	v_mfma_f32_16x16x32_bf16 v[48:51], v[194:197], v[198:201], v[48:51]
	ds_read_b128 v[246:249], v182 offset:16192
	s_waitcnt lgkmcnt(3)
	v_mfma_f32_16x16x32_bf16 v[44:47], v[178:181], v[202:205], v[44:47]
	v_mfma_f32_16x16x32_bf16 v[40:43], v[186:189], v[202:205], v[40:43]
	v_mfma_f32_16x16x32_bf16 v[36:39], v[190:193], v[202:205], v[36:39]
	v_mfma_f32_16x16x32_bf16 v[32:35], v[194:197], v[202:205], v[32:35]
	s_add_i32 s33, s33, 1
	s_and_b32 s98, s33, 1
	s_mul_i32 s98, s98, 0x12000
	v_add3_u32 v183, s98, v171, v177
	v_add3_u32 v182, s98, v176, v177
	s_cmp_lg_u32 s33, 4
	s_waitcnt lgkmcnt(0)
	s_barrier
	s_cbranch_scc0 .Lgm3_exit
	ds_read_b128 v[198:201], v182
	ds_read_b128 v[202:205], v182 offset:2304
	v_mfma_f32_16x16x32_bf16 v[28:31], v[178:181], v[242:245], v[28:31]
	v_mfma_f32_16x16x32_bf16 v[8:11], v[178:181], v[246:249], v[8:11]
	ds_read_b128 v[178:181], v183 offset:36864
	v_mfma_f32_16x16x32_bf16 v[24:27], v[186:189], v[242:245], v[24:27]
	v_mfma_f32_16x16x32_bf16 v[4:7], v[186:189], v[246:249], v[4:7]
	ds_read_b128 v[186:189], v183 offset:39168
	v_mfma_f32_16x16x32_bf16 v[20:23], v[190:193], v[242:245], v[20:23]
	v_mfma_f32_16x16x32_bf16 v[0:3], v[190:193], v[246:249], v[0:3]
	ds_read_b128 v[190:193], v183 offset:41472
	v_mfma_f32_16x16x32_bf16 v[16:19], v[194:197], v[242:245], v[16:19]
	v_mfma_f32_16x16x32_bf16 v[12:15], v[194:197], v[246:249], v[12:15]
	ds_read_b128 v[194:197], v183 offset:43776
	s_branch .Lgm3_main

; DI f32x4 mfma16(bf16x8 a, bf16x8 b, f32x4 c) { return __builtin_amdgcn_mfma_f32_16x16x32_bf16(a, b, c, 0, 0, 0); }
; template <int MI, int NJ, bool SWAP, class AP, class BP>
; DI void gemm_main(f32x4 (&acc)[MI][NJ], const AP& ap, int a_kstep, const BP& bp, int b_kstep, int nk, bf16_t* smem) {
;     ...
;   auto gload = [&](int kt) {
;     const bf16_t* ab = ap.base + (size_t)kt * a_kstep; const bf16_t* bb = bp.base + (size_t)kt * b_kstep;
; #pragma unroll
;     for (int i = 0; i < CA; ++i) ra[i] = *(const u32x4*)(ab + pa[i]);
; #pragma unroll
;     for (int i = 0; i < CB; ++i) rb[i] = *(const u32x4*)(bb + pb[i]);
;   };
;   auto sstore = [&](int buf) {
;     bf16_t* As = smem + buf * L::STAGE; bf16_t* Bs = As + L::A_ELEMS;
; #pragma unroll
;     for (int i = 0; i < CA; ++i) { const int c = tid + NTHR * i; *(u32x4*)(As + (c >> 3) * LDT + (c & 7) * 8) = oka[i] ? ra[i] : (u32x4){0u, 0u, 0u, 0u}; }
; #pragma unroll
;     for (int i = 0; i < CB; ++i) { const int c = tid + NTHR * i; *(u32x4*)(Bs + (c >> 3) * LDT + (c & 7) * 8) = rb[i]; }
;   };
;   gload(0); sstore(0); gload(nk > 1 ? 1 : 0); __syncthreads();
; #pragma unroll 1
;   for (int kt = 0; kt < nk; ++kt) {
;     const int buf = kt & 1;
;     sstore(buf ^ 1);
;     gload(kt + 2 < nk ? kt + 2 : nk - 1);
;     __builtin_amdgcn_sched_barrier(0);
;     const bf16_t* As = smem + buf * L::STAGE + (wm * 16 * MI + l15) * LDT + quad * 8;
;     const bf16_t* Bs = smem + buf * L::STAGE + L::A_ELEMS + (wn * 16 * NJ + l15) * LDT + quad * 8;
; #pragma unroll
;     for (int ks = 0; ks < 2; ++ks) {
;       if (MI * NJ >= 32 && ks == 1) asm volatile("" ::: "memory");
;       bf16x8 b[NJ];
; #pragma unroll
;       for (int j = 0; j < NJ; ++j) b[j] = *(const bf16x8*)(Bs + j * 16 * LDT + ks * 32);
; #pragma unroll
;       for (int i = 0; i < MI; ++i) {
;         const bf16x8 a = *(const bf16x8*)(As + i * 16 * LDT + ks * 32);
; #pragma unroll
;         for (int j = 0; j < NJ; ++j) acc[i][j] = SWAP ? mfma16(b[j], a, acc[i][j]) : mfma16(a, b[j], acc[i][j]);
;       }
;     }
;     __syncthreads();
;   }
.Lgm4_main:
	ds_read_b128 v[242:245], v182 offset:4608
	s_waitcnt lgkmcnt(4)
	v_mfma_f32_16x16x32_bf16 v[140:143], v[198:201], v[178:181], v[140:143]
	s_waitcnt lgkmcnt(3)
	v_mfma_f32_16x16x32_bf16 v[120:123], v[198:201], v[186:189], v[120:123]
	s_waitcnt lgkmcnt(2)
	v_mfma_f32_16x16x32_bf16 v[116:119], v[198:201], v[190:193], v[116:119]
	v_lshlrev_b32_e32 v250, 1, v160
	s_and_b32 s16, s5, 1
	s_xor_b32 s33, s16, 1
	s_mul_i32 s33, s33, 0x12000
	v_add3_u32 v250, s33, v250, v172
	s_waitcnt vmcnt(7)
	ds_write_b128 v250, v[124:127]
	s_waitcnt lgkmcnt(2)
	v_mfma_f32_16x16x32_bf16 v[112:115], v[198:201], v[194:197], v[112:115]
	ds_read_b128 v[246:249], v182 offset:6912
	v_mfma_f32_16x16x32_bf16 v[108:111], v[202:205], v[178:181], v[108:111]
	v_mfma_f32_16x16x32_bf16 v[104:107], v[202:205], v[186:189], v[104:107]
	v_mfma_f32_16x16x32_bf16 v[100:103], v[202:205], v[190:193], v[100:103]
	s_cmp_eq_u32 s5, 0
	v_lshlrev_b32_e32 v251, 1, v173
	v_add3_u32 v251, s33, v251, v172
	v_lshlrev_b32_e32 v252, 1, v174
	v_add3_u32 v252, s33, v252, v172
	v_lshlrev_b32_e32 v253, 1, v175
	v_add3_u32 v253, s33, v253, v172
	s_cselect_b32 s33, s48, 0x180
	s_add_u32 s52, s0, s33
	s_addc_u32 s53, s1, 0
	v_lshl_add_u64 v[124:125], s[52:53], 0, v[162:163]
	s_nop 0
	global_load_dwordx4 v[124:127], v[124:125], off
	v_mfma_f32_16x16x32_bf16 v[96:99], v[202:205], v[194:197], v[96:99]
	ds_read_b128 v[198:201], v182 offset:9216
	s_waitcnt lgkmcnt(3)
	v_mfma_f32_16x16x32_bf16 v[92:95], v[242:245], v[178:181], v[92:95]
	s_waitcnt vmcnt(7)
	ds_write_b128 v251, v[128:131]
	v_mfma_f32_16x16x32_bf16 v[88:91], v[242:245], v[186:189], v[88:91]
	v_mfma_f32_16x16x32_bf16 v[84:87], v[242:245], v[190:193], v[84:87]
	v_mfma_f32_16x16x32_bf16 v[80:83], v[242:245], v[194:197], v[80:83]
	ds_read_b128 v[202:205], v182 offset:11520
	s_waitcnt lgkmcnt(3)
	v_mfma_f32_16x16x32_bf16 v[76:79], v[246:249], v[178:181], v[76:79]
	v_lshl_add_u64 v[128:129], s[52:53], 0, v[164:165]
	s_nop 0
	global_load_dwordx4 v[128:131], v[128:129], off
	v_mfma_f32_16x16x32_bf16 v[72:75], v[246:249], v[186:189], v[72:75]
	v_mfma_f32_16x16x32_bf16 v[68:71], v[246:249], v[190:193], v[68:71]
	s_waitcnt vmcnt(7)
	ds_write_b128 v252, v[132:135]
	v_mfma_f32_16x16x32_bf16 v[64:67], v[246:249], v[194:197], v[64:67]
	ds_read_b128 v[242:245], v182 offset:13824
	s_waitcnt lgkmcnt(4)
	v_mfma_f32_16x16x32_bf16 v[60:63], v[198:201], v[178:181], v[60:63]
	v_mfma_f32_16x16x32_bf16 v[56:59], v[198:201], v[186:189], v[56:59]
	v_mfma_f32_16x16x32_bf16 v[52:55], v[198:201], v[190:193], v[52:55]
	v_lshl_add_u64 v[132:133], s[52:53], 0, v[166:167]
	s_nop 0
	global_load_dwordx4 v[132:135], v[132:133], off
	v_mfma_f32_16x16x32_bf16 v[48:51], v[198:201], v[194:197], v[48:51]
	ds_read_b128 v[246:249], v182 offset:16128
	s_waitcnt lgkmcnt(3)
	v_mfma_f32_16x16x32_bf16 v[44:47], v[202:205], v[178:181], v[44:47]
	s_waitcnt vmcnt(7)
	ds_write_b128 v253, v[136:139]
	v_mfma_f32_16x16x32_bf16 v[40:43], v[202:205], v[186:189], v[40:43]
	v_mfma_f32_16x16x32_bf16 v[36:39], v[202:205], v[190:193], v[36:39]
	v_mfma_f32_16x16x32_bf16 v[32:35], v[202:205], v[194:197], v[32:35]
	ds_read_b128 v[198:201], v182 offset:64
	s_waitcnt lgkmcnt(3)
	v_mfma_f32_16x16x32_bf16 v[28:31], v[242:245], v[178:181], v[28:31]
	v_lshl_add_u64 v[136:137], s[52:53], 0, v[168:169]
	s_nop 0
	global_load_dwordx4 v[136:139], v[136:137], off
	v_mfma_f32_16x16x32_bf16 v[24:27], v[242:245], v[186:189], v[24:27]
	v_mfma_f32_16x16x32_bf16 v[20:23], v[242:245], v[190:193], v[20:23]
	s_waitcnt vmcnt(7)
	ds_write_b128 v250, v[144:147] offset:36864
	v_mfma_f32_16x16x32_bf16 v[16:19], v[242:245], v[194:197], v[16:19]
	ds_read_b128 v[202:205], v182 offset:2368
	s_waitcnt lgkmcnt(4)
; DI f32x4 mfma16(bf16x8 a, bf16x8 b, f32x4 c) { return __builtin_amdgcn_mfma_f32_16x16x32_bf16(a, b, c, 0, 0, 0); }
; template <int MI, int NJ, bool SWAP, class AP, class BP>
; DI void gemm_main(f32x4 (&acc)[MI][NJ], const AP& ap, int a_kstep, const BP& bp, int b_kstep, int nk, bf16_t* smem) {
;     ...
;   auto gload = [&](int kt) {
;     const bf16_t* ab = ap.base + (size_t)kt * a_kstep; const bf16_t* bb = bp.base + (size_t)kt * b_kstep;
; #pragma unroll
;     for (int i = 0; i < CA; ++i) ra[i] = *(const u32x4*)(ab + pa[i]);
; #pragma unroll
;     for (int i = 0; i < CB; ++i) rb[i] = *(const u32x4*)(bb + pb[i]);
;   };
;   auto sstore = [&](int buf) {
;     bf16_t* As = smem + buf * L::STAGE; bf16_t* Bs = As + L::A_ELEMS;
; #pragma unroll
;     for (int i = 0; i < CA; ++i) { const int c = tid + NTHR * i; *(u32x4*)(As + (c >> 3) * LDT + (c & 7) * 8) = oka[i] ? ra[i] : (u32x4){0u, 0u, 0u, 0u}; }
; #pragma unroll
;     for (int i = 0; i < CB; ++i) { const int c = tid + NTHR * i; *(u32x4*)(Bs + (c >> 3) * LDT + (c & 7) * 8) = rb[i]; }
;   };
;   gload(0); sstore(0); gload(nk > 1 ? 1 : 0); __syncthreads();
; #pragma unroll 1
;   for (int kt = 0; kt < nk; ++kt) {
;     const int buf = kt & 1;
;     sstore(buf ^ 1);
;     gload(kt + 2 < nk ? kt + 2 : nk - 1);
;     __builtin_amdgcn_sched_barrier(0);
;     const bf16_t* As = smem + buf * L::STAGE + (wm * 16 * MI + l15) * LDT + quad * 8;
;     const bf16_t* Bs = smem + buf * L::STAGE + L::A_ELEMS + (wn * 16 * NJ + l15) * LDT + quad * 8;
; #pragma unroll
;     for (int ks = 0; ks < 2; ++ks) {
;       if (MI * NJ >= 32 && ks == 1) asm volatile("" ::: "memory");
;       bf16x8 b[NJ];
; #pragma unroll
;       for (int j = 0; j < NJ; ++j) b[j] = *(const bf16x8*)(Bs + j * 16 * LDT + ks * 32);
; #pragma unroll
;       for (int i = 0; i < MI; ++i) {
;         const bf16x8 a = *(const bf16x8*)(As + i * 16 * LDT + ks * 32);
; #pragma unroll
;         for (int j = 0; j < NJ; ++j) acc[i][j] = SWAP ? mfma16(b[j], a, acc[i][j]) : mfma16(a, b[j], acc[i][j]);
;       }
;     }
;     __syncthreads();
;   }
	v_mfma_f32_16x16x32_bf16 v[8:11], v[246:249], v[178:181], v[8:11]
	ds_read_b128 v[178:181], v183 offset:36928
	v_mfma_f32_16x16x32_bf16 v[4:7], v[246:249], v[186:189], v[4:7]
	ds_read_b128 v[186:189], v183 offset:39232
	v_mfma_f32_16x16x32_bf16 v[0:3], v[246:249], v[190:193], v[0:3]
	ds_read_b128 v[190:193], v183 offset:41536
	s_add_u32 s52, s2, s33
	s_addc_u32 s53, s3, 0
	v_lshl_add_u64 v[144:145], s[52:53], 0, v[162:163]
	s_nop 0
	global_load_dwordx4 v[144:147], v[144:145], off
	v_mfma_f32_16x16x32_bf16 v[12:15], v[246:249], v[194:197], v[12:15]
	ds_read_b128 v[194:197], v183 offset:43840
	ds_read_b128 v[242:245], v182 offset:4672
	s_waitcnt lgkmcnt(4)
	v_mfma_f32_16x16x32_bf16 v[140:143], v[198:201], v[178:181], v[140:143]
	s_waitcnt vmcnt(7)
	ds_write_b128 v251, v[148:151] offset:36864
	s_waitcnt lgkmcnt(4)
	v_mfma_f32_16x16x32_bf16 v[120:123], v[198:201], v[186:189], v[120:123]
	s_waitcnt lgkmcnt(3)
	v_mfma_f32_16x16x32_bf16 v[116:119], v[198:201], v[190:193], v[116:119]
	s_waitcnt lgkmcnt(2)
	v_mfma_f32_16x16x32_bf16 v[112:115], v[198:201], v[194:197], v[112:115]
	ds_read_b128 v[246:249], v182 offset:6976
	v_mfma_f32_16x16x32_bf16 v[108:111], v[202:205], v[178:181], v[108:111]
	v_lshl_add_u64 v[148:149], s[52:53], 0, v[164:165]
	s_nop 0
	global_load_dwordx4 v[148:151], v[148:149], off
	v_mfma_f32_16x16x32_bf16 v[104:107], v[202:205], v[186:189], v[104:107]
	v_mfma_f32_16x16x32_bf16 v[100:103], v[202:205], v[190:193], v[100:103]
	s_waitcnt vmcnt(7)
	ds_write_b128 v252, v[152:155] offset:36864
	v_mfma_f32_16x16x32_bf16 v[96:99], v[202:205], v[194:197], v[96:99]
	ds_read_b128 v[198:201], v182 offset:9280
	s_waitcnt lgkmcnt(4)
	v_mfma_f32_16x16x32_bf16 v[92:95], v[242:245], v[178:181], v[92:95]
	v_mfma_f32_16x16x32_bf16 v[88:91], v[242:245], v[186:189], v[88:91]
	v_mfma_f32_16x16x32_bf16 v[84:87], v[242:245], v[190:193], v[84:87]
	v_lshl_add_u64 v[152:153], s[52:53], 0, v[166:167]
	s_nop 0
	global_load_dwordx4 v[152:155], v[152:153], off
	v_mfma_f32_16x16x32_bf16 v[80:83], v[242:245], v[194:197], v[80:83]
	ds_read_b128 v[202:205], v182 offset:11584
	s_waitcnt lgkmcnt(3)
	v_mfma_f32_16x16x32_bf16 v[76:79], v[246:249], v[178:181], v[76:79]
	s_waitcnt vmcnt(7)
	ds_write_b128 v253, v[156:159] offset:36864
	v_mfma_f32_16x16x32_bf16 v[72:75], v[246:249], v[186:189], v[72:75]
	v_mfma_f32_16x16x32_bf16 v[68:71], v[246:249], v[190:193], v[68:71]
	v_mfma_f32_16x16x32_bf16 v[64:67], v[246:249], v[194:197], v[64:67]
	ds_read_b128 v[242:245], v182 offset:13888
	s_waitcnt lgkmcnt(3)
	v_mfma_f32_16x16x32_bf16 v[60:63], v[198:201], v[178:181], v[60:63]
	v_lshl_add_u64 v[156:157], s[52:53], 0, v[168:169]
	s_nop 0
	global_load_dwordx4 v[156:159], v[156:157], off
	v_mfma_f32_16x16x32_bf16 v[56:59], v[198:201], v[186:189], v[56:59]
	v_mfma_f32_16x16x32_bf16 v[52:55], v[198:201], v[190:193], v[52:55]
	v_mfma_f32_16x16x32_bf16 v[48:51], v[198:201], v[194:197], v[48:51]
	ds_read_b128 v[246:249], v182 offset:16192
	s_waitcnt lgkmcnt(3)
	v_mfma_f32_16x16x32_bf16 v[44:47], v[202:205], v[178:181], v[44:47]
	v_mfma_f32_16x16x32_bf16 v[40:43], v[202:205], v[186:189], v[40:43]
	v_mfma_f32_16x16x32_bf16 v[36:39], v[202:205], v[190:193], v[36:39]
	v_mfma_f32_16x16x32_bf16 v[32:35], v[202:205], v[194:197], v[32:35]
	s_add_i32 s5, s5, 1
	s_and_b32 s98, s5, 1
	s_mul_i32 s98, s98, 0x12000
	v_add3_u32 v182, s98, v176, v177
	v_add3_u32 v183, s98, v171, v177
	s_cmp_lg_u32 s5, 4
	s_waitcnt lgkmcnt(0)
	s_barrier
	s_cbranch_scc0 .Lgm4_exit
	ds_read_b128 v[198:201], v182
	ds_read_b128 v[202:205], v182 offset:2304
	v_mfma_f32_16x16x32_bf16 v[28:31], v[242:245], v[178:181], v[28:31]
	v_mfma_f32_16x16x32_bf16 v[8:11], v[246:249], v[178:181], v[8:11]
	ds_read_b128 v[178:181], v183 offset:36864
	v_mfma_f32_16x16x32_bf16 v[24:27], v[242:245], v[186:189], v[24:27]
	v_mfma_f32_16x16x32_bf16 v[4:7], v[246:249], v[186:189], v[4:7]
	ds_read_b128 v[186:189], v183 offset:39168
	v_mfma_f32_16x16x32_bf16 v[20:23], v[242:245], v[190:193], v[20:23]
	v_mfma_f32_16x16x32_bf16 v[0:3], v[246:249], v[190:193], v[0:3]
	ds_read_b128 v[190:193], v183 offset:41472
	v_mfma_f32_16x16x32_bf16 v[16:19], v[242:245], v[194:197], v[16:19]
	v_mfma_f32_16x16x32_bf16 v[12:15], v[246:249], v[194:197], v[12:15]
	ds_read_b128 v[194:197], v183 offset:43776
	s_branch .Lgm4_main

; DI f32x4 mfma16(bf16x8 a, bf16x8 b, f32x4 c) { return __builtin_amdgcn_mfma_f32_16x16x32_bf16(a, b, c, 0, 0, 0); }
; template <int MI, int NJ, bool SWAP, class AP, class BP>
; DI void gemm_main(f32x4 (&acc)[MI][NJ], const AP& ap, int a_kstep, const BP& bp, int b_kstep, int nk, bf16_t* smem) {
;     ...
;   auto gload = [&](int kt) {
;     const bf16_t* ab = ap.base + (size_t)kt * a_kstep; const bf16_t* bb = bp.base + (size_t)kt * b_kstep;
; #pragma unroll
;     for (int i = 0; i < CA; ++i) ra[i] = *(const u32x4*)(ab + pa[i]);
; #pragma unroll
;     for (int i = 0; i < CB; ++i) rb[i] = *(const u32x4*)(bb + pb[i]);
;   };
;   auto sstore = [&](int buf) {
;     bf16_t* As = smem + buf * L::STAGE; bf16_t* Bs = As + L::A_ELEMS;
; #pragma unroll
;     for (int i = 0; i < CA; ++i) { const int c = tid + NTHR * i; *(u32x4*)(As + (c >> 3) * LDT + (c & 7) * 8) = oka[i] ? ra[i] : (u32x4){0u, 0u, 0u, 0u}; }
; #pragma unroll
;     for (int i = 0; i < CB; ++i) { const int c = tid + NTHR * i; *(u32x4*)(Bs + (c >> 3) * LDT + (c & 7) * 8) = rb[i]; }
;   };
;   gload(0); sstore(0); gload(nk > 1 ? 1 : 0); __syncthreads();
; #pragma unroll 1
;   for (int kt = 0; kt < nk; ++kt) {
;     const int buf = kt & 1;
;     sstore(buf ^ 1);
;     gload(kt + 2 < nk ? kt + 2 : nk - 1);
;     __builtin_amdgcn_sched_barrier(0);
;     const bf16_t* As = smem + buf * L::STAGE + (wm * 16 * MI + l15) * LDT + quad * 8;
;     const bf16_t* Bs = smem + buf * L::STAGE + L::A_ELEMS + (wn * 16 * NJ + l15) * LDT + quad * 8;
; #pragma unroll
;     for (int ks = 0; ks < 2; ++ks) {
;       if (MI * NJ >= 32 && ks == 1) asm volatile("" ::: "memory");
;       bf16x8 b[NJ];
; #pragma unroll
;       for (int j = 0; j < NJ; ++j) b[j] = *(const bf16x8*)(Bs + j * 16 * LDT + ks * 32);
; #pragma unroll
;       for (int i = 0; i < MI; ++i) {
;         const bf16x8 a = *(const bf16x8*)(As + i * 16 * LDT + ks * 32);
; #pragma unroll
;         for (int j = 0; j < NJ; ++j) acc[i][j] = SWAP ? mfma16(b[j], a, acc[i][j]) : mfma16(a, b[j], acc[i][j]);
;       }
;     }
;     __syncthreads();
;   }
.Lgm5_main:
	ds_read_b128 v[242:245], v177 offset:4608
	s_waitcnt lgkmcnt(4)
	v_mfma_f32_16x16x32_bf16 v[156:159], v[178:181], v[194:197], v[156:159]
	s_waitcnt lgkmcnt(3)
	v_mfma_f32_16x16x32_bf16 v[152:155], v[182:185], v[194:197], v[152:155]
	s_waitcnt lgkmcnt(2)
	v_mfma_f32_16x16x32_bf16 v[148:151], v[186:189], v[194:197], v[148:151]
	s_and_b32 s15, s1, 1
	s_min_u32 s16, s1, 13
	s_xor_b32 s17, s15, 1
	s_mul_i32 s17, s17, 0x12000
	v_add3_u32 v250, s17, v172, v170
	s_waitcnt vmcnt(7)
	ds_write_b128 v250, v[112:115]
	s_waitcnt lgkmcnt(2)
	v_mfma_f32_16x16x32_bf16 v[128:131], v[190:193], v[194:197], v[128:131]
	ds_read_b128 v[246:249], v177 offset:6912
	v_mfma_f32_16x16x32_bf16 v[108:111], v[178:181], v[198:201], v[108:111]
	v_mfma_f32_16x16x32_bf16 v[104:107], v[182:185], v[198:201], v[104:107]
	v_mfma_f32_16x16x32_bf16 v[100:103], v[186:189], v[198:201], v[100:103]
	s_lshl_b32 s26, s16, 7
	s_add_u32 s16, s2, s26
	v_add3_u32 v251, s17, v174, v170
	v_add3_u32 v252, s17, v175, v170
	v_add3_u32 v253, s17, v176, v170
	s_addc_u32 s17, s3, 0
	v_lshl_add_u64 v[112:113], s[16:17], 0, v[162:163]
	s_nop 0
	global_load_dwordx4 v[112:115], v[112:113], off offset:256
	v_mfma_f32_16x16x32_bf16 v[96:99], v[190:193], v[198:201], v[96:99]
	ds_read_b128 v[194:197], v177 offset:9216
	s_waitcnt lgkmcnt(3)
	v_mfma_f32_16x16x32_bf16 v[92:95], v[178:181], v[242:245], v[92:95]
	s_waitcnt vmcnt(7)
	ds_write_b128 v251, v[116:119]
	v_mfma_f32_16x16x32_bf16 v[88:91], v[182:185], v[242:245], v[88:91]
	v_mfma_f32_16x16x32_bf16 v[84:87], v[186:189], v[242:245], v[84:87]
	v_mfma_f32_16x16x32_bf16 v[80:83], v[190:193], v[242:245], v[80:83]
	ds_read_b128 v[198:201], v177 offset:11520
	s_waitcnt lgkmcnt(3)
	v_mfma_f32_16x16x32_bf16 v[76:79], v[178:181], v[246:249], v[76:79]
	v_lshl_add_u64 v[116:117], s[16:17], 0, v[164:165]
	s_nop 0
	global_load_dwordx4 v[116:119], v[116:117], off offset:256
	v_mfma_f32_16x16x32_bf16 v[72:75], v[182:185], v[246:249], v[72:75]
	v_mfma_f32_16x16x32_bf16 v[68:71], v[186:189], v[246:249], v[68:71]
	s_waitcnt vmcnt(7)
	ds_write_b128 v252, v[120:123]
	v_mfma_f32_16x16x32_bf16 v[64:67], v[190:193], v[246:249], v[64:67]
	ds_read_b128 v[242:245], v177 offset:13824
	s_waitcnt lgkmcnt(4)
	v_mfma_f32_16x16x32_bf16 v[60:63], v[178:181], v[194:197], v[60:63]
	v_mfma_f32_16x16x32_bf16 v[56:59], v[182:185], v[194:197], v[56:59]
	v_mfma_f32_16x16x32_bf16 v[52:55], v[186:189], v[194:197], v[52:55]
	v_lshl_add_u64 v[120:121], s[16:17], 0, v[166:167]
	s_nop 0
	global_load_dwordx4 v[120:123], v[120:121], off offset:256
	v_mfma_f32_16x16x32_bf16 v[48:51], v[190:193], v[194:197], v[48:51]
	ds_read_b128 v[246:249], v177 offset:16128
	s_waitcnt lgkmcnt(3)
	v_mfma_f32_16x16x32_bf16 v[44:47], v[178:181], v[198:201], v[44:47]
	s_waitcnt vmcnt(7)
	ds_write_b128 v253, v[124:127]
	v_mfma_f32_16x16x32_bf16 v[40:43], v[182:185], v[198:201], v[40:43]
	v_mfma_f32_16x16x32_bf16 v[36:39], v[186:189], v[198:201], v[36:39]
	v_mfma_f32_16x16x32_bf16 v[32:35], v[190:193], v[198:201], v[32:35]
	ds_read_b128 v[194:197], v177 offset:64
	s_waitcnt lgkmcnt(3)
	v_mfma_f32_16x16x32_bf16 v[28:31], v[178:181], v[242:245], v[28:31]
	v_lshl_add_u64 v[124:125], s[16:17], 0, v[168:169]
	s_nop 0
	global_load_dwordx4 v[124:127], v[124:125], off offset:256
	v_mfma_f32_16x16x32_bf16 v[24:27], v[182:185], v[242:245], v[24:27]
	v_mfma_f32_16x16x32_bf16 v[20:23], v[186:189], v[242:245], v[20:23]
	s_waitcnt vmcnt(7)
	ds_write_b128 v250, v[132:135] offset:36864
	v_mfma_f32_16x16x32_bf16 v[16:19], v[190:193], v[242:245], v[16:19]
	ds_read_b128 v[198:201], v177 offset:2368
	s_waitcnt lgkmcnt(4)
	v_mfma_f32_16x16x32_bf16 v[8:11], v[178:181], v[246:249], v[8:11]
	ds_read_b128 v[178:181], v202 offset:36928
	v_mfma_f32_16x16x32_bf16 v[4:7], v[182:185], v[246:249], v[4:7]
	ds_read_b128 v[182:185], v202 offset:39232
	v_mfma_f32_16x16x32_bf16 v[0:3], v[186:189], v[246:249], v[0:3]
	ds_read_b128 v[186:189], v202 offset:41536
	s_add_u32 s16, s12, s26
	s_addc_u32 s17, s13, 0
	v_lshl_add_u64 v[132:133], s[16:17], 0, v[162:163]
	s_nop 0
	global_load_dwordx4 v[132:135], v[132:133], off offset:256
	v_mfma_f32_16x16x32_bf16 v[12:15], v[190:193], v[246:249], v[12:15]
	ds_read_b128 v[190:193], v202 offset:43840
	ds_read_b128 v[242:245], v177 offset:4672
	s_waitcnt lgkmcnt(4)
; DI f32x4 mfma16(bf16x8 a, bf16x8 b, f32x4 c) { return __builtin_amdgcn_mfma_f32_16x16x32_bf16(a, b, c, 0, 0, 0); }
; template <int MI, int NJ, bool SWAP, class AP, class BP>
; DI void gemm_main(f32x4 (&acc)[MI][NJ], const AP& ap, int a_kstep, const BP& bp, int b_kstep, int nk, bf16_t* smem) {
;     ...
;   auto gload = [&](int kt) {
;     const bf16_t* ab = ap.base + (size_t)kt * a_kstep; const bf16_t* bb = bp.base + (size_t)kt * b_kstep;
; #pragma unroll
;     for (int i = 0; i < CA; ++i) ra[i] = *(const u32x4*)(ab + pa[i]);
; #pragma unroll
;     for (int i = 0; i < CB; ++i) rb[i] = *(const u32x4*)(bb + pb[i]);
;   };
;   auto sstore = [&](int buf) {
;     bf16_t* As = smem + buf * L::STAGE; bf16_t* Bs = As + L::A_ELEMS;
; #pragma unroll
;     for (int i = 0; i < CA; ++i) { const int c = tid + NTHR * i; *(u32x4*)(As + (c >> 3) * LDT + (c & 7) * 8) = oka[i] ? ra[i] : (u32x4){0u, 0u, 0u, 0u}; }
; #pragma unroll
;     for (int i = 0; i < CB; ++i) { const int c = tid + NTHR * i; *(u32x4*)(Bs + (c >> 3) * LDT + (c & 7) * 8) = rb[i]; }
;   };
;   gload(0); sstore(0); gload(nk > 1 ? 1 : 0); __syncthreads();
; #pragma unroll 1
;   for (int kt = 0; kt < nk; ++kt) {
;     const int buf = kt & 1;
;     sstore(buf ^ 1);
;     gload(kt + 2 < nk ? kt + 2 : nk - 1);
;     __builtin_amdgcn_sched_barrier(0);
;     const bf16_t* As = smem + buf * L::STAGE + (wm * 16 * MI + l15) * LDT + quad * 8;
;     const bf16_t* Bs = smem + buf * L::STAGE + L::A_ELEMS + (wn * 16 * NJ + l15) * LDT + quad * 8;
; #pragma unroll
;     for (int ks = 0; ks < 2; ++ks) {
;       if (MI * NJ >= 32 && ks == 1) asm volatile("" ::: "memory");
;       bf16x8 b[NJ];
; #pragma unroll
;       for (int j = 0; j < NJ; ++j) b[j] = *(const bf16x8*)(Bs + j * 16 * LDT + ks * 32);
; #pragma unroll
;       for (int i = 0; i < MI; ++i) {
;         const bf16x8 a = *(const bf16x8*)(As + i * 16 * LDT + ks * 32);
; #pragma unroll
;         for (int j = 0; j < NJ; ++j) acc[i][j] = SWAP ? mfma16(b[j], a, acc[i][j]) : mfma16(a, b[j], acc[i][j]);
;       }
;     }
;     __syncthreads();
;   }
	v_mfma_f32_16x16x32_bf16 v[156:159], v[178:181], v[194:197], v[156:159]
	s_waitcnt vmcnt(7)
	ds_write_b128 v251, v[136:139] offset:36864
	s_waitcnt lgkmcnt(4)
	v_mfma_f32_16x16x32_bf16 v[152:155], v[182:185], v[194:197], v[152:155]
	s_waitcnt lgkmcnt(3)
	v_mfma_f32_16x16x32_bf16 v[148:151], v[186:189], v[194:197], v[148:151]
	s_waitcnt lgkmcnt(2)
	v_mfma_f32_16x16x32_bf16 v[128:131], v[190:193], v[194:197], v[128:131]
	ds_read_b128 v[246:249], v177 offset:6976
	v_mfma_f32_16x16x32_bf16 v[108:111], v[178:181], v[198:201], v[108:111]
	v_lshl_add_u64 v[136:137], s[16:17], 0, v[164:165]
	s_nop 0
	global_load_dwordx4 v[136:139], v[136:137], off offset:256
	v_mfma_f32_16x16x32_bf16 v[104:107], v[182:185], v[198:201], v[104:107]
	v_mfma_f32_16x16x32_bf16 v[100:103], v[186:189], v[198:201], v[100:103]
	s_waitcnt vmcnt(7)
	ds_write_b128 v252, v[140:143] offset:36864
	v_mfma_f32_16x16x32_bf16 v[96:99], v[190:193], v[198:201], v[96:99]
	ds_read_b128 v[194:197], v177 offset:9280
	s_waitcnt lgkmcnt(4)
	v_mfma_f32_16x16x32_bf16 v[92:95], v[178:181], v[242:245], v[92:95]
	v_mfma_f32_16x16x32_bf16 v[88:91], v[182:185], v[242:245], v[88:91]
	v_mfma_f32_16x16x32_bf16 v[84:87], v[186:189], v[242:245], v[84:87]
	v_lshl_add_u64 v[140:141], s[16:17], 0, v[166:167]
	s_nop 0
	global_load_dwordx4 v[140:143], v[140:141], off offset:256
	v_mfma_f32_16x16x32_bf16 v[80:83], v[190:193], v[242:245], v[80:83]
	ds_read_b128 v[198:201], v177 offset:11584
	s_waitcnt lgkmcnt(3)
	v_mfma_f32_16x16x32_bf16 v[76:79], v[178:181], v[246:249], v[76:79]
	s_waitcnt vmcnt(7)
	ds_write_b128 v253, v[144:147] offset:36864
	v_mfma_f32_16x16x32_bf16 v[72:75], v[182:185], v[246:249], v[72:75]
	v_mfma_f32_16x16x32_bf16 v[68:71], v[186:189], v[246:249], v[68:71]
	v_mfma_f32_16x16x32_bf16 v[64:67], v[190:193], v[246:249], v[64:67]
	ds_read_b128 v[242:245], v177 offset:13888
	s_waitcnt lgkmcnt(3)
	v_mfma_f32_16x16x32_bf16 v[60:63], v[178:181], v[194:197], v[60:63]
	v_lshl_add_u64 v[144:145], s[16:17], 0, v[168:169]
	s_nop 0
	global_load_dwordx4 v[144:147], v[144:145], off offset:256
	v_mfma_f32_16x16x32_bf16 v[56:59], v[182:185], v[194:197], v[56:59]
	v_mfma_f32_16x16x32_bf16 v[52:55], v[186:189], v[194:197], v[52:55]
	v_mfma_f32_16x16x32_bf16 v[48:51], v[190:193], v[194:197], v[48:51]
	ds_read_b128 v[246:249], v177 offset:16192
	s_waitcnt lgkmcnt(3)
	v_mfma_f32_16x16x32_bf16 v[44:47], v[178:181], v[198:201], v[44:47]
	v_mfma_f32_16x16x32_bf16 v[40:43], v[182:185], v[198:201], v[40:43]
	v_mfma_f32_16x16x32_bf16 v[36:39], v[186:189], v[198:201], v[36:39]
	v_mfma_f32_16x16x32_bf16 v[32:35], v[190:193], v[198:201], v[32:35]
	s_add_i32 s1, s1, 1
	s_and_b32 s98, s1, 1
	s_mul_i32 s98, s98, 0x12000
	v_add3_u32 v202, s98, v160, v173
	v_add3_u32 v177, s98, v171, v173
	s_cmp_lg_u32 s1, 16
	s_waitcnt lgkmcnt(0)
	s_barrier
	s_cbranch_scc0 .Lgm5_exit
	ds_read_b128 v[194:197], v177
	ds_read_b128 v[198:201], v177 offset:2304
	v_mfma_f32_16x16x32_bf16 v[28:31], v[178:181], v[242:245], v[28:31]
	v_mfma_f32_16x16x32_bf16 v[8:11], v[178:181], v[246:249], v[8:11]
	ds_read_b128 v[178:181], v202 offset:36864
	v_mfma_f32_16x16x32_bf16 v[24:27], v[182:185], v[242:245], v[24:27]
	v_mfma_f32_16x16x32_bf16 v[4:7], v[182:185], v[246:249], v[4:7]
	ds_read_b128 v[182:185], v202 offset:39168
	v_mfma_f32_16x16x32_bf16 v[20:23], v[186:189], v[242:245], v[20:23]
	v_mfma_f32_16x16x32_bf16 v[0:3], v[186:189], v[246:249], v[0:3]
	ds_read_b128 v[186:189], v202 offset:41472
	v_mfma_f32_16x16x32_bf16 v[16:19], v[190:193], v[242:245], v[16:19]
	v_mfma_f32_16x16x32_bf16 v[12:15], v[190:193], v[246:249], v[12:15]
	ds_read_b128 v[190:193], v202 offset:43776
	s_branch .Lgm5_main

; DI f32x4 mfma16(bf16x8 a, bf16x8 b, f32x4 c) { return __builtin_amdgcn_mfma_f32_16x16x32_bf16(a, b, c, 0, 0, 0); }
; template <int MI, int NJ, bool SWAP, class AP, class BP>
; DI void gemm_main(f32x4 (&acc)[MI][NJ], const AP& ap, int a_kstep, const BP& bp, int b_kstep, int nk, bf16_t* smem) {
;     ...
;   auto gload = [&](int kt) {
;     const bf16_t* ab = ap.base + (size_t)kt * a_kstep; const bf16_t* bb = bp.base + (size_t)kt * b_kstep;
; #pragma unroll
;     for (int i = 0; i < CA; ++i) ra[i] = *(const u32x4*)(ab + pa[i]);
; #pragma unroll
;     for (int i = 0; i < CB; ++i) rb[i] = *(const u32x4*)(bb + pb[i]);
;   };
;   auto sstore = [&](int buf) {
;     bf16_t* As = smem + buf * L::STAGE; bf16_t* Bs = As + L::A_ELEMS;
; #pragma unroll
;     for (int i = 0; i < CA; ++i) { const int c = tid + NTHR * i; *(u32x4*)(As + (c >> 3) * LDT + (c & 7) * 8) = oka[i] ? ra[i] : (u32x4){0u, 0u, 0u, 0u}; }
; #pragma unroll
;     for (int i = 0; i < CB; ++i) { const int c = tid + NTHR * i; *(u32x4*)(Bs + (c >> 3) * LDT + (c & 7) * 8) = rb[i]; }
;   };
;   gload(0); sstore(0); gload(nk > 1 ? 1 : 0); __syncthreads();
; #pragma unroll 1
;   for (int kt = 0; kt < nk; ++kt) {
;     const int buf = kt & 1;
;     sstore(buf ^ 1);
;     gload(kt + 2 < nk ? kt + 2 : nk - 1);
;     __builtin_amdgcn_sched_barrier(0);
;     const bf16_t* As = smem + buf * L::STAGE + (wm * 16 * MI + l15) * LDT + quad * 8;
;     const bf16_t* Bs = smem + buf * L::STAGE + L::A_ELEMS + (wn * 16 * NJ + l15) * LDT + quad * 8;
; #pragma unroll
;     for (int ks = 0; ks < 2; ++ks) {
;       if (MI * NJ >= 32 && ks == 1) asm volatile("" ::: "memory");
;       bf16x8 b[NJ];
; #pragma unroll
;       for (int j = 0; j < NJ; ++j) b[j] = *(const bf16x8*)(Bs + j * 16 * LDT + ks * 32);
; #pragma unroll
;       for (int i = 0; i < MI; ++i) {
;         const bf16x8 a = *(const bf16x8*)(As + i * 16 * LDT + ks * 32);
; #pragma unroll
;         for (int j = 0; j < NJ; ++j) acc[i][j] = SWAP ? mfma16(b[j], a, acc[i][j]) : mfma16(a, b[j], acc[i][j]);
;       }
;     }
;     __syncthreads();
;   }
.Lgm6_main:
	ds_read_b128 v[246:249], v181 offset:4608
	s_waitcnt lgkmcnt(4)
	v_mfma_f32_16x16x32_bf16 v[156:159], v[182:185], v[198:201], v[156:159]
	s_waitcnt lgkmcnt(3)
	v_mfma_f32_16x16x32_bf16 v[152:155], v[186:189], v[198:201], v[152:155]
	s_waitcnt lgkmcnt(2)
	v_mfma_f32_16x16x32_bf16 v[148:151], v[190:193], v[198:201], v[148:151]
	s_waitcnt vmcnt(7)
	v_cndmask_b32_e32 v139, 0, v139, vcc
	v_cndmask_b32_e32 v138, 0, v138, vcc
	v_cndmask_b32_e32 v137, 0, v137, vcc
	v_cndmask_b32_e32 v136, 0, v136, vcc
	s_and_b32 s31, s30, 1
	s_xor_b32 s33, s31, 1
	s_mul_i32 s33, s33, 0x12000
	v_add3_u32 v254, s33, v172, v169
	ds_write_b128 v254, v[136:139]
	s_waitcnt lgkmcnt(2)
	v_mfma_f32_16x16x32_bf16 v[144:147], v[194:197], v[198:201], v[144:147]
	ds_read_b128 v[250:253], v181 offset:6912
	v_mfma_f32_16x16x32_bf16 v[108:111], v[182:185], v[242:245], v[108:111]
	v_mfma_f32_16x16x32_bf16 v[104:107], v[186:189], v[242:245], v[104:107]
	v_mfma_f32_16x16x32_bf16 v[100:103], v[190:193], v[242:245], v[100:103]
	v_add3_u32 v238, s33, v173, v169
	v_add3_u32 v239, s33, v174, v169
	v_add3_u32 v255, s33, v175, v169
	s_min_u32 s33, s30, 13
	s_lshl_b32 s33, s33, 7
	s_add_u32 s34, s12, s33
	s_addc_u32 s35, s13, 0
	s_nop 0
	global_load_dwordx4 v[136:139], v176, s[34:35] offset:256
	v_mfma_f32_16x16x32_bf16 v[96:99], v[194:197], v[242:245], v[96:99]
	ds_read_b128 v[198:201], v181 offset:9216
	s_waitcnt lgkmcnt(3)
	v_mfma_f32_16x16x32_bf16 v[92:95], v[182:185], v[246:249], v[92:95]
	s_waitcnt vmcnt(7)
	v_cndmask_b32_e64 v127, 0, v127, s[0:1]
	v_cndmask_b32_e64 v126, 0, v126, s[0:1]
	v_cndmask_b32_e64 v125, 0, v125, s[0:1]
	v_cndmask_b32_e64 v124, 0, v124, s[0:1]
	ds_write_b128 v238, v[124:127]
	v_mfma_f32_16x16x32_bf16 v[88:91], v[186:189], v[246:249], v[88:91]
	v_mfma_f32_16x16x32_bf16 v[84:87], v[190:193], v[246:249], v[84:87]
	v_mfma_f32_16x16x32_bf16 v[80:83], v[194:197], v[246:249], v[80:83]
	ds_read_b128 v[242:245], v181 offset:11520
	s_waitcnt lgkmcnt(3)
	v_mfma_f32_16x16x32_bf16 v[76:79], v[182:185], v[250:253], v[76:79]
	s_nop 0
	global_load_dwordx4 v[124:127], v177, s[34:35] offset:256
	v_mfma_f32_16x16x32_bf16 v[72:75], v[186:189], v[250:253], v[72:75]
	v_mfma_f32_16x16x32_bf16 v[68:71], v[190:193], v[250:253], v[68:71]
	s_waitcnt vmcnt(7)
	v_cndmask_b32_e64 v115, 0, v115, s[2:3]
	v_cndmask_b32_e64 v114, 0, v114, s[2:3]
	v_cndmask_b32_e64 v113, 0, v113, s[2:3]
	v_cndmask_b32_e64 v112, 0, v112, s[2:3]
	ds_write_b128 v239, v[112:115]
	v_mfma_f32_16x16x32_bf16 v[64:67], v[194:197], v[250:253], v[64:67]
	ds_read_b128 v[246:249], v181 offset:13824
	s_waitcnt lgkmcnt(4)
	v_mfma_f32_16x16x32_bf16 v[60:63], v[182:185], v[198:201], v[60:63]
	v_mfma_f32_16x16x32_bf16 v[56:59], v[186:189], v[198:201], v[56:59]
	v_mfma_f32_16x16x32_bf16 v[52:55], v[190:193], v[198:201], v[52:55]
	v_mfma_f32_16x16x32_bf16 v[48:51], v[194:197], v[198:201], v[48:51]
	ds_read_b128 v[250:253], v181 offset:16128
	s_waitcnt lgkmcnt(3)
	v_mfma_f32_16x16x32_bf16 v[44:47], v[182:185], v[242:245], v[44:47]
	s_waitcnt vmcnt(6)
	v_cndmask_b32_e64 v112, 0, v116, s[4:5]
	v_cndmask_b32_e64 v115, 0, v119, s[4:5]
	v_cndmask_b32_e64 v114, 0, v118, s[4:5]
	v_cndmask_b32_e64 v113, 0, v117, s[4:5]
	ds_write_b128 v255, v[112:115]
	v_mfma_f32_16x16x32_bf16 v[40:43], v[186:189], v[242:245], v[40:43]
	v_mfma_f32_16x16x32_bf16 v[36:39], v[190:193], v[242:245], v[36:39]
	v_mfma_f32_16x16x32_bf16 v[32:35], v[194:197], v[242:245], v[32:35]
	ds_read_b128 v[198:201], v181 offset:64
	s_waitcnt lgkmcnt(3)
	v_mfma_f32_16x16x32_bf16 v[28:31], v[182:185], v[246:249], v[28:31]
	s_nop 0
	global_load_dwordx4 v[112:115], v178, s[34:35] offset:256
	s_nop 0
	global_load_dwordx4 v[116:119], v179, s[34:35] offset:256
	v_mfma_f32_16x16x32_bf16 v[24:27], v[186:189], v[246:249], v[24:27]
	v_mfma_f32_16x16x32_bf16 v[20:23], v[190:193], v[246:249], v[20:23]
	s_waitcnt vmcnt(7)
	ds_write_b128 v254, v[120:123] offset:36864
	v_mfma_f32_16x16x32_bf16 v[16:19], v[194:197], v[246:249], v[16:19]
	ds_read_b128 v[242:245], v181 offset:2368
	s_waitcnt lgkmcnt(4)
; DI f32x4 mfma16(bf16x8 a, bf16x8 b, f32x4 c) { return __builtin_amdgcn_mfma_f32_16x16x32_bf16(a, b, c, 0, 0, 0); }
; template <int MI, int NJ, bool SWAP, class AP, class BP>
; DI void gemm_main(f32x4 (&acc)[MI][NJ], const AP& ap, int a_kstep, const BP& bp, int b_kstep, int nk, bf16_t* smem) {
;     ...
;   auto gload = [&](int kt) {
;     const bf16_t* ab = ap.base + (size_t)kt * a_kstep; const bf16_t* bb = bp.base + (size_t)kt * b_kstep;
; #pragma unroll
;     for (int i = 0; i < CA; ++i) ra[i] = *(const u32x4*)(ab + pa[i]);
; #pragma unroll
;     for (int i = 0; i < CB; ++i) rb[i] = *(const u32x4*)(bb + pb[i]);
;   };
;   auto sstore = [&](int buf) {
;     bf16_t* As = smem + buf * L::STAGE; bf16_t* Bs = As + L::A_ELEMS;
; #pragma unroll
;     for (int i = 0; i < CA; ++i) { const int c = tid + NTHR * i; *(u32x4*)(As + (c >> 3) * LDT + (c & 7) * 8) = oka[i] ? ra[i] : (u32x4){0u, 0u, 0u, 0u}; }
; #pragma unroll
;     for (int i = 0; i < CB; ++i) { const int c = tid + NTHR * i; *(u32x4*)(Bs + (c >> 3) * LDT + (c & 7) * 8) = rb[i]; }
;   };
;   gload(0); sstore(0); gload(nk > 1 ? 1 : 0); __syncthreads();
; #pragma unroll 1
;   for (int kt = 0; kt < nk; ++kt) {
;     const int buf = kt & 1;
;     sstore(buf ^ 1);
;     gload(kt + 2 < nk ? kt + 2 : nk - 1);
;     __builtin_amdgcn_sched_barrier(0);
;     const bf16_t* As = smem + buf * L::STAGE + (wm * 16 * MI + l15) * LDT + quad * 8;
;     const bf16_t* Bs = smem + buf * L::STAGE + L::A_ELEMS + (wn * 16 * NJ + l15) * LDT + quad * 8;
; #pragma unroll
;     for (int ks = 0; ks < 2; ++ks) {
;       if (MI * NJ >= 32 && ks == 1) asm volatile("" ::: "memory");
;       bf16x8 b[NJ];
; #pragma unroll
;       for (int j = 0; j < NJ; ++j) b[j] = *(const bf16x8*)(Bs + j * 16 * LDT + ks * 32);
; #pragma unroll
;       for (int i = 0; i < MI; ++i) {
;         const bf16x8 a = *(const bf16x8*)(As + i * 16 * LDT + ks * 32);
; #pragma unroll
;         for (int j = 0; j < NJ; ++j) acc[i][j] = SWAP ? mfma16(b[j], a, acc[i][j]) : mfma16(a, b[j], acc[i][j]);
;       }
;     }
;     __syncthreads();
;   }
	v_mfma_f32_16x16x32_bf16 v[12:15], v[182:185], v[250:253], v[12:15]
	ds_read_b128 v[182:185], v202 offset:36928
	v_mfma_f32_16x16x32_bf16 v[8:11], v[186:189], v[250:253], v[8:11]
	ds_read_b128 v[186:189], v202 offset:39232
	v_mfma_f32_16x16x32_bf16 v[4:7], v[190:193], v[250:253], v[4:7]
	ds_read_b128 v[190:193], v202 offset:41536
	s_add_u32 s34, s14, s33
	s_addc_u32 s35, s15, 0
	v_lshl_add_u64 v[120:121], v[160:161], 1, s[34:35]
	s_nop 0
	global_load_dwordx4 v[120:123], v[120:121], off offset:256
	v_mfma_f32_16x16x32_bf16 v[0:3], v[194:197], v[250:253], v[0:3]
	ds_read_b128 v[194:197], v202 offset:43840
	ds_read_b128 v[246:249], v181 offset:4672
	s_waitcnt lgkmcnt(4)
	v_mfma_f32_16x16x32_bf16 v[156:159], v[182:185], v[198:201], v[156:159]
	s_waitcnt vmcnt(7)
	ds_write_b128 v238, v[128:131] offset:36864
	s_waitcnt lgkmcnt(4)
	v_mfma_f32_16x16x32_bf16 v[152:155], v[186:189], v[198:201], v[152:155]
	s_waitcnt lgkmcnt(3)
	v_mfma_f32_16x16x32_bf16 v[148:151], v[190:193], v[198:201], v[148:151]
	s_waitcnt lgkmcnt(2)
	v_mfma_f32_16x16x32_bf16 v[144:147], v[194:197], v[198:201], v[144:147]
	ds_read_b128 v[250:253], v181 offset:6976
	v_mfma_f32_16x16x32_bf16 v[108:111], v[182:185], v[242:245], v[108:111]
	v_lshl_add_u64 v[128:129], v[162:163], 1, s[34:35]
	s_nop 0
	global_load_dwordx4 v[128:131], v[128:129], off offset:256
	v_mfma_f32_16x16x32_bf16 v[104:107], v[186:189], v[242:245], v[104:107]
	v_mfma_f32_16x16x32_bf16 v[100:103], v[190:193], v[242:245], v[100:103]
	s_waitcnt vmcnt(7)
	ds_write_b128 v239, v[132:135] offset:36864
	v_mfma_f32_16x16x32_bf16 v[96:99], v[194:197], v[242:245], v[96:99]
	ds_read_b128 v[198:201], v181 offset:9280
	s_waitcnt lgkmcnt(4)
	v_mfma_f32_16x16x32_bf16 v[92:95], v[182:185], v[246:249], v[92:95]
	v_mfma_f32_16x16x32_bf16 v[88:91], v[186:189], v[246:249], v[88:91]
	v_mfma_f32_16x16x32_bf16 v[84:87], v[190:193], v[246:249], v[84:87]
	v_lshl_add_u64 v[132:133], v[164:165], 1, s[34:35]
	s_nop 0
	global_load_dwordx4 v[132:135], v[132:133], off offset:256
	v_mfma_f32_16x16x32_bf16 v[80:83], v[194:197], v[246:249], v[80:83]
	ds_read_b128 v[242:245], v181 offset:11584
	s_waitcnt lgkmcnt(3)
	v_mfma_f32_16x16x32_bf16 v[76:79], v[182:185], v[250:253], v[76:79]
	s_waitcnt vmcnt(7)
	ds_write_b128 v255, v[140:143] offset:36864
	v_mfma_f32_16x16x32_bf16 v[72:75], v[186:189], v[250:253], v[72:75]
	v_mfma_f32_16x16x32_bf16 v[68:71], v[190:193], v[250:253], v[68:71]
	v_mfma_f32_16x16x32_bf16 v[64:67], v[194:197], v[250:253], v[64:67]
	ds_read_b128 v[246:249], v181 offset:13888
	s_waitcnt lgkmcnt(3)
	v_mfma_f32_16x16x32_bf16 v[60:63], v[182:185], v[198:201], v[60:63]
	v_lshl_add_u64 v[140:141], v[166:167], 1, s[34:35]
	s_nop 0
	global_load_dwordx4 v[140:143], v[140:141], off offset:256
	v_mfma_f32_16x16x32_bf16 v[56:59], v[186:189], v[198:201], v[56:59]
	v_mfma_f32_16x16x32_bf16 v[52:55], v[190:193], v[198:201], v[52:55]
	v_mfma_f32_16x16x32_bf16 v[48:51], v[194:197], v[198:201], v[48:51]
	ds_read_b128 v[250:253], v181 offset:16192
	s_waitcnt lgkmcnt(3)
	v_mfma_f32_16x16x32_bf16 v[44:47], v[182:185], v[242:245], v[44:47]
	v_mfma_f32_16x16x32_bf16 v[40:43], v[186:189], v[242:245], v[40:43]
	v_mfma_f32_16x16x32_bf16 v[36:39], v[190:193], v[242:245], v[36:39]
	v_mfma_f32_16x16x32_bf16 v[32:35], v[194:197], v[242:245], v[32:35]
	s_add_i32 s30, s30, 1
	s_and_b32 s98, s30, 1
	s_mul_i32 s98, s98, 0x12000
	v_add3_u32 v181, s98, v170, v180
	v_add3_u32 v202, s98, v171, v180
	s_cmp_lg_u32 s30, 16
	s_waitcnt lgkmcnt(0)
	s_barrier
	s_cbranch_scc0 .Lgm6_exit
	ds_read_b128 v[198:201], v181
	ds_read_b128 v[242:245], v181 offset:2304
	v_mfma_f32_16x16x32_bf16 v[28:31], v[182:185], v[246:249], v[28:31]
	v_mfma_f32_16x16x32_bf16 v[12:15], v[182:185], v[250:253], v[12:15]
	ds_read_b128 v[182:185], v202 offset:36864
	v_mfma_f32_16x16x32_bf16 v[24:27], v[186:189], v[246:249], v[24:27]
	v_mfma_f32_16x16x32_bf16 v[8:11], v[186:189], v[250:253], v[8:11]
	ds_read_b128 v[186:189], v202 offset:39168
	v_mfma_f32_16x16x32_bf16 v[20:23], v[190:193], v[246:249], v[20:23]
	v_mfma_f32_16x16x32_bf16 v[4:7], v[190:193], v[250:253], v[4:7]
	ds_read_b128 v[190:193], v202 offset:41472
	v_mfma_f32_16x16x32_bf16 v[16:19], v[194:197], v[246:249], v[16:19]
	v_mfma_f32_16x16x32_bf16 v[0:3], v[194:197], v[250:253], v[0:3]
	ds_read_b128 v[194:197], v202 offset:43776
	s_branch .Lgm6_main

; DI f32x4 mfma16(bf16x8 a, bf16x8 b, f32x4 c) { return __builtin_amdgcn_mfma_f32_16x16x32_bf16(a, b, c, 0, 0, 0); }
; template <int MI, int NJ, bool SWAP, class AP, class BP>
; DI void gemm_main(f32x4 (&acc)[MI][NJ], const AP& ap, int a_kstep, const BP& bp, int b_kstep, int nk, bf16_t* smem) {
;     ...
;   auto gload = [&](int kt) {
;     const bf16_t* ab = ap.base + (size_t)kt * a_kstep; const bf16_t* bb = bp.base + (size_t)kt * b_kstep;
; #pragma unroll
;     for (int i = 0; i < CA; ++i) ra[i] = *(const u32x4*)(ab + pa[i]);
; #pragma unroll
;     for (int i = 0; i < CB; ++i) rb[i] = *(const u32x4*)(bb + pb[i]);
;   };
;   auto sstore = [&](int buf) {
;     bf16_t* As = smem + buf * L::STAGE; bf16_t* Bs = As + L::A_ELEMS;
; #pragma unroll
;     for (int i = 0; i < CA; ++i) { const int c = tid + NTHR * i; *(u32x4*)(As + (c >> 3) * LDT + (c & 7) * 8) = oka[i] ? ra[i] : (u32x4){0u, 0u, 0u, 0u}; }
; #pragma unroll
;     for (int i = 0; i < CB; ++i) { const int c = tid + NTHR * i; *(u32x4*)(Bs + (c >> 3) * LDT + (c & 7) * 8) = rb[i]; }
;   };
;   gload(0); sstore(0); gload(nk > 1 ? 1 : 0); __syncthreads();
; #pragma unroll 1
;   for (int kt = 0; kt < nk; ++kt) {
;     const int buf = kt & 1;
;     sstore(buf ^ 1);
;     gload(kt + 2 < nk ? kt + 2 : nk - 1);
;     __builtin_amdgcn_sched_barrier(0);
;     const bf16_t* As = smem + buf * L::STAGE + (wm * 16 * MI + l15) * LDT + quad * 8;
;     const bf16_t* Bs = smem + buf * L::STAGE + L::A_ELEMS + (wn * 16 * NJ + l15) * LDT + quad * 8;
; #pragma unroll
;     for (int ks = 0; ks < 2; ++ks) {
;       if (MI * NJ >= 32 && ks == 1) asm volatile("" ::: "memory");
;       bf16x8 b[NJ];
; #pragma unroll
;       for (int j = 0; j < NJ; ++j) b[j] = *(const bf16x8*)(Bs + j * 16 * LDT + ks * 32);
; #pragma unroll
;       for (int i = 0; i < MI; ++i) {
;         const bf16x8 a = *(const bf16x8*)(As + i * 16 * LDT + ks * 32);
; #pragma unroll
;         for (int j = 0; j < NJ; ++j) acc[i][j] = SWAP ? mfma16(b[j], a, acc[i][j]) : mfma16(a, b[j], acc[i][j]);
;       }
;     }
;     __syncthreads();
;   }
.Lgm7_main:
	ds_read_b128 v[242:245], v177 offset:4608
	s_waitcnt lgkmcnt(4)
	v_mfma_f32_16x16x32_bf16 v[156:159], v[178:181], v[194:197], v[156:159]
	s_waitcnt lgkmcnt(3)
	v_mfma_f32_16x16x32_bf16 v[152:155], v[182:185], v[194:197], v[152:155]
	s_waitcnt lgkmcnt(2)
	v_mfma_f32_16x16x32_bf16 v[148:151], v[186:189], v[194:197], v[148:151]
	s_and_b32 s24, s21, 1
	s_min_u32 s22, s21, 41
	s_xor_b32 s23, s24, 1
	s_mul_i32 s23, s23, 0x12000
	v_add3_u32 v250, s23, v172, v170
	s_waitcnt vmcnt(7)
	ds_write_b128 v250, v[112:115]
	s_waitcnt lgkmcnt(2)
	v_mfma_f32_16x16x32_bf16 v[144:147], v[190:193], v[194:197], v[144:147]
	ds_read_b128 v[246:249], v177 offset:6912
	v_mfma_f32_16x16x32_bf16 v[108:111], v[178:181], v[198:201], v[108:111]
	v_mfma_f32_16x16x32_bf16 v[104:107], v[182:185], v[198:201], v[104:107]
	v_mfma_f32_16x16x32_bf16 v[100:103], v[186:189], v[198:201], v[100:103]
	s_lshl_b32 s25, s22, 7
	s_add_u32 s22, s6, s25
	v_add3_u32 v251, s23, v173, v170
	v_add3_u32 v252, s23, v174, v170
	v_add3_u32 v253, s23, v175, v170
	s_addc_u32 s23, s7, 0
	v_lshl_add_u64 v[112:113], s[22:23], 0, v[162:163]
	s_nop 0
	global_load_dwordx4 v[112:115], v[112:113], off offset:256
	v_mfma_f32_16x16x32_bf16 v[96:99], v[190:193], v[198:201], v[96:99]
	ds_read_b128 v[194:197], v177 offset:9216
	s_waitcnt lgkmcnt(3)
	v_mfma_f32_16x16x32_bf16 v[92:95], v[178:181], v[242:245], v[92:95]
	s_waitcnt vmcnt(7)
	ds_write_b128 v251, v[116:119]
	v_mfma_f32_16x16x32_bf16 v[88:91], v[182:185], v[242:245], v[88:91]
	v_mfma_f32_16x16x32_bf16 v[84:87], v[186:189], v[242:245], v[84:87]
	v_mfma_f32_16x16x32_bf16 v[80:83], v[190:193], v[242:245], v[80:83]
	ds_read_b128 v[198:201], v177 offset:11520
	s_waitcnt lgkmcnt(3)
	v_mfma_f32_16x16x32_bf16 v[76:79], v[178:181], v[246:249], v[76:79]
	v_lshl_add_u64 v[116:117], s[22:23], 0, v[164:165]
	s_nop 0
	global_load_dwordx4 v[116:119], v[116:117], off offset:256
	v_mfma_f32_16x16x32_bf16 v[72:75], v[182:185], v[246:249], v[72:75]
	v_mfma_f32_16x16x32_bf16 v[68:71], v[186:189], v[246:249], v[68:71]
	s_waitcnt vmcnt(7)
	ds_write_b128 v252, v[120:123]
	v_mfma_f32_16x16x32_bf16 v[64:67], v[190:193], v[246:249], v[64:67]
	ds_read_b128 v[242:245], v177 offset:13824
	s_waitcnt lgkmcnt(4)
	v_mfma_f32_16x16x32_bf16 v[60:63], v[178:181], v[194:197], v[60:63]
	v_mfma_f32_16x16x32_bf16 v[56:59], v[182:185], v[194:197], v[56:59]
	v_mfma_f32_16x16x32_bf16 v[52:55], v[186:189], v[194:197], v[52:55]
	v_lshl_add_u64 v[120:121], s[22:23], 0, v[166:167]
	s_nop 0
	global_load_dwordx4 v[120:123], v[120:121], off offset:256
	v_mfma_f32_16x16x32_bf16 v[48:51], v[190:193], v[194:197], v[48:51]
	ds_read_b128 v[246:249], v177 offset:16128
	s_waitcnt lgkmcnt(3)
	v_mfma_f32_16x16x32_bf16 v[44:47], v[178:181], v[198:201], v[44:47]
	s_waitcnt vmcnt(7)
	ds_write_b128 v253, v[124:127]
	v_mfma_f32_16x16x32_bf16 v[40:43], v[182:185], v[198:201], v[40:43]
	v_mfma_f32_16x16x32_bf16 v[36:39], v[186:189], v[198:201], v[36:39]
	v_mfma_f32_16x16x32_bf16 v[32:35], v[190:193], v[198:201], v[32:35]
	ds_read_b128 v[194:197], v177 offset:64
	s_waitcnt lgkmcnt(3)
	v_mfma_f32_16x16x32_bf16 v[28:31], v[178:181], v[242:245], v[28:31]
	v_lshl_add_u64 v[124:125], s[22:23], 0, v[168:169]
	s_nop 0
	global_load_dwordx4 v[124:127], v[124:125], off offset:256
	v_mfma_f32_16x16x32_bf16 v[24:27], v[182:185], v[242:245], v[24:27]
	v_mfma_f32_16x16x32_bf16 v[20:23], v[186:189], v[242:245], v[20:23]
	s_waitcnt vmcnt(7)
	ds_write_b128 v250, v[128:131] offset:36864
	v_mfma_f32_16x16x32_bf16 v[16:19], v[190:193], v[242:245], v[16:19]
	ds_read_b128 v[198:201], v177 offset:2368
	s_waitcnt lgkmcnt(4)
	v_mfma_f32_16x16x32_bf16 v[8:11], v[178:181], v[246:249], v[8:11]
	ds_read_b128 v[178:181], v202 offset:36928
	v_mfma_f32_16x16x32_bf16 v[4:7], v[182:185], v[246:249], v[4:7]
	ds_read_b128 v[182:185], v202 offset:39232
	v_mfma_f32_16x16x32_bf16 v[0:3], v[186:189], v[246:249], v[0:3]
	ds_read_b128 v[186:189], v202 offset:41536
	s_add_u32 s22, s8, s25
	s_addc_u32 s23, s9, 0
	v_lshl_add_u64 v[128:129], s[22:23], 0, v[162:163]
	s_nop 0
	global_load_dwordx4 v[128:131], v[128:129], off offset:256
	v_mfma_f32_16x16x32_bf16 v[12:15], v[190:193], v[246:249], v[12:15]
	ds_read_b128 v[190:193], v202 offset:43840
	ds_read_b128 v[242:245], v177 offset:4672
	s_waitcnt lgkmcnt(4)
; DI f32x4 mfma16(bf16x8 a, bf16x8 b, f32x4 c) { return __builtin_amdgcn_mfma_f32_16x16x32_bf16(a, b, c, 0, 0, 0); }
; template <int MI, int NJ, bool SWAP, class AP, class BP>
; DI void gemm_main(f32x4 (&acc)[MI][NJ], const AP& ap, int a_kstep, const BP& bp, int b_kstep, int nk, bf16_t* smem) {
;     ...
;   auto gload = [&](int kt) {
;     const bf16_t* ab = ap.base + (size_t)kt * a_kstep; const bf16_t* bb = bp.base + (size_t)kt * b_kstep;
; #pragma unroll
;     for (int i = 0; i < CA; ++i) ra[i] = *(const u32x4*)(ab + pa[i]);
; #pragma unroll
;     for (int i = 0; i < CB; ++i) rb[i] = *(const u32x4*)(bb + pb[i]);
;   };
;   auto sstore = [&](int buf) {
;     bf16_t* As = smem + buf * L::STAGE; bf16_t* Bs = As + L::A_ELEMS;
; #pragma unroll
;     for (int i = 0; i < CA; ++i) { const int c = tid + NTHR * i; *(u32x4*)(As + (c >> 3) * LDT + (c & 7) * 8) = oka[i] ? ra[i] : (u32x4){0u, 0u, 0u, 0u}; }
; #pragma unroll
;     for (int i = 0; i < CB; ++i) { const int c = tid + NTHR * i; *(u32x4*)(Bs + (c >> 3) * LDT + (c & 7) * 8) = rb[i]; }
;   };
;   gload(0); sstore(0); gload(nk > 1 ? 1 : 0); __syncthreads();
; #pragma unroll 1
;   for (int kt = 0; kt < nk; ++kt) {
;     const int buf = kt & 1;
;     sstore(buf ^ 1);
;     gload(kt + 2 < nk ? kt + 2 : nk - 1);
;     __builtin_amdgcn_sched_barrier(0);
;     const bf16_t* As = smem + buf * L::STAGE + (wm * 16 * MI + l15) * LDT + quad * 8;
;     const bf16_t* Bs = smem + buf * L::STAGE + L::A_ELEMS + (wn * 16 * NJ + l15) * LDT + quad * 8;
; #pragma unroll
;     for (int ks = 0; ks < 2; ++ks) {
;       if (MI * NJ >= 32 && ks == 1) asm volatile("" ::: "memory");
;       bf16x8 b[NJ];
; #pragma unroll
;       for (int j = 0; j < NJ; ++j) b[j] = *(const bf16x8*)(Bs + j * 16 * LDT + ks * 32);
; #pragma unroll
;       for (int i = 0; i < MI; ++i) {
;         const bf16x8 a = *(const bf16x8*)(As + i * 16 * LDT + ks * 32);
; #pragma unroll
;         for (int j = 0; j < NJ; ++j) acc[i][j] = SWAP ? mfma16(b[j], a, acc[i][j]) : mfma16(a, b[j], acc[i][j]);
;       }
;     }
;     __syncthreads();
;   }
	v_mfma_f32_16x16x32_bf16 v[156:159], v[178:181], v[194:197], v[156:159]
	s_waitcnt vmcnt(7)
	ds_write_b128 v251, v[132:135] offset:36864
	s_waitcnt lgkmcnt(4)
	v_mfma_f32_16x16x32_bf16 v[152:155], v[182:185], v[194:197], v[152:155]
	s_waitcnt lgkmcnt(3)
	v_mfma_f32_16x16x32_bf16 v[148:151], v[186:189], v[194:197], v[148:151]
	s_waitcnt lgkmcnt(2)
	v_mfma_f32_16x16x32_bf16 v[144:147], v[190:193], v[194:197], v[144:147]
	ds_read_b128 v[246:249], v177 offset:6976
	v_mfma_f32_16x16x32_bf16 v[108:111], v[178:181], v[198:201], v[108:111]
	v_lshl_add_u64 v[132:133], s[22:23], 0, v[164:165]
	s_nop 0
	global_load_dwordx4 v[132:135], v[132:133], off offset:256
	v_mfma_f32_16x16x32_bf16 v[104:107], v[182:185], v[198:201], v[104:107]
	v_mfma_f32_16x16x32_bf16 v[100:103], v[186:189], v[198:201], v[100:103]
	s_waitcnt vmcnt(7)
	ds_write_b128 v252, v[136:139] offset:36864
	v_mfma_f32_16x16x32_bf16 v[96:99], v[190:193], v[198:201], v[96:99]
	ds_read_b128 v[194:197], v177 offset:9280
	s_waitcnt lgkmcnt(4)
	v_mfma_f32_16x16x32_bf16 v[92:95], v[178:181], v[242:245], v[92:95]
	v_mfma_f32_16x16x32_bf16 v[88:91], v[182:185], v[242:245], v[88:91]
	v_mfma_f32_16x16x32_bf16 v[84:87], v[186:189], v[242:245], v[84:87]
	v_lshl_add_u64 v[136:137], s[22:23], 0, v[166:167]
	s_nop 0
	global_load_dwordx4 v[136:139], v[136:137], off offset:256
	v_mfma_f32_16x16x32_bf16 v[80:83], v[190:193], v[242:245], v[80:83]
	ds_read_b128 v[198:201], v177 offset:11584
	s_waitcnt lgkmcnt(3)
	v_mfma_f32_16x16x32_bf16 v[76:79], v[178:181], v[246:249], v[76:79]
	s_waitcnt vmcnt(7)
	ds_write_b128 v253, v[140:143] offset:36864
	v_mfma_f32_16x16x32_bf16 v[72:75], v[182:185], v[246:249], v[72:75]
	v_mfma_f32_16x16x32_bf16 v[68:71], v[186:189], v[246:249], v[68:71]
	v_mfma_f32_16x16x32_bf16 v[64:67], v[190:193], v[246:249], v[64:67]
	ds_read_b128 v[242:245], v177 offset:13888
	s_waitcnt lgkmcnt(3)
	v_mfma_f32_16x16x32_bf16 v[60:63], v[178:181], v[194:197], v[60:63]
	v_lshl_add_u64 v[140:141], s[22:23], 0, v[168:169]
	s_nop 0
	global_load_dwordx4 v[140:143], v[140:141], off offset:256
	v_mfma_f32_16x16x32_bf16 v[56:59], v[182:185], v[194:197], v[56:59]
	v_mfma_f32_16x16x32_bf16 v[52:55], v[186:189], v[194:197], v[52:55]
	v_mfma_f32_16x16x32_bf16 v[48:51], v[190:193], v[194:197], v[48:51]
	ds_read_b128 v[246:249], v177 offset:16192
	s_waitcnt lgkmcnt(3)
	v_mfma_f32_16x16x32_bf16 v[44:47], v[178:181], v[198:201], v[44:47]
	v_mfma_f32_16x16x32_bf16 v[40:43], v[182:185], v[198:201], v[40:43]
	v_mfma_f32_16x16x32_bf16 v[36:39], v[186:189], v[198:201], v[36:39]
	v_mfma_f32_16x16x32_bf16 v[32:35], v[190:193], v[198:201], v[32:35]
	s_add_i32 s21, s21, 1
	s_and_b32 s98, s21, 1
	s_mul_i32 s98, s98, 0x12000
	v_add3_u32 v202, s98, v160, v176
	v_add3_u32 v177, s98, v171, v176
	s_cmp_lg_u32 s21, 44
	s_waitcnt lgkmcnt(0)
	s_barrier
	s_cbranch_scc0 .Lgm7_exit
	ds_read_b128 v[194:197], v177
	ds_read_b128 v[198:201], v177 offset:2304
	v_mfma_f32_16x16x32_bf16 v[28:31], v[178:181], v[242:245], v[28:31]
	v_mfma_f32_16x16x32_bf16 v[8:11], v[178:181], v[246:249], v[8:11]
	ds_read_b128 v[178:181], v202 offset:36864
	v_mfma_f32_16x16x32_bf16 v[24:27], v[182:185], v[242:245], v[24:27]
	v_mfma_f32_16x16x32_bf16 v[4:7], v[182:185], v[246:249], v[4:7]
	ds_read_b128 v[182:185], v202 offset:39168
	v_mfma_f32_16x16x32_bf16 v[20:23], v[186:189], v[242:245], v[20:23]
	v_mfma_f32_16x16x32_bf16 v[0:3], v[186:189], v[246:249], v[0:3]
	ds_read_b128 v[186:189], v202 offset:41472
	v_mfma_f32_16x16x32_bf16 v[16:19], v[190:193], v[242:245], v[16:19]
	v_mfma_f32_16x16x32_bf16 v[12:15], v[190:193], v[246:249], v[12:15]
	ds_read_b128 v[190:193], v202 offset:43776
	s_branch .Lgm7_main

; DI f32x4 mfma16(bf16x8 a, bf16x8 b, f32x4 c) { return __builtin_amdgcn_mfma_f32_16x16x32_bf16(a, b, c, 0, 0, 0); }
; template <int MI, int NJ, bool SWAP, class AP, class BP>
; DI void gemm_main(f32x4 (&acc)[MI][NJ], const AP& ap, int a_kstep, const BP& bp, int b_kstep, int nk, bf16_t* smem) {
;     ...
;   auto gload = [&](int kt) {
;     const bf16_t* ab = ap.base + (size_t)kt * a_kstep; const bf16_t* bb = bp.base + (size_t)kt * b_kstep;
; #pragma unroll
;     for (int i = 0; i < CA; ++i) ra[i] = *(const u32x4*)(ab + pa[i]);
; #pragma unroll
;     for (int i = 0; i < CB; ++i) rb[i] = *(const u32x4*)(bb + pb[i]);
;   };
;   auto sstore = [&](int buf) {
;     bf16_t* As = smem + buf * L::STAGE; bf16_t* Bs = As + L::A_ELEMS;
; #pragma unroll
;     for (int i = 0; i < CA; ++i) { const int c = tid + NTHR * i; *(u32x4*)(As + (c >> 3) * LDT + (c & 7) * 8) = oka[i] ? ra[i] : (u32x4){0u, 0u, 0u, 0u}; }
; #pragma unroll
;     for (int i = 0; i < CB; ++i) { const int c = tid + NTHR * i; *(u32x4*)(Bs + (c >> 3) * LDT + (c & 7) * 8) = rb[i]; }
;   };
;   gload(0); sstore(0); gload(nk > 1 ? 1 : 0); __syncthreads();
; #pragma unroll 1
;   for (int kt = 0; kt < nk; ++kt) {
;     const int buf = kt & 1;
;     sstore(buf ^ 1);
;     gload(kt + 2 < nk ? kt + 2 : nk - 1);
;     __builtin_amdgcn_sched_barrier(0);
;     const bf16_t* As = smem + buf * L::STAGE + (wm * 16 * MI + l15) * LDT + quad * 8;
;     const bf16_t* Bs = smem + buf * L::STAGE + L::A_ELEMS + (wn * 16 * NJ + l15) * LDT + quad * 8;
; #pragma unroll
;     for (int ks = 0; ks < 2; ++ks) {
;       if (MI * NJ >= 32 && ks == 1) asm volatile("" ::: "memory");
;       bf16x8 b[NJ];
; #pragma unroll
;       for (int j = 0; j < NJ; ++j) b[j] = *(const bf16x8*)(Bs + j * 16 * LDT + ks * 32);
; #pragma unroll
;       for (int i = 0; i < MI; ++i) {
;         const bf16x8 a = *(const bf16x8*)(As + i * 16 * LDT + ks * 32);
; #pragma unroll
;         for (int j = 0; j < NJ; ++j) acc[i][j] = SWAP ? mfma16(b[j], a, acc[i][j]) : mfma16(a, b[j], acc[i][j]);
;       }
;     }
;     __syncthreads();
;   }
.Lgm8_main:
	ds_read_b128 v[246:249], v210 offset:4608
	s_waitcnt lgkmcnt(4)
	v_mfma_f32_16x16x32_bf16 v[124:127], v[190:193], v[206:209], v[124:127]
	s_waitcnt lgkmcnt(3)
	v_mfma_f32_16x16x32_bf16 v[120:123], v[194:197], v[206:209], v[120:123]
	s_waitcnt lgkmcnt(2)
	v_mfma_f32_16x16x32_bf16 v[116:119], v[198:201], v[206:209], v[116:119]
	s_and_b32 s5, s4, 1
	s_xor_b32 s23, s5, 1
	s_mul_i32 s23, s23, 0x12000
	v_add3_u32 v254, s23, v185, v183
	s_waitcnt vmcnt(7)
	ds_write_b128 v254, v[128:131]
	s_waitcnt lgkmcnt(2)
	v_mfma_f32_16x16x32_bf16 v[112:115], v[202:205], v[206:209], v[112:115]
	ds_read_b128 v[250:253], v210 offset:6912
	v_mfma_f32_16x16x32_bf16 v[108:111], v[190:193], v[242:245], v[108:111]
	v_mfma_f32_16x16x32_bf16 v[104:107], v[194:197], v[242:245], v[104:107]
	v_mfma_f32_16x16x32_bf16 v[100:103], v[198:201], v[242:245], v[100:103]
	s_min_u32 s99, s4, 13
	s_lshl_b32 s99, s99, 7
	s_add_u32 s26, s0, s99
	s_addc_u32 s27, s1, 0
	v_lshl_add_u64 v[128:129], s[26:27], 0, v[162:163]
	s_nop 0
	global_load_dwordx4 v[128:131], v[128:129], off offset:256
	v_mfma_f32_16x16x32_bf16 v[96:99], v[202:205], v[242:245], v[96:99]
	ds_read_b128 v[206:209], v210 offset:9216
	s_waitcnt lgkmcnt(3)
	v_mfma_f32_16x16x32_bf16 v[92:95], v[190:193], v[246:249], v[92:95]
	v_add3_u32 v238, s23, v187, v183
	s_waitcnt vmcnt(7)
	ds_write_b128 v238, v[132:135]
	v_mfma_f32_16x16x32_bf16 v[88:91], v[194:197], v[246:249], v[88:91]
	v_mfma_f32_16x16x32_bf16 v[84:87], v[198:201], v[246:249], v[84:87]
	v_mfma_f32_16x16x32_bf16 v[80:83], v[202:205], v[246:249], v[80:83]
	ds_read_b128 v[242:245], v210 offset:11520
	s_waitcnt lgkmcnt(3)
	v_mfma_f32_16x16x32_bf16 v[76:79], v[190:193], v[250:253], v[76:79]
	v_lshl_add_u64 v[132:133], s[26:27], 0, v[164:165]
	s_nop 0
	global_load_dwordx4 v[132:135], v[132:133], off offset:256
	v_mfma_f32_16x16x32_bf16 v[72:75], v[194:197], v[250:253], v[72:75]
	v_mfma_f32_16x16x32_bf16 v[68:71], v[198:201], v[250:253], v[68:71]
	v_add3_u32 v239, s23, v188, v183
	s_waitcnt vmcnt(7)
	ds_write_b128 v239, v[136:139]
	v_mfma_f32_16x16x32_bf16 v[64:67], v[202:205], v[250:253], v[64:67]
	ds_read_b128 v[246:249], v210 offset:13824
	s_waitcnt lgkmcnt(4)
	v_mfma_f32_16x16x32_bf16 v[60:63], v[190:193], v[206:209], v[60:63]
	v_mfma_f32_16x16x32_bf16 v[56:59], v[194:197], v[206:209], v[56:59]
	v_mfma_f32_16x16x32_bf16 v[52:55], v[198:201], v[206:209], v[52:55]
	v_lshl_add_u64 v[136:137], s[26:27], 0, v[166:167]
	s_nop 0
	global_load_dwordx4 v[136:139], v[136:137], off offset:256
	v_mfma_f32_16x16x32_bf16 v[48:51], v[202:205], v[206:209], v[48:51]
	ds_read_b128 v[250:253], v210 offset:16128
	s_waitcnt lgkmcnt(3)
	v_mfma_f32_16x16x32_bf16 v[44:47], v[190:193], v[242:245], v[44:47]
	v_add3_u32 v255, s23, v189, v183
	s_waitcnt vmcnt(7)
	ds_write_b128 v255, v[140:143]
	v_mfma_f32_16x16x32_bf16 v[40:43], v[194:197], v[242:245], v[40:43]
	v_mfma_f32_16x16x32_bf16 v[36:39], v[198:201], v[242:245], v[36:39]
	v_mfma_f32_16x16x32_bf16 v[32:35], v[202:205], v[242:245], v[32:35]
	ds_read_b128 v[206:209], v210 offset:64
	s_waitcnt lgkmcnt(3)
	v_mfma_f32_16x16x32_bf16 v[28:31], v[190:193], v[246:249], v[28:31]
	v_lshl_add_u64 v[140:141], s[26:27], 0, v[168:169]
	s_nop 0
	global_load_dwordx4 v[140:143], v[140:141], off offset:256
	v_mfma_f32_16x16x32_bf16 v[24:27], v[194:197], v[246:249], v[24:27]
	v_mfma_f32_16x16x32_bf16 v[20:23], v[198:201], v[246:249], v[20:23]
	s_waitcnt vmcnt(7)
	ds_write_b128 v254, v[144:147] offset:36864
	v_mfma_f32_16x16x32_bf16 v[16:19], v[202:205], v[246:249], v[16:19]
	ds_read_b128 v[242:245], v210 offset:2368
	s_waitcnt lgkmcnt(4)
	v_mfma_f32_16x16x32_bf16 v[12:15], v[190:193], v[250:253], v[12:15]
	ds_read_b128 v[190:193], v211 offset:36928
	v_mfma_f32_16x16x32_bf16 v[8:11], v[194:197], v[250:253], v[8:11]
	ds_read_b128 v[194:197], v211 offset:39232
	v_mfma_f32_16x16x32_bf16 v[4:7], v[198:201], v[250:253], v[4:7]
	ds_read_b128 v[198:201], v211 offset:41536
	s_add_u32 s26, s2, s99
	s_addc_u32 s27, s3, 0
	v_lshl_add_u64 v[144:145], s[26:27], 0, v[162:163]
	s_nop 0
	global_load_dwordx4 v[144:147], v[144:145], off offset:256
	v_mfma_f32_16x16x32_bf16 v[0:3], v[202:205], v[250:253], v[0:3]
	ds_read_b128 v[202:205], v211 offset:43840
	ds_read_b128 v[246:249], v210 offset:4672
	s_waitcnt lgkmcnt(4)
; DI f32x4 mfma16(bf16x8 a, bf16x8 b, f32x4 c) { return __builtin_amdgcn_mfma_f32_16x16x32_bf16(a, b, c, 0, 0, 0); }
; template <int MI, int NJ, bool SWAP, class AP, class BP>
; DI void gemm_main(f32x4 (&acc)[MI][NJ], const AP& ap, int a_kstep, const BP& bp, int b_kstep, int nk, bf16_t* smem) {
;     ...
;   auto gload = [&](int kt) {
;     const bf16_t* ab = ap.base + (size_t)kt * a_kstep; const bf16_t* bb = bp.base + (size_t)kt * b_kstep;
; #pragma unroll
;     for (int i = 0; i < CA; ++i) ra[i] = *(const u32x4*)(ab + pa[i]);
; #pragma unroll
;     for (int i = 0; i < CB; ++i) rb[i] = *(const u32x4*)(bb + pb[i]);
;   };
;   auto sstore = [&](int buf) {
;     bf16_t* As = smem + buf * L::STAGE; bf16_t* Bs = As + L::A_ELEMS;
; #pragma unroll
;     for (int i = 0; i < CA; ++i) { const int c = tid + NTHR * i; *(u32x4*)(As + (c >> 3) * LDT + (c & 7) * 8) = oka[i] ? ra[i] : (u32x4){0u, 0u, 0u, 0u}; }
; #pragma unroll
;     for (int i = 0; i < CB; ++i) { const int c = tid + NTHR * i; *(u32x4*)(Bs + (c >> 3) * LDT + (c & 7) * 8) = rb[i]; }
;   };
;   gload(0); sstore(0); gload(nk > 1 ? 1 : 0); __syncthreads();
; #pragma unroll 1
;   for (int kt = 0; kt < nk; ++kt) {
;     const int buf = kt & 1;
;     sstore(buf ^ 1);
;     gload(kt + 2 < nk ? kt + 2 : nk - 1);
;     __builtin_amdgcn_sched_barrier(0);
;     const bf16_t* As = smem + buf * L::STAGE + (wm * 16 * MI + l15) * LDT + quad * 8;
;     const bf16_t* Bs = smem + buf * L::STAGE + L::A_ELEMS + (wn * 16 * NJ + l15) * LDT + quad * 8;
; #pragma unroll
;     for (int ks = 0; ks < 2; ++ks) {
;       if (MI * NJ >= 32 && ks == 1) asm volatile("" ::: "memory");
;       bf16x8 b[NJ];
; #pragma unroll
;       for (int j = 0; j < NJ; ++j) b[j] = *(const bf16x8*)(Bs + j * 16 * LDT + ks * 32);
; #pragma unroll
;       for (int i = 0; i < MI; ++i) {
;         const bf16x8 a = *(const bf16x8*)(As + i * 16 * LDT + ks * 32);
; #pragma unroll
;         for (int j = 0; j < NJ; ++j) acc[i][j] = SWAP ? mfma16(b[j], a, acc[i][j]) : mfma16(a, b[j], acc[i][j]);
;       }
;     }
;     __syncthreads();
;   }
	v_mfma_f32_16x16x32_bf16 v[124:127], v[190:193], v[206:209], v[124:127]
	s_waitcnt vmcnt(7)
	ds_write_b128 v238, v[148:151] offset:36864
	s_waitcnt lgkmcnt(4)
	v_mfma_f32_16x16x32_bf16 v[120:123], v[194:197], v[206:209], v[120:123]
	s_waitcnt lgkmcnt(3)
	v_mfma_f32_16x16x32_bf16 v[116:119], v[198:201], v[206:209], v[116:119]
	s_waitcnt lgkmcnt(2)
	v_mfma_f32_16x16x32_bf16 v[112:115], v[202:205], v[206:209], v[112:115]
	ds_read_b128 v[250:253], v210 offset:6976
	v_mfma_f32_16x16x32_bf16 v[108:111], v[190:193], v[242:245], v[108:111]
	v_lshl_add_u64 v[148:149], s[26:27], 0, v[164:165]
	s_nop 0
	global_load_dwordx4 v[148:151], v[148:149], off offset:256
	v_mfma_f32_16x16x32_bf16 v[104:107], v[194:197], v[242:245], v[104:107]
	v_mfma_f32_16x16x32_bf16 v[100:103], v[198:201], v[242:245], v[100:103]
	s_waitcnt vmcnt(7)
	ds_write_b128 v239, v[152:155] offset:36864
	v_mfma_f32_16x16x32_bf16 v[96:99], v[202:205], v[242:245], v[96:99]
	ds_read_b128 v[206:209], v210 offset:9280
	s_waitcnt lgkmcnt(4)
	v_mfma_f32_16x16x32_bf16 v[92:95], v[190:193], v[246:249], v[92:95]
	v_mfma_f32_16x16x32_bf16 v[88:91], v[194:197], v[246:249], v[88:91]
	v_mfma_f32_16x16x32_bf16 v[84:87], v[198:201], v[246:249], v[84:87]
	v_lshl_add_u64 v[152:153], s[26:27], 0, v[166:167]
	s_nop 0
	global_load_dwordx4 v[152:155], v[152:153], off offset:256
	v_mfma_f32_16x16x32_bf16 v[80:83], v[202:205], v[246:249], v[80:83]
	ds_read_b128 v[242:245], v210 offset:11584
	s_waitcnt lgkmcnt(3)
	v_mfma_f32_16x16x32_bf16 v[76:79], v[190:193], v[250:253], v[76:79]
	s_waitcnt vmcnt(7)
	ds_write_b128 v255, v[156:159] offset:36864
	v_mfma_f32_16x16x32_bf16 v[72:75], v[194:197], v[250:253], v[72:75]
	v_mfma_f32_16x16x32_bf16 v[68:71], v[198:201], v[250:253], v[68:71]
	v_mfma_f32_16x16x32_bf16 v[64:67], v[202:205], v[250:253], v[64:67]
	ds_read_b128 v[246:249], v210 offset:13888
	s_waitcnt lgkmcnt(3)
	v_mfma_f32_16x16x32_bf16 v[60:63], v[190:193], v[206:209], v[60:63]
	v_lshl_add_u64 v[156:157], s[26:27], 0, v[168:169]
	s_nop 0
	global_load_dwordx4 v[156:159], v[156:157], off offset:256
	v_mfma_f32_16x16x32_bf16 v[56:59], v[194:197], v[206:209], v[56:59]
	v_mfma_f32_16x16x32_bf16 v[52:55], v[198:201], v[206:209], v[52:55]
	v_mfma_f32_16x16x32_bf16 v[48:51], v[202:205], v[206:209], v[48:51]
	ds_read_b128 v[250:253], v210 offset:16192
	s_waitcnt lgkmcnt(3)
	v_mfma_f32_16x16x32_bf16 v[44:47], v[190:193], v[242:245], v[44:47]
	v_mfma_f32_16x16x32_bf16 v[40:43], v[194:197], v[242:245], v[40:43]
	v_mfma_f32_16x16x32_bf16 v[36:39], v[198:201], v[242:245], v[36:39]
	v_mfma_f32_16x16x32_bf16 v[32:35], v[202:205], v[242:245], v[32:35]
	s_add_i32 s4, s4, 1
	s_and_b32 s98, s4, 1
	s_mul_i32 s98, s98, 0x12000
	v_add3_u32 v210, s98, v184, v186
	v_add3_u32 v211, s98, v160, v186
	s_cmp_lg_u32 s4, 16
	s_waitcnt lgkmcnt(0)
	s_barrier
	s_cbranch_scc0 .Lgm8_exit
	ds_read_b128 v[206:209], v210
	ds_read_b128 v[242:245], v210 offset:2304
	v_mfma_f32_16x16x32_bf16 v[28:31], v[190:193], v[246:249], v[28:31]
	v_mfma_f32_16x16x32_bf16 v[12:15], v[190:193], v[250:253], v[12:15]
	ds_read_b128 v[190:193], v211 offset:36864
	v_mfma_f32_16x16x32_bf16 v[24:27], v[194:197], v[246:249], v[24:27]
	v_mfma_f32_16x16x32_bf16 v[8:11], v[194:197], v[250:253], v[8:11]
	ds_read_b128 v[194:197], v211 offset:39168
	v_mfma_f32_16x16x32_bf16 v[20:23], v[198:201], v[246:249], v[20:23]
	v_mfma_f32_16x16x32_bf16 v[4:7], v[198:201], v[250:253], v[4:7]
	ds_read_b128 v[198:201], v211 offset:41472
	v_mfma_f32_16x16x32_bf16 v[16:19], v[202:205], v[246:249], v[16:19]
	v_mfma_f32_16x16x32_bf16 v[0:3], v[202:205], v[250:253], v[0:3]
	ds_read_b128 v[202:205], v211 offset:43776
	s_branch .Lgm8_main

; DI f32x4 mfma16(bf16x8 a, bf16x8 b, f32x4 c) { return __builtin_amdgcn_mfma_f32_16x16x32_bf16(a, b, c, 0, 0, 0); }
; template <int MI, int NJ, bool SWAP, class AP, class BP>
; DI void gemm_main(f32x4 (&acc)[MI][NJ], const AP& ap, int a_kstep, const BP& bp, int b_kstep, int nk, bf16_t* smem) {
;     ...
;   auto gload = [&](int kt) {
;     const bf16_t* ab = ap.base + (size_t)kt * a_kstep; const bf16_t* bb = bp.base + (size_t)kt * b_kstep;
; #pragma unroll
;     for (int i = 0; i < CA; ++i) ra[i] = *(const u32x4*)(ab + pa[i]);
; #pragma unroll
;     for (int i = 0; i < CB; ++i) rb[i] = *(const u32x4*)(bb + pb[i]);
;   };
;   auto sstore = [&](int buf) {
;     bf16_t* As = smem + buf * L::STAGE; bf16_t* Bs = As + L::A_ELEMS;
; #pragma unroll
;     for (int i = 0; i < CA; ++i) { const int c = tid + NTHR * i; *(u32x4*)(As + (c >> 3) * LDT + (c & 7) * 8) = oka[i] ? ra[i] : (u32x4){0u, 0u, 0u, 0u}; }
; #pragma unroll
;     for (int i = 0; i < CB; ++i) { const int c = tid + NTHR * i; *(u32x4*)(Bs + (c >> 3) * LDT + (c & 7) * 8) = rb[i]; }
;   };
;   gload(0); sstore(0); gload(nk > 1 ? 1 : 0); __syncthreads();
; #pragma unroll 1
;   for (int kt = 0; kt < nk; ++kt) {
;     const int buf = kt & 1;
;     sstore(buf ^ 1);
;     gload(kt + 2 < nk ? kt + 2 : nk - 1);
;     __builtin_amdgcn_sched_barrier(0);
;     const bf16_t* As = smem + buf * L::STAGE + (wm * 16 * MI + l15) * LDT + quad * 8;
;     const bf16_t* Bs = smem + buf * L::STAGE + L::A_ELEMS + (wn * 16 * NJ + l15) * LDT + quad * 8;
; #pragma unroll
;     for (int ks = 0; ks < 2; ++ks) {
;       if (MI * NJ >= 32 && ks == 1) asm volatile("" ::: "memory");
;       bf16x8 b[NJ];
; #pragma unroll
;       for (int j = 0; j < NJ; ++j) b[j] = *(const bf16x8*)(Bs + j * 16 * LDT + ks * 32);
; #pragma unroll
;       for (int i = 0; i < MI; ++i) {
;         const bf16x8 a = *(const bf16x8*)(As + i * 16 * LDT + ks * 32);
; #pragma unroll
;         for (int j = 0; j < NJ; ++j) acc[i][j] = SWAP ? mfma16(b[j], a, acc[i][j]) : mfma16(a, b[j], acc[i][j]);
;       }
;     }
;     __syncthreads();
;   }
.Lgm10_main:
	ds_read_b128 v[246:249], v198 offset:4608
	s_waitcnt lgkmcnt(4)
	v_mfma_f32_16x16x32_bf16 v[156:159], v[178:181], v[194:197], v[156:159]
	s_waitcnt lgkmcnt(3)
	v_mfma_f32_16x16x32_bf16 v[152:155], v[182:185], v[194:197], v[152:155]
	s_waitcnt lgkmcnt(2)
	v_mfma_f32_16x16x32_bf16 v[148:151], v[186:189], v[194:197], v[148:151]
	s_and_b32 s33, s8, 1
	s_xor_b32 s37, s33, 1
	s_mul_i32 s37, s37, 0x12000
	v_add3_u32 v254, s37, v173, v171
	s_waitcnt vmcnt(7)
	ds_write_b128 v254, v[112:115]
	s_waitcnt lgkmcnt(2)
	v_mfma_f32_16x16x32_bf16 v[144:147], v[190:193], v[194:197], v[144:147]
	ds_read_b128 v[250:253], v198 offset:6912
	v_mfma_f32_16x16x32_bf16 v[108:111], v[178:181], v[242:245], v[108:111]
	v_mfma_f32_16x16x32_bf16 v[104:107], v[182:185], v[242:245], v[104:107]
	v_mfma_f32_16x16x32_bf16 v[100:103], v[186:189], v[242:245], v[100:103]
	s_min_u32 s99, s8, 3
	s_lshl_b32 s99, s99, 7
	s_add_u32 s38, s0, s99
	s_addc_u32 s39, s1, 0
	v_lshl_add_u64 v[112:113], s[38:39], 0, v[162:163]
	s_nop 0
	global_load_dwordx4 v[112:115], v[112:113], off offset:256
	v_mfma_f32_16x16x32_bf16 v[96:99], v[190:193], v[242:245], v[96:99]
	ds_read_b128 v[194:197], v198 offset:9216
	s_waitcnt lgkmcnt(3)
	v_mfma_f32_16x16x32_bf16 v[92:95], v[178:181], v[246:249], v[92:95]
	v_add3_u32 v238, s37, v174, v171
	s_waitcnt vmcnt(6)
	ds_write_b128 v238, v[116:119]
	v_mfma_f32_16x16x32_bf16 v[88:91], v[182:185], v[246:249], v[88:91]
	v_mfma_f32_16x16x32_bf16 v[84:87], v[186:189], v[246:249], v[84:87]
	v_mfma_f32_16x16x32_bf16 v[80:83], v[190:193], v[246:249], v[80:83]
	ds_read_b128 v[242:245], v198 offset:11520
	s_waitcnt lgkmcnt(3)
	v_mfma_f32_16x16x32_bf16 v[76:79], v[178:181], v[250:253], v[76:79]
	v_lshl_add_u64 v[116:117], s[38:39], 0, v[164:165]
	s_nop 0
	global_load_dwordx4 v[116:119], v[116:117], off offset:256
	v_mfma_f32_16x16x32_bf16 v[72:75], v[182:185], v[250:253], v[72:75]
	v_mfma_f32_16x16x32_bf16 v[68:71], v[186:189], v[250:253], v[68:71]
	v_add3_u32 v239, s37, v175, v171
	s_waitcnt vmcnt(6)
	ds_write_b128 v239, v[120:123]
	v_mfma_f32_16x16x32_bf16 v[64:67], v[190:193], v[250:253], v[64:67]
	ds_read_b128 v[246:249], v198 offset:13824
	s_waitcnt lgkmcnt(4)
	v_mfma_f32_16x16x32_bf16 v[60:63], v[178:181], v[194:197], v[60:63]
	v_mfma_f32_16x16x32_bf16 v[56:59], v[182:185], v[194:197], v[56:59]
	v_mfma_f32_16x16x32_bf16 v[52:55], v[186:189], v[194:197], v[52:55]
	v_lshl_add_u64 v[120:121], s[38:39], 0, v[166:167]
	s_nop 0
	global_load_dwordx4 v[120:123], v[120:121], off offset:256
	v_mfma_f32_16x16x32_bf16 v[48:51], v[190:193], v[194:197], v[48:51]
	ds_read_b128 v[250:253], v198 offset:16128
	s_waitcnt lgkmcnt(3)
	v_mfma_f32_16x16x32_bf16 v[44:47], v[178:181], v[242:245], v[44:47]
	v_add3_u32 v255, s37, v176, v171
	s_waitcnt vmcnt(6)
	ds_write_b128 v255, v[124:127]
	v_mfma_f32_16x16x32_bf16 v[40:43], v[182:185], v[242:245], v[40:43]
	v_mfma_f32_16x16x32_bf16 v[36:39], v[186:189], v[242:245], v[36:39]
	v_mfma_f32_16x16x32_bf16 v[32:35], v[190:193], v[242:245], v[32:35]
	ds_read_b128 v[194:197], v198 offset:64
	s_waitcnt lgkmcnt(3)
	v_mfma_f32_16x16x32_bf16 v[28:31], v[178:181], v[246:249], v[28:31]
	v_lshl_add_u64 v[124:125], s[38:39], 0, v[168:169]
	s_nop 0
	global_load_dwordx4 v[124:127], v[124:125], off offset:256
	v_mfma_f32_16x16x32_bf16 v[24:27], v[182:185], v[246:249], v[24:27]
	v_mfma_f32_16x16x32_bf16 v[20:23], v[186:189], v[246:249], v[20:23]
	ds_write_b128 v254, v[128:131] offset:36864
	v_mfma_f32_16x16x32_bf16 v[16:19], v[190:193], v[246:249], v[16:19]
	ds_read_b128 v[242:245], v198 offset:2368
	s_waitcnt lgkmcnt(4)
	v_mfma_f32_16x16x32_bf16 v[12:15], v[178:181], v[250:253], v[12:15]
	ds_read_b128 v[178:181], v199 offset:36928
	v_mfma_f32_16x16x32_bf16 v[8:11], v[182:185], v[250:253], v[8:11]
	ds_read_b128 v[182:185], v199 offset:39232
	v_mfma_f32_16x16x32_bf16 v[4:7], v[186:189], v[250:253], v[4:7]
	ds_read_b128 v[186:189], v199 offset:41536
	s_add_u32 s38, s2, s99
	s_addc_u32 s39, s3, 0
	v_lshl_add_u64 v[128:129], s[38:39], 0, v[162:163]
	s_nop 0
	global_load_dwordx4 v[128:131], v[128:129], off offset:256
	v_mfma_f32_16x16x32_bf16 v[0:3], v[190:193], v[250:253], v[0:3]
	ds_read_b128 v[190:193], v199 offset:43840
	ds_read_b128 v[246:249], v198 offset:4672
	s_waitcnt lgkmcnt(4)
; DI f32x4 mfma16(bf16x8 a, bf16x8 b, f32x4 c) { return __builtin_amdgcn_mfma_f32_16x16x32_bf16(a, b, c, 0, 0, 0); }
; template <int MI, int NJ, bool SWAP, class AP, class BP>
; DI void gemm_main(f32x4 (&acc)[MI][NJ], const AP& ap, int a_kstep, const BP& bp, int b_kstep, int nk, bf16_t* smem) {
;     ...
;   auto gload = [&](int kt) {
;     const bf16_t* ab = ap.base + (size_t)kt * a_kstep; const bf16_t* bb = bp.base + (size_t)kt * b_kstep;
; #pragma unroll
;     for (int i = 0; i < CA; ++i) ra[i] = *(const u32x4*)(ab + pa[i]);
; #pragma unroll
;     for (int i = 0; i < CB; ++i) rb[i] = *(const u32x4*)(bb + pb[i]);
;   };
;   auto sstore = [&](int buf) {
;     bf16_t* As = smem + buf * L::STAGE; bf16_t* Bs = As + L::A_ELEMS;
; #pragma unroll
;     for (int i = 0; i < CA; ++i) { const int c = tid + NTHR * i; *(u32x4*)(As + (c >> 3) * LDT + (c & 7) * 8) = oka[i] ? ra[i] : (u32x4){0u, 0u, 0u, 0u}; }
; #pragma unroll
;     for (int i = 0; i < CB; ++i) { const int c = tid + NTHR * i; *(u32x4*)(Bs + (c >> 3) * LDT + (c & 7) * 8) = rb[i]; }
;   };
;   gload(0); sstore(0); gload(nk > 1 ? 1 : 0); __syncthreads();
; #pragma unroll 1
;   for (int kt = 0; kt < nk; ++kt) {
;     const int buf = kt & 1;
;     sstore(buf ^ 1);
;     gload(kt + 2 < nk ? kt + 2 : nk - 1);
;     __builtin_amdgcn_sched_barrier(0);
;     const bf16_t* As = smem + buf * L::STAGE + (wm * 16 * MI + l15) * LDT + quad * 8;
;     const bf16_t* Bs = smem + buf * L::STAGE + L::A_ELEMS + (wn * 16 * NJ + l15) * LDT + quad * 8;
; #pragma unroll
;     for (int ks = 0; ks < 2; ++ks) {
;       if (MI * NJ >= 32 && ks == 1) asm volatile("" ::: "memory");
;       bf16x8 b[NJ];
; #pragma unroll
;       for (int j = 0; j < NJ; ++j) b[j] = *(const bf16x8*)(Bs + j * 16 * LDT + ks * 32);
; #pragma unroll
;       for (int i = 0; i < MI; ++i) {
;         const bf16x8 a = *(const bf16x8*)(As + i * 16 * LDT + ks * 32);
; #pragma unroll
;         for (int j = 0; j < NJ; ++j) acc[i][j] = SWAP ? mfma16(b[j], a, acc[i][j]) : mfma16(a, b[j], acc[i][j]);
;       }
;     }
;     __syncthreads();
;   }
	v_mfma_f32_16x16x32_bf16 v[156:159], v[178:181], v[194:197], v[156:159]
	s_waitcnt vmcnt(7)
	ds_write_b128 v238, v[132:135] offset:36864
	s_waitcnt lgkmcnt(4)
	v_mfma_f32_16x16x32_bf16 v[152:155], v[182:185], v[194:197], v[152:155]
	s_waitcnt lgkmcnt(3)
	v_mfma_f32_16x16x32_bf16 v[148:151], v[186:189], v[194:197], v[148:151]
	s_waitcnt lgkmcnt(2)
	v_mfma_f32_16x16x32_bf16 v[144:147], v[190:193], v[194:197], v[144:147]
	ds_read_b128 v[250:253], v198 offset:6976
	v_mfma_f32_16x16x32_bf16 v[108:111], v[178:181], v[242:245], v[108:111]
	v_lshl_add_u64 v[132:133], s[38:39], 0, v[164:165]
	s_nop 0
	global_load_dwordx4 v[132:135], v[132:133], off offset:256
	v_mfma_f32_16x16x32_bf16 v[104:107], v[182:185], v[242:245], v[104:107]
	v_mfma_f32_16x16x32_bf16 v[100:103], v[186:189], v[242:245], v[100:103]
	s_waitcnt vmcnt(7)
	ds_write_b128 v239, v[136:139] offset:36864
	v_mfma_f32_16x16x32_bf16 v[96:99], v[190:193], v[242:245], v[96:99]
	ds_read_b128 v[194:197], v198 offset:9280
	s_waitcnt lgkmcnt(4)
	v_mfma_f32_16x16x32_bf16 v[92:95], v[178:181], v[246:249], v[92:95]
	v_mfma_f32_16x16x32_bf16 v[88:91], v[182:185], v[246:249], v[88:91]
	v_mfma_f32_16x16x32_bf16 v[84:87], v[186:189], v[246:249], v[84:87]
	v_lshl_add_u64 v[136:137], s[38:39], 0, v[166:167]
	s_nop 0
	global_load_dwordx4 v[136:139], v[136:137], off offset:256
	v_mfma_f32_16x16x32_bf16 v[80:83], v[190:193], v[246:249], v[80:83]
	ds_read_b128 v[242:245], v198 offset:11584
	s_waitcnt lgkmcnt(3)
	v_mfma_f32_16x16x32_bf16 v[76:79], v[178:181], v[250:253], v[76:79]
	s_waitcnt vmcnt(7)
	ds_write_b128 v255, v[140:143] offset:36864
	v_mfma_f32_16x16x32_bf16 v[72:75], v[182:185], v[250:253], v[72:75]
	v_mfma_f32_16x16x32_bf16 v[68:71], v[186:189], v[250:253], v[68:71]
	v_mfma_f32_16x16x32_bf16 v[64:67], v[190:193], v[250:253], v[64:67]
	ds_read_b128 v[246:249], v198 offset:13888
	s_waitcnt lgkmcnt(3)
	v_mfma_f32_16x16x32_bf16 v[60:63], v[178:181], v[194:197], v[60:63]
	v_lshl_add_u64 v[140:141], s[38:39], 0, v[168:169]
	s_nop 0
	global_load_dwordx4 v[140:143], v[140:141], off offset:256
	v_mfma_f32_16x16x32_bf16 v[56:59], v[182:185], v[194:197], v[56:59]
	v_mfma_f32_16x16x32_bf16 v[52:55], v[186:189], v[194:197], v[52:55]
	v_mfma_f32_16x16x32_bf16 v[48:51], v[190:193], v[194:197], v[48:51]
	ds_read_b128 v[250:253], v198 offset:16192
	s_waitcnt lgkmcnt(3)
	v_mfma_f32_16x16x32_bf16 v[44:47], v[178:181], v[242:245], v[44:47]
	v_mfma_f32_16x16x32_bf16 v[40:43], v[182:185], v[242:245], v[40:43]
	v_mfma_f32_16x16x32_bf16 v[36:39], v[186:189], v[242:245], v[36:39]
	v_mfma_f32_16x16x32_bf16 v[32:35], v[190:193], v[242:245], v[32:35]
	s_add_i32 s8, s8, 1
	s_and_b32 s98, s8, 1
	s_mul_i32 s98, s98, 0x12000
	v_add3_u32 v198, s98, v172, v177
	v_add3_u32 v199, s98, v160, v177
	s_cmp_lg_u32 s8, 6
	s_waitcnt lgkmcnt(0)
	s_barrier
	s_cbranch_scc0 .Lgm10_exit
	ds_read_b128 v[194:197], v198
	ds_read_b128 v[242:245], v198 offset:2304
	v_mfma_f32_16x16x32_bf16 v[28:31], v[178:181], v[246:249], v[28:31]
	v_mfma_f32_16x16x32_bf16 v[12:15], v[178:181], v[250:253], v[12:15]
	ds_read_b128 v[178:181], v199 offset:36864
	v_mfma_f32_16x16x32_bf16 v[24:27], v[182:185], v[246:249], v[24:27]
	v_mfma_f32_16x16x32_bf16 v[8:11], v[182:185], v[250:253], v[8:11]
	ds_read_b128 v[182:185], v199 offset:39168
	v_mfma_f32_16x16x32_bf16 v[20:23], v[186:189], v[246:249], v[20:23]
	v_mfma_f32_16x16x32_bf16 v[4:7], v[186:189], v[250:253], v[4:7]
	ds_read_b128 v[186:189], v199 offset:41472
	v_mfma_f32_16x16x32_bf16 v[16:19], v[190:193], v[246:249], v[16:19]
	v_mfma_f32_16x16x32_bf16 v[0:3], v[190:193], v[250:253], v[0:3]
	ds_read_b128 v[190:193], v199 offset:43776
	s_branch .Lgm10_main

; DI f32x4 mfma16(bf16x8 a, bf16x8 b, f32x4 c) { return __builtin_amdgcn_mfma_f32_16x16x32_bf16(a, b, c, 0, 0, 0); }
; template <int MI, int NJ, bool SWAP, class AP, class BP>
; DI void gemm_main(f32x4 (&acc)[MI][NJ], const AP& ap, int a_kstep, const BP& bp, int b_kstep, int nk, bf16_t* smem) {
;     ...
;   auto gload = [&](int kt) {
;     const bf16_t* ab = ap.base + (size_t)kt * a_kstep; const bf16_t* bb = bp.base + (size_t)kt * b_kstep;
; #pragma unroll
;     for (int i = 0; i < CA; ++i) ra[i] = *(const u32x4*)(ab + pa[i]);
; #pragma unroll
;     for (int i = 0; i < CB; ++i) rb[i] = *(const u32x4*)(bb + pb[i]);
;   };
;   auto sstore = [&](int buf) {
;     bf16_t* As = smem + buf * L::STAGE; bf16_t* Bs = As + L::A_ELEMS;
; #pragma unroll
;     for (int i = 0; i < CA; ++i) { const int c = tid + NTHR * i; *(u32x4*)(As + (c >> 3) * LDT + (c & 7) * 8) = oka[i] ? ra[i] : (u32x4){0u, 0u, 0u, 0u}; }
; #pragma unroll
;     for (int i = 0; i < CB; ++i) { const int c = tid + NTHR * i; *(u32x4*)(Bs + (c >> 3) * LDT + (c & 7) * 8) = rb[i]; }
;   };
;   gload(0); sstore(0); gload(nk > 1 ? 1 : 0); __syncthreads();
; #pragma unroll 1
;   for (int kt = 0; kt < nk; ++kt) {
;     const int buf = kt & 1;
;     sstore(buf ^ 1);
;     gload(kt + 2 < nk ? kt + 2 : nk - 1);
;     __builtin_amdgcn_sched_barrier(0);
;     const bf16_t* As = smem + buf * L::STAGE + (wm * 16 * MI + l15) * LDT + quad * 8;
;     const bf16_t* Bs = smem + buf * L::STAGE + L::A_ELEMS + (wn * 16 * NJ + l15) * LDT + quad * 8;
; #pragma unroll
;     for (int ks = 0; ks < 2; ++ks) {
;       if (MI * NJ >= 32 && ks == 1) asm volatile("" ::: "memory");
;       bf16x8 b[NJ];
; #pragma unroll
;       for (int j = 0; j < NJ; ++j) b[j] = *(const bf16x8*)(Bs + j * 16 * LDT + ks * 32);
; #pragma unroll
;       for (int i = 0; i < MI; ++i) {
;         const bf16x8 a = *(const bf16x8*)(As + i * 16 * LDT + ks * 32);
; #pragma unroll
;         for (int j = 0; j < NJ; ++j) acc[i][j] = SWAP ? mfma16(b[j], a, acc[i][j]) : mfma16(a, b[j], acc[i][j]);
;       }
;     }
;     __syncthreads();
;   }
.Lgm13_main:
	ds_read_b128 v[242:245], v177 offset:4608
	s_waitcnt lgkmcnt(4)
	v_mfma_f32_16x16x32_bf16 v[156:159], v[178:181], v[194:197], v[156:159]
	s_waitcnt lgkmcnt(3)
	v_mfma_f32_16x16x32_bf16 v[152:155], v[182:185], v[194:197], v[152:155]
	s_waitcnt lgkmcnt(2)
	v_mfma_f32_16x16x32_bf16 v[148:151], v[186:189], v[194:197], v[148:151]
	s_and_b32 s15, s1, 1
	s_min_u32 s16, s1, 13
	s_xor_b32 s17, s15, 1
	s_mul_i32 s17, s17, 0x12000
	v_add3_u32 v250, s17, v172, v170
	s_waitcnt vmcnt(7)
	ds_write_b128 v250, v[112:115]
	s_waitcnt lgkmcnt(2)
	v_mfma_f32_16x16x32_bf16 v[144:147], v[190:193], v[194:197], v[144:147]
	ds_read_b128 v[246:249], v177 offset:6912
	v_mfma_f32_16x16x32_bf16 v[108:111], v[178:181], v[198:201], v[108:111]
	v_mfma_f32_16x16x32_bf16 v[104:107], v[182:185], v[198:201], v[104:107]
	v_mfma_f32_16x16x32_bf16 v[100:103], v[186:189], v[198:201], v[100:103]
	s_lshl_b32 s26, s16, 7
	s_add_u32 s16, s2, s26
	v_add3_u32 v251, s17, v174, v170
	v_add3_u32 v252, s17, v175, v170
	v_add3_u32 v253, s17, v176, v170
	s_addc_u32 s17, s3, 0
	v_lshl_add_u64 v[112:113], s[16:17], 0, v[162:163]
	s_nop 0
	global_load_dwordx4 v[112:115], v[112:113], off offset:256
	v_mfma_f32_16x16x32_bf16 v[96:99], v[190:193], v[198:201], v[96:99]
	ds_read_b128 v[194:197], v177 offset:9216
	s_waitcnt lgkmcnt(3)
	v_mfma_f32_16x16x32_bf16 v[92:95], v[178:181], v[242:245], v[92:95]
	s_waitcnt vmcnt(7)
	ds_write_b128 v251, v[116:119]
	v_mfma_f32_16x16x32_bf16 v[88:91], v[182:185], v[242:245], v[88:91]
	v_mfma_f32_16x16x32_bf16 v[84:87], v[186:189], v[242:245], v[84:87]
	v_mfma_f32_16x16x32_bf16 v[80:83], v[190:193], v[242:245], v[80:83]
	ds_read_b128 v[198:201], v177 offset:11520
	s_waitcnt lgkmcnt(3)
	v_mfma_f32_16x16x32_bf16 v[76:79], v[178:181], v[246:249], v[76:79]
	v_lshl_add_u64 v[116:117], s[16:17], 0, v[164:165]
	s_nop 0
	global_load_dwordx4 v[116:119], v[116:117], off offset:256
	v_mfma_f32_16x16x32_bf16 v[72:75], v[182:185], v[246:249], v[72:75]
	v_mfma_f32_16x16x32_bf16 v[68:71], v[186:189], v[246:249], v[68:71]
	s_waitcnt vmcnt(7)
	ds_write_b128 v252, v[120:123]
	v_mfma_f32_16x16x32_bf16 v[64:67], v[190:193], v[246:249], v[64:67]
	ds_read_b128 v[242:245], v177 offset:13824
	s_waitcnt lgkmcnt(4)
	v_mfma_f32_16x16x32_bf16 v[60:63], v[178:181], v[194:197], v[60:63]
	v_mfma_f32_16x16x32_bf16 v[56:59], v[182:185], v[194:197], v[56:59]
	v_mfma_f32_16x16x32_bf16 v[52:55], v[186:189], v[194:197], v[52:55]
	v_lshl_add_u64 v[120:121], s[16:17], 0, v[166:167]
	s_nop 0
	global_load_dwordx4 v[120:123], v[120:121], off offset:256
	v_mfma_f32_16x16x32_bf16 v[48:51], v[190:193], v[194:197], v[48:51]
	ds_read_b128 v[246:249], v177 offset:16128
	s_waitcnt lgkmcnt(3)
	v_mfma_f32_16x16x32_bf16 v[44:47], v[178:181], v[198:201], v[44:47]
	s_waitcnt vmcnt(7)
	ds_write_b128 v253, v[124:127]
	v_mfma_f32_16x16x32_bf16 v[40:43], v[182:185], v[198:201], v[40:43]
	v_mfma_f32_16x16x32_bf16 v[36:39], v[186:189], v[198:201], v[36:39]
	v_mfma_f32_16x16x32_bf16 v[32:35], v[190:193], v[198:201], v[32:35]
	ds_read_b128 v[194:197], v177 offset:64
	s_waitcnt lgkmcnt(3)
	v_mfma_f32_16x16x32_bf16 v[28:31], v[178:181], v[242:245], v[28:31]
	v_lshl_add_u64 v[124:125], s[16:17], 0, v[168:169]
	s_nop 0
	global_load_dwordx4 v[124:127], v[124:125], off offset:256
	v_mfma_f32_16x16x32_bf16 v[24:27], v[182:185], v[242:245], v[24:27]
	v_mfma_f32_16x16x32_bf16 v[20:23], v[186:189], v[242:245], v[20:23]
	s_waitcnt vmcnt(7)
	ds_write_b128 v250, v[128:131] offset:36864
	v_mfma_f32_16x16x32_bf16 v[16:19], v[190:193], v[242:245], v[16:19]
	ds_read_b128 v[198:201], v177 offset:2368
	s_waitcnt lgkmcnt(4)
	v_mfma_f32_16x16x32_bf16 v[8:11], v[178:181], v[246:249], v[8:11]
	ds_read_b128 v[178:181], v202 offset:36928
	v_mfma_f32_16x16x32_bf16 v[4:7], v[182:185], v[246:249], v[4:7]
	ds_read_b128 v[182:185], v202 offset:39232
	v_mfma_f32_16x16x32_bf16 v[0:3], v[186:189], v[246:249], v[0:3]
	ds_read_b128 v[186:189], v202 offset:41536
	s_add_u32 s16, s12, s26
	s_addc_u32 s17, s13, 0
	v_lshl_add_u64 v[128:129], s[16:17], 0, v[162:163]
	s_nop 0
	global_load_dwordx4 v[128:131], v[128:129], off offset:256
	v_mfma_f32_16x16x32_bf16 v[12:15], v[190:193], v[246:249], v[12:15]
	ds_read_b128 v[190:193], v202 offset:43840
	ds_read_b128 v[242:245], v177 offset:4672
	s_waitcnt lgkmcnt(4)
; DI f32x4 mfma16(bf16x8 a, bf16x8 b, f32x4 c) { return __builtin_amdgcn_mfma_f32_16x16x32_bf16(a, b, c, 0, 0, 0); }
; template <int MI, int NJ, bool SWAP, class AP, class BP>
; DI void gemm_main(f32x4 (&acc)[MI][NJ], const AP& ap, int a_kstep, const BP& bp, int b_kstep, int nk, bf16_t* smem) {
;     ...
;   auto gload = [&](int kt) {
;     const bf16_t* ab = ap.base + (size_t)kt * a_kstep; const bf16_t* bb = bp.base + (size_t)kt * b_kstep;
; #pragma unroll
;     for (int i = 0; i < CA; ++i) ra[i] = *(const u32x4*)(ab + pa[i]);
; #pragma unroll
;     for (int i = 0; i < CB; ++i) rb[i] = *(const u32x4*)(bb + pb[i]);
;   };
;   auto sstore = [&](int buf) {
;     bf16_t* As = smem + buf * L::STAGE; bf16_t* Bs = As + L::A_ELEMS;
; #pragma unroll
;     for (int i = 0; i < CA; ++i) { const int c = tid + NTHR * i; *(u32x4*)(As + (c >> 3) * LDT + (c & 7) * 8) = oka[i] ? ra[i] : (u32x4){0u, 0u, 0u, 0u}; }
; #pragma unroll
;     for (int i = 0; i < CB; ++i) { const int c = tid + NTHR * i; *(u32x4*)(Bs + (c >> 3) * LDT + (c & 7) * 8) = rb[i]; }
;   };
;   gload(0); sstore(0); gload(nk > 1 ? 1 : 0); __syncthreads();
; #pragma unroll 1
;   for (int kt = 0; kt < nk; ++kt) {
;     const int buf = kt & 1;
;     sstore(buf ^ 1);
;     gload(kt + 2 < nk ? kt + 2 : nk - 1);
;     __builtin_amdgcn_sched_barrier(0);
;     const bf16_t* As = smem + buf * L::STAGE + (wm * 16 * MI + l15) * LDT + quad * 8;
;     const bf16_t* Bs = smem + buf * L::STAGE + L::A_ELEMS + (wn * 16 * NJ + l15) * LDT + quad * 8;
; #pragma unroll
;     for (int ks = 0; ks < 2; ++ks) {
;       if (MI * NJ >= 32 && ks == 1) asm volatile("" ::: "memory");
;       bf16x8 b[NJ];
; #pragma unroll
;       for (int j = 0; j < NJ; ++j) b[j] = *(const bf16x8*)(Bs + j * 16 * LDT + ks * 32);
; #pragma unroll
;       for (int i = 0; i < MI; ++i) {
;         const bf16x8 a = *(const bf16x8*)(As + i * 16 * LDT + ks * 32);
; #pragma unroll
;         for (int j = 0; j < NJ; ++j) acc[i][j] = SWAP ? mfma16(b[j], a, acc[i][j]) : mfma16(a, b[j], acc[i][j]);
;       }
;     }
;     __syncthreads();
;   }
	v_mfma_f32_16x16x32_bf16 v[156:159], v[178:181], v[194:197], v[156:159]
	s_waitcnt vmcnt(7)
	ds_write_b128 v251, v[132:135] offset:36864
	s_waitcnt lgkmcnt(4)
	v_mfma_f32_16x16x32_bf16 v[152:155], v[182:185], v[194:197], v[152:155]
	s_waitcnt lgkmcnt(3)
	v_mfma_f32_16x16x32_bf16 v[148:151], v[186:189], v[194:197], v[148:151]
	s_waitcnt lgkmcnt(2)
	v_mfma_f32_16x16x32_bf16 v[144:147], v[190:193], v[194:197], v[144:147]
	ds_read_b128 v[246:249], v177 offset:6976
	v_mfma_f32_16x16x32_bf16 v[108:111], v[178:181], v[198:201], v[108:111]
	v_lshl_add_u64 v[132:133], s[16:17], 0, v[164:165]
	s_nop 0
	global_load_dwordx4 v[132:135], v[132:133], off offset:256
	v_mfma_f32_16x16x32_bf16 v[104:107], v[182:185], v[198:201], v[104:107]
	v_mfma_f32_16x16x32_bf16 v[100:103], v[186:189], v[198:201], v[100:103]
	s_waitcnt vmcnt(7)
	ds_write_b128 v252, v[136:139] offset:36864
	v_mfma_f32_16x16x32_bf16 v[96:99], v[190:193], v[198:201], v[96:99]
	ds_read_b128 v[194:197], v177 offset:9280
	s_waitcnt lgkmcnt(4)
	v_mfma_f32_16x16x32_bf16 v[92:95], v[178:181], v[242:245], v[92:95]
	v_mfma_f32_16x16x32_bf16 v[88:91], v[182:185], v[242:245], v[88:91]
	v_mfma_f32_16x16x32_bf16 v[84:87], v[186:189], v[242:245], v[84:87]
	v_lshl_add_u64 v[136:137], s[16:17], 0, v[166:167]
	s_nop 0
	global_load_dwordx4 v[136:139], v[136:137], off offset:256
	v_mfma_f32_16x16x32_bf16 v[80:83], v[190:193], v[242:245], v[80:83]
	ds_read_b128 v[198:201], v177 offset:11584
	s_waitcnt lgkmcnt(3)
	v_mfma_f32_16x16x32_bf16 v[76:79], v[178:181], v[246:249], v[76:79]
	s_waitcnt vmcnt(7)
	ds_write_b128 v253, v[140:143] offset:36864
	v_mfma_f32_16x16x32_bf16 v[72:75], v[182:185], v[246:249], v[72:75]
	v_mfma_f32_16x16x32_bf16 v[68:71], v[186:189], v[246:249], v[68:71]
	v_mfma_f32_16x16x32_bf16 v[64:67], v[190:193], v[246:249], v[64:67]
	ds_read_b128 v[242:245], v177 offset:13888
	s_waitcnt lgkmcnt(3)
	v_mfma_f32_16x16x32_bf16 v[60:63], v[178:181], v[194:197], v[60:63]
	v_lshl_add_u64 v[140:141], s[16:17], 0, v[168:169]
	s_nop 0
	global_load_dwordx4 v[140:143], v[140:141], off offset:256
	v_mfma_f32_16x16x32_bf16 v[56:59], v[182:185], v[194:197], v[56:59]
	v_mfma_f32_16x16x32_bf16 v[52:55], v[186:189], v[194:197], v[52:55]
	v_mfma_f32_16x16x32_bf16 v[48:51], v[190:193], v[194:197], v[48:51]
	ds_read_b128 v[246:249], v177 offset:16192
	s_waitcnt lgkmcnt(3)
	v_mfma_f32_16x16x32_bf16 v[44:47], v[178:181], v[198:201], v[44:47]
	v_mfma_f32_16x16x32_bf16 v[40:43], v[182:185], v[198:201], v[40:43]
	v_mfma_f32_16x16x32_bf16 v[36:39], v[186:189], v[198:201], v[36:39]
	v_mfma_f32_16x16x32_bf16 v[32:35], v[190:193], v[198:201], v[32:35]
	s_add_i32 s1, s1, 1
	s_and_b32 s98, s1, 1
	s_mul_i32 s98, s98, 0x12000
	v_add3_u32 v202, s98, v160, v173
	v_add3_u32 v177, s98, v171, v173
	s_cmp_lg_u32 s1, 16
	s_waitcnt lgkmcnt(0)
	s_barrier
	s_cbranch_scc0 .Lgm13_exit
	ds_read_b128 v[194:197], v177
	ds_read_b128 v[198:201], v177 offset:2304
	v_mfma_f32_16x16x32_bf16 v[28:31], v[178:181], v[242:245], v[28:31]
	v_mfma_f32_16x16x32_bf16 v[8:11], v[178:181], v[246:249], v[8:11]
	ds_read_b128 v[178:181], v202 offset:36864
	v_mfma_f32_16x16x32_bf16 v[24:27], v[182:185], v[242:245], v[24:27]
	v_mfma_f32_16x16x32_bf16 v[4:7], v[182:185], v[246:249], v[4:7]
	ds_read_b128 v[182:185], v202 offset:39168
	v_mfma_f32_16x16x32_bf16 v[20:23], v[186:189], v[242:245], v[20:23]
	v_mfma_f32_16x16x32_bf16 v[0:3], v[186:189], v[246:249], v[0:3]
	ds_read_b128 v[186:189], v202 offset:41472
	v_mfma_f32_16x16x32_bf16 v[16:19], v[190:193], v[242:245], v[16:19]
	v_mfma_f32_16x16x32_bf16 v[12:15], v[190:193], v[246:249], v[12:15]
	ds_read_b128 v[190:193], v202 offset:43776
	s_branch .Lgm13_main

; DI f32x4 mfma16(bf16x8 a, bf16x8 b, f32x4 c) { return __builtin_amdgcn_mfma_f32_16x16x32_bf16(a, b, c, 0, 0, 0); }
; template <int MI, int NJ, bool SWAP, class AP, class BP>
; DI void gemm_main(f32x4 (&acc)[MI][NJ], const AP& ap, int a_kstep, const BP& bp, int b_kstep, int nk, bf16_t* smem) {
;     ...
;   auto gload = [&](int kt) {
;     const bf16_t* ab = ap.base + (size_t)kt * a_kstep; const bf16_t* bb = bp.base + (size_t)kt * b_kstep;
; #pragma unroll
;     for (int i = 0; i < CA; ++i) ra[i] = *(const u32x4*)(ab + pa[i]);
; #pragma unroll
;     for (int i = 0; i < CB; ++i) rb[i] = *(const u32x4*)(bb + pb[i]);
;   };
;   auto sstore = [&](int buf) {
;     bf16_t* As = smem + buf * L::STAGE; bf16_t* Bs = As + L::A_ELEMS;
; #pragma unroll
;     for (int i = 0; i < CA; ++i) { const int c = tid + NTHR * i; *(u32x4*)(As + (c >> 3) * LDT + (c & 7) * 8) = oka[i] ? ra[i] : (u32x4){0u, 0u, 0u, 0u}; }
; #pragma unroll
;     for (int i = 0; i < CB; ++i) { const int c = tid + NTHR * i; *(u32x4*)(Bs + (c >> 3) * LDT + (c & 7) * 8) = rb[i]; }
;   };
;   gload(0); sstore(0); gload(nk > 1 ? 1 : 0); __syncthreads();
; #pragma unroll 1
;   for (int kt = 0; kt < nk; ++kt) {
;     const int buf = kt & 1;
;     sstore(buf ^ 1);
;     gload(kt + 2 < nk ? kt + 2 : nk - 1);
;     __builtin_amdgcn_sched_barrier(0);
;     const bf16_t* As = smem + buf * L::STAGE + (wm * 16 * MI + l15) * LDT + quad * 8;
;     const bf16_t* Bs = smem + buf * L::STAGE + L::A_ELEMS + (wn * 16 * NJ + l15) * LDT + quad * 8;
; #pragma unroll
;     for (int ks = 0; ks < 2; ++ks) {
;       if (MI * NJ >= 32 && ks == 1) asm volatile("" ::: "memory");
;       bf16x8 b[NJ];
; #pragma unroll
;       for (int j = 0; j < NJ; ++j) b[j] = *(const bf16x8*)(Bs + j * 16 * LDT + ks * 32);
; #pragma unroll
;       for (int i = 0; i < MI; ++i) {
;         const bf16x8 a = *(const bf16x8*)(As + i * 16 * LDT + ks * 32);
; #pragma unroll
;         for (int j = 0; j < NJ; ++j) acc[i][j] = SWAP ? mfma16(b[j], a, acc[i][j]) : mfma16(a, b[j], acc[i][j]);
;       }
;     }
;     __syncthreads();
;   }
.Lgm14_main:
	ds_read_b128 v[242:245], v181 offset:4608
	s_waitcnt lgkmcnt(4)
	v_mfma_f32_16x16x32_bf16 v[156:159], v[182:185], v[198:201], v[156:159]
	s_waitcnt lgkmcnt(3)
	v_mfma_f32_16x16x32_bf16 v[152:155], v[186:189], v[198:201], v[152:155]
	s_waitcnt lgkmcnt(2)
	v_mfma_f32_16x16x32_bf16 v[148:151], v[190:193], v[198:201], v[148:151]
	s_waitcnt vmcnt(7)
	v_cndmask_b32_e32 v143, 0, v143, vcc
	v_cndmask_b32_e32 v142, 0, v142, vcc
	v_cndmask_b32_e32 v141, 0, v141, vcc
	v_cndmask_b32_e32 v140, 0, v140, vcc
	s_and_b32 s46, s43, 1
	s_min_u32 s44, s43, 13
	s_xor_b32 s45, s46, 1
	s_mul_i32 s45, s45, 0x12000
	v_add3_u32 v250, s45, v172, v169
	ds_write_b128 v250, v[140:143]
	s_waitcnt lgkmcnt(2)
	v_mfma_f32_16x16x32_bf16 v[144:147], v[194:197], v[198:201], v[144:147]
	ds_read_b128 v[246:249], v181 offset:6912
	v_mfma_f32_16x16x32_bf16 v[108:111], v[182:185], v[202:205], v[108:111]
	v_mfma_f32_16x16x32_bf16 v[104:107], v[186:189], v[202:205], v[104:107]
	v_mfma_f32_16x16x32_bf16 v[100:103], v[190:193], v[202:205], v[100:103]
	s_lshl_b32 s47, s44, 7
	s_add_u32 s44, s18, s47
	v_add3_u32 v251, s45, v173, v169
	v_add3_u32 v252, s45, v174, v169
	v_add3_u32 v253, s45, v175, v169
	s_addc_u32 s45, s19, 0
	s_nop 0
	global_load_dwordx4 v[140:143], v176, s[44:45] offset:256
	v_mfma_f32_16x16x32_bf16 v[96:99], v[194:197], v[202:205], v[96:99]
	ds_read_b128 v[198:201], v181 offset:9216
	s_waitcnt lgkmcnt(3)
	v_mfma_f32_16x16x32_bf16 v[92:95], v[182:185], v[242:245], v[92:95]
	s_waitcnt vmcnt(7)
	v_cndmask_b32_e64 v131, 0, v131, s[0:1]
	v_cndmask_b32_e64 v130, 0, v130, s[0:1]
	v_cndmask_b32_e64 v129, 0, v129, s[0:1]
	v_cndmask_b32_e64 v128, 0, v128, s[0:1]
	ds_write_b128 v251, v[128:131]
	v_mfma_f32_16x16x32_bf16 v[88:91], v[186:189], v[242:245], v[88:91]
	v_mfma_f32_16x16x32_bf16 v[84:87], v[190:193], v[242:245], v[84:87]
	v_mfma_f32_16x16x32_bf16 v[80:83], v[194:197], v[242:245], v[80:83]
	ds_read_b128 v[202:205], v181 offset:11520
	s_waitcnt lgkmcnt(3)
	v_mfma_f32_16x16x32_bf16 v[76:79], v[182:185], v[246:249], v[76:79]
	s_nop 0
	global_load_dwordx4 v[128:131], v177, s[44:45] offset:256
	v_mfma_f32_16x16x32_bf16 v[72:75], v[186:189], v[246:249], v[72:75]
	v_mfma_f32_16x16x32_bf16 v[68:71], v[190:193], v[246:249], v[68:71]
	s_waitcnt vmcnt(7)
	v_cndmask_b32_e64 v115, 0, v115, s[2:3]
	v_cndmask_b32_e64 v114, 0, v114, s[2:3]
	v_cndmask_b32_e64 v113, 0, v113, s[2:3]
	v_cndmask_b32_e64 v112, 0, v112, s[2:3]
	ds_write_b128 v252, v[112:115]
	v_mfma_f32_16x16x32_bf16 v[64:67], v[194:197], v[246:249], v[64:67]
	ds_read_b128 v[242:245], v181 offset:13824
	s_waitcnt lgkmcnt(4)
	v_mfma_f32_16x16x32_bf16 v[60:63], v[182:185], v[198:201], v[60:63]
	v_mfma_f32_16x16x32_bf16 v[56:59], v[186:189], v[198:201], v[56:59]
	v_mfma_f32_16x16x32_bf16 v[52:55], v[190:193], v[198:201], v[52:55]
	s_nop 0
	global_load_dwordx4 v[112:115], v178, s[44:45] offset:256
	v_mfma_f32_16x16x32_bf16 v[48:51], v[194:197], v[198:201], v[48:51]
	ds_read_b128 v[246:249], v181 offset:16128
	s_waitcnt lgkmcnt(3)
	v_mfma_f32_16x16x32_bf16 v[44:47], v[182:185], v[202:205], v[44:47]
	s_waitcnt vmcnt(7)
	v_cndmask_b32_e64 v135, 0, v135, s[4:5]
	v_cndmask_b32_e64 v134, 0, v134, s[4:5]
	v_cndmask_b32_e64 v133, 0, v133, s[4:5]
	v_cndmask_b32_e64 v132, 0, v132, s[4:5]
	ds_write_b128 v253, v[132:135]
	v_mfma_f32_16x16x32_bf16 v[40:43], v[186:189], v[202:205], v[40:43]
	v_mfma_f32_16x16x32_bf16 v[36:39], v[190:193], v[202:205], v[36:39]
	v_mfma_f32_16x16x32_bf16 v[32:35], v[194:197], v[202:205], v[32:35]
	ds_read_b128 v[198:201], v181 offset:64
	s_waitcnt lgkmcnt(3)
	v_mfma_f32_16x16x32_bf16 v[28:31], v[182:185], v[242:245], v[28:31]
	s_nop 0
	global_load_dwordx4 v[132:135], v179, s[44:45] offset:256
	v_mfma_f32_16x16x32_bf16 v[24:27], v[186:189], v[242:245], v[24:27]
	v_mfma_f32_16x16x32_bf16 v[20:23], v[190:193], v[242:245], v[20:23]
	s_waitcnt vmcnt(7)
	ds_write_b128 v250, v[116:119] offset:36864
	v_mfma_f32_16x16x32_bf16 v[12:15], v[194:197], v[242:245], v[12:15]
	ds_read_b128 v[202:205], v181 offset:2368
	s_waitcnt lgkmcnt(4)
; DI f32x4 mfma16(bf16x8 a, bf16x8 b, f32x4 c) { return __builtin_amdgcn_mfma_f32_16x16x32_bf16(a, b, c, 0, 0, 0); }
; template <int MI, int NJ, bool SWAP, class AP, class BP>
; DI void gemm_main(f32x4 (&acc)[MI][NJ], const AP& ap, int a_kstep, const BP& bp, int b_kstep, int nk, bf16_t* smem) {
;     ...
;   auto gload = [&](int kt) {
;     const bf16_t* ab = ap.base + (size_t)kt * a_kstep; const bf16_t* bb = bp.base + (size_t)kt * b_kstep;
; #pragma unroll
;     for (int i = 0; i < CA; ++i) ra[i] = *(const u32x4*)(ab + pa[i]);
; #pragma unroll
;     for (int i = 0; i < CB; ++i) rb[i] = *(const u32x4*)(bb + pb[i]);
;   };
;   auto sstore = [&](int buf) {
;     bf16_t* As = smem + buf * L::STAGE; bf16_t* Bs = As + L::A_ELEMS;
; #pragma unroll
;     for (int i = 0; i < CA; ++i) { const int c = tid + NTHR * i; *(u32x4*)(As + (c >> 3) * LDT + (c & 7) * 8) = oka[i] ? ra[i] : (u32x4){0u, 0u, 0u, 0u}; }
; #pragma unroll
;     for (int i = 0; i < CB; ++i) { const int c = tid + NTHR * i; *(u32x4*)(Bs + (c >> 3) * LDT + (c & 7) * 8) = rb[i]; }
;   };
;   gload(0); sstore(0); gload(nk > 1 ? 1 : 0); __syncthreads();
; #pragma unroll 1
;   for (int kt = 0; kt < nk; ++kt) {
;     const int buf = kt & 1;
;     sstore(buf ^ 1);
;     gload(kt + 2 < nk ? kt + 2 : nk - 1);
;     __builtin_amdgcn_sched_barrier(0);
;     const bf16_t* As = smem + buf * L::STAGE + (wm * 16 * MI + l15) * LDT + quad * 8;
;     const bf16_t* Bs = smem + buf * L::STAGE + L::A_ELEMS + (wn * 16 * NJ + l15) * LDT + quad * 8;
; #pragma unroll
;     for (int ks = 0; ks < 2; ++ks) {
;       if (MI * NJ >= 32 && ks == 1) asm volatile("" ::: "memory");
;       bf16x8 b[NJ];
; #pragma unroll
;       for (int j = 0; j < NJ; ++j) b[j] = *(const bf16x8*)(Bs + j * 16 * LDT + ks * 32);
; #pragma unroll
;       for (int i = 0; i < MI; ++i) {
;         const bf16x8 a = *(const bf16x8*)(As + i * 16 * LDT + ks * 32);
; #pragma unroll
;         for (int j = 0; j < NJ; ++j) acc[i][j] = SWAP ? mfma16(b[j], a, acc[i][j]) : mfma16(a, b[j], acc[i][j]);
;       }
;     }
;     __syncthreads();
;   }
	v_mfma_f32_16x16x32_bf16 v[8:11], v[182:185], v[246:249], v[8:11]
	ds_read_b128 v[182:185], v206 offset:36928
	v_mfma_f32_16x16x32_bf16 v[4:7], v[186:189], v[246:249], v[4:7]
	ds_read_b128 v[186:189], v206 offset:39232
	v_mfma_f32_16x16x32_bf16 v[0:3], v[190:193], v[246:249], v[0:3]
	ds_read_b128 v[190:193], v206 offset:41536
	s_add_u32 s44, s20, s47
	s_addc_u32 s45, s21, 0
	v_lshl_add_u64 v[116:117], v[160:161], 1, s[44:45]
	s_nop 0
	global_load_dwordx4 v[116:119], v[116:117], off offset:256
	v_mfma_f32_16x16x32_bf16 v[16:19], v[194:197], v[246:249], v[16:19]
	ds_read_b128 v[194:197], v206 offset:43840
	ds_read_b128 v[242:245], v181 offset:4672
	s_waitcnt lgkmcnt(4)
	v_mfma_f32_16x16x32_bf16 v[156:159], v[182:185], v[198:201], v[156:159]
	s_waitcnt vmcnt(7)
	ds_write_b128 v251, v[120:123] offset:36864
	s_waitcnt lgkmcnt(4)
	v_mfma_f32_16x16x32_bf16 v[152:155], v[186:189], v[198:201], v[152:155]
	s_waitcnt lgkmcnt(3)
	v_mfma_f32_16x16x32_bf16 v[148:151], v[190:193], v[198:201], v[148:151]
	s_waitcnt lgkmcnt(2)
	v_mfma_f32_16x16x32_bf16 v[144:147], v[194:197], v[198:201], v[144:147]
	ds_read_b128 v[246:249], v181 offset:6976
	v_mfma_f32_16x16x32_bf16 v[108:111], v[182:185], v[202:205], v[108:111]
	v_lshl_add_u64 v[120:121], v[162:163], 1, s[44:45]
	s_nop 0
	global_load_dwordx4 v[120:123], v[120:121], off offset:256
	v_mfma_f32_16x16x32_bf16 v[104:107], v[186:189], v[202:205], v[104:107]
	v_mfma_f32_16x16x32_bf16 v[100:103], v[190:193], v[202:205], v[100:103]
	s_waitcnt vmcnt(7)
	ds_write_b128 v252, v[124:127] offset:36864
	v_mfma_f32_16x16x32_bf16 v[96:99], v[194:197], v[202:205], v[96:99]
	ds_read_b128 v[198:201], v181 offset:9280
	s_waitcnt lgkmcnt(4)
	v_mfma_f32_16x16x32_bf16 v[92:95], v[182:185], v[242:245], v[92:95]
	v_mfma_f32_16x16x32_bf16 v[88:91], v[186:189], v[242:245], v[88:91]
	v_mfma_f32_16x16x32_bf16 v[84:87], v[190:193], v[242:245], v[84:87]
	v_lshl_add_u64 v[124:125], v[164:165], 1, s[44:45]
	s_nop 0
	global_load_dwordx4 v[124:127], v[124:125], off offset:256
	v_mfma_f32_16x16x32_bf16 v[80:83], v[194:197], v[242:245], v[80:83]
	ds_read_b128 v[202:205], v181 offset:11584
	s_waitcnt lgkmcnt(3)
	v_mfma_f32_16x16x32_bf16 v[76:79], v[182:185], v[246:249], v[76:79]
	s_waitcnt vmcnt(7)
	ds_write_b128 v253, v[136:139] offset:36864
	v_mfma_f32_16x16x32_bf16 v[72:75], v[186:189], v[246:249], v[72:75]
	v_mfma_f32_16x16x32_bf16 v[68:71], v[190:193], v[246:249], v[68:71]
	v_mfma_f32_16x16x32_bf16 v[64:67], v[194:197], v[246:249], v[64:67]
	ds_read_b128 v[242:245], v181 offset:13888
	s_waitcnt lgkmcnt(3)
	v_mfma_f32_16x16x32_bf16 v[60:63], v[182:185], v[198:201], v[60:63]
	v_lshl_add_u64 v[136:137], v[166:167], 1, s[44:45]
	s_nop 0
	global_load_dwordx4 v[136:139], v[136:137], off offset:256
	v_mfma_f32_16x16x32_bf16 v[56:59], v[186:189], v[198:201], v[56:59]
	v_mfma_f32_16x16x32_bf16 v[52:55], v[190:193], v[198:201], v[52:55]
	v_mfma_f32_16x16x32_bf16 v[48:51], v[194:197], v[198:201], v[48:51]
	ds_read_b128 v[246:249], v181 offset:16192
	s_waitcnt lgkmcnt(3)
	v_mfma_f32_16x16x32_bf16 v[44:47], v[182:185], v[202:205], v[44:47]
	v_mfma_f32_16x16x32_bf16 v[40:43], v[186:189], v[202:205], v[40:43]
	v_mfma_f32_16x16x32_bf16 v[36:39], v[190:193], v[202:205], v[36:39]
	v_mfma_f32_16x16x32_bf16 v[32:35], v[194:197], v[202:205], v[32:35]
	s_add_i32 s43, s43, 1
	s_and_b32 s98, s43, 1
	s_mul_i32 s98, s98, 0x12000
	v_add3_u32 v206, s98, v171, v180
	v_add3_u32 v181, s98, v170, v180
	s_cmp_lg_u32 s43, 16
	s_waitcnt lgkmcnt(0)
	s_barrier
	s_cbranch_scc0 .Lgm14_exit
	ds_read_b128 v[198:201], v181
	ds_read_b128 v[202:205], v181 offset:2304
	v_mfma_f32_16x16x32_bf16 v[28:31], v[182:185], v[242:245], v[28:31]
	v_mfma_f32_16x16x32_bf16 v[8:11], v[182:185], v[246:249], v[8:11]
	ds_read_b128 v[182:185], v206 offset:36864
	v_mfma_f32_16x16x32_bf16 v[24:27], v[186:189], v[242:245], v[24:27]
	v_mfma_f32_16x16x32_bf16 v[4:7], v[186:189], v[246:249], v[4:7]
	ds_read_b128 v[186:189], v206 offset:39168
	v_mfma_f32_16x16x32_bf16 v[20:23], v[190:193], v[242:245], v[20:23]
	v_mfma_f32_16x16x32_bf16 v[0:3], v[190:193], v[246:249], v[0:3]
	ds_read_b128 v[190:193], v206 offset:41472
	v_mfma_f32_16x16x32_bf16 v[12:15], v[194:197], v[242:245], v[12:15]
	v_mfma_f32_16x16x32_bf16 v[16:19], v[194:197], v[246:249], v[16:19]
	ds_read_b128 v[194:197], v206 offset:43776
	s_branch .Lgm14_main

; DI f32x4 mfma16(bf16x8 a, bf16x8 b, f32x4 c) { return __builtin_amdgcn_mfma_f32_16x16x32_bf16(a, b, c, 0, 0, 0); }
; template <int MI, int NJ, bool SWAP, class AP, class BP>
; DI void gemm_main(f32x4 (&acc)[MI][NJ], const AP& ap, int a_kstep, const BP& bp, int b_kstep, int nk, bf16_t* smem) {
;     ...
;   auto gload = [&](int kt) {
;     const bf16_t* ab = ap.base + (size_t)kt * a_kstep; const bf16_t* bb = bp.base + (size_t)kt * b_kstep;
; #pragma unroll
;     for (int i = 0; i < CA; ++i) ra[i] = *(const u32x4*)(ab + pa[i]);
; #pragma unroll
;     for (int i = 0; i < CB; ++i) rb[i] = *(const u32x4*)(bb + pb[i]);
;   };
;   auto sstore = [&](int buf) {
;     bf16_t* As = smem + buf * L::STAGE; bf16_t* Bs = As + L::A_ELEMS;
; #pragma unroll
;     for (int i = 0; i < CA; ++i) { const int c = tid + NTHR * i; *(u32x4*)(As + (c >> 3) * LDT + (c & 7) * 8) = oka[i] ? ra[i] : (u32x4){0u, 0u, 0u, 0u}; }
; #pragma unroll
;     for (int i = 0; i < CB; ++i) { const int c = tid + NTHR * i; *(u32x4*)(Bs + (c >> 3) * LDT + (c & 7) * 8) = rb[i]; }
;   };
;   gload(0); sstore(0); gload(nk > 1 ? 1 : 0); __syncthreads();
; #pragma unroll 1
;   for (int kt = 0; kt < nk; ++kt) {
;     const int buf = kt & 1;
;     sstore(buf ^ 1);
;     gload(kt + 2 < nk ? kt + 2 : nk - 1);
;     __builtin_amdgcn_sched_barrier(0);
;     const bf16_t* As = smem + buf * L::STAGE + (wm * 16 * MI + l15) * LDT + quad * 8;
;     const bf16_t* Bs = smem + buf * L::STAGE + L::A_ELEMS + (wn * 16 * NJ + l15) * LDT + quad * 8;
; #pragma unroll
;     for (int ks = 0; ks < 2; ++ks) {
;       if (MI * NJ >= 32 && ks == 1) asm volatile("" ::: "memory");
;       bf16x8 b[NJ];
; #pragma unroll
;       for (int j = 0; j < NJ; ++j) b[j] = *(const bf16x8*)(Bs + j * 16 * LDT + ks * 32);
; #pragma unroll
;       for (int i = 0; i < MI; ++i) {
;         const bf16x8 a = *(const bf16x8*)(As + i * 16 * LDT + ks * 32);
; #pragma unroll
;         for (int j = 0; j < NJ; ++j) acc[i][j] = SWAP ? mfma16(b[j], a, acc[i][j]) : mfma16(a, b[j], acc[i][j]);
;       }
;     }
;     __syncthreads();
;   }
.Lgm15_main:
	ds_read_b128 v[242:245], v177 offset:4608
	s_waitcnt lgkmcnt(4)
	v_mfma_f32_16x16x32_bf16 v[156:159], v[178:181], v[194:197], v[156:159]
	s_waitcnt lgkmcnt(3)
	v_mfma_f32_16x16x32_bf16 v[152:155], v[182:185], v[194:197], v[152:155]
	s_waitcnt lgkmcnt(2)
	v_mfma_f32_16x16x32_bf16 v[148:151], v[186:189], v[194:197], v[148:151]
	s_and_b32 s17, s16, 1
	s_min_u32 s18, s16, 41
	s_xor_b32 s19, s17, 1
	s_mul_i32 s19, s19, 0x12000
	v_add3_u32 v250, s19, v172, v170
	s_waitcnt vmcnt(7)
	ds_write_b128 v250, v[112:115]
	s_waitcnt lgkmcnt(2)
	v_mfma_f32_16x16x32_bf16 v[144:147], v[190:193], v[194:197], v[144:147]
	ds_read_b128 v[246:249], v177 offset:6912
	v_mfma_f32_16x16x32_bf16 v[108:111], v[178:181], v[198:201], v[108:111]
	v_mfma_f32_16x16x32_bf16 v[104:107], v[182:185], v[198:201], v[104:107]
	v_mfma_f32_16x16x32_bf16 v[100:103], v[186:189], v[198:201], v[100:103]
	s_lshl_b32 s20, s18, 7
	s_add_u32 s18, s2, s20
	v_add3_u32 v251, s19, v173, v170
	v_add3_u32 v252, s19, v174, v170
	v_add3_u32 v253, s19, v175, v170
	s_addc_u32 s19, s3, 0
	v_lshl_add_u64 v[112:113], s[18:19], 0, v[162:163]
	s_nop 0
	global_load_dwordx4 v[112:115], v[112:113], off offset:256
	v_mfma_f32_16x16x32_bf16 v[96:99], v[190:193], v[198:201], v[96:99]
	ds_read_b128 v[194:197], v177 offset:9216
	s_waitcnt lgkmcnt(3)
	v_mfma_f32_16x16x32_bf16 v[92:95], v[178:181], v[242:245], v[92:95]
	s_waitcnt vmcnt(7)
	ds_write_b128 v251, v[116:119]
	v_mfma_f32_16x16x32_bf16 v[88:91], v[182:185], v[242:245], v[88:91]
	v_mfma_f32_16x16x32_bf16 v[84:87], v[186:189], v[242:245], v[84:87]
	v_mfma_f32_16x16x32_bf16 v[80:83], v[190:193], v[242:245], v[80:83]
	ds_read_b128 v[198:201], v177 offset:11520
	s_waitcnt lgkmcnt(3)
	v_mfma_f32_16x16x32_bf16 v[76:79], v[178:181], v[246:249], v[76:79]
	v_lshl_add_u64 v[116:117], s[18:19], 0, v[164:165]
	s_nop 0
	global_load_dwordx4 v[116:119], v[116:117], off offset:256
	v_mfma_f32_16x16x32_bf16 v[72:75], v[182:185], v[246:249], v[72:75]
	v_mfma_f32_16x16x32_bf16 v[68:71], v[186:189], v[246:249], v[68:71]
	s_waitcnt vmcnt(7)
	ds_write_b128 v252, v[120:123]
	v_mfma_f32_16x16x32_bf16 v[64:67], v[190:193], v[246:249], v[64:67]
	ds_read_b128 v[242:245], v177 offset:13824
	s_waitcnt lgkmcnt(4)
	v_mfma_f32_16x16x32_bf16 v[60:63], v[178:181], v[194:197], v[60:63]
	v_mfma_f32_16x16x32_bf16 v[56:59], v[182:185], v[194:197], v[56:59]
	v_mfma_f32_16x16x32_bf16 v[52:55], v[186:189], v[194:197], v[52:55]
	v_lshl_add_u64 v[120:121], s[18:19], 0, v[166:167]
	s_nop 0
	global_load_dwordx4 v[120:123], v[120:121], off offset:256
	v_mfma_f32_16x16x32_bf16 v[48:51], v[190:193], v[194:197], v[48:51]
	ds_read_b128 v[246:249], v177 offset:16128
	s_waitcnt lgkmcnt(3)
	v_mfma_f32_16x16x32_bf16 v[44:47], v[178:181], v[198:201], v[44:47]
	s_waitcnt vmcnt(7)
	ds_write_b128 v253, v[124:127]
	v_mfma_f32_16x16x32_bf16 v[40:43], v[182:185], v[198:201], v[40:43]
	v_mfma_f32_16x16x32_bf16 v[36:39], v[186:189], v[198:201], v[36:39]
	v_mfma_f32_16x16x32_bf16 v[32:35], v[190:193], v[198:201], v[32:35]
	ds_read_b128 v[194:197], v177 offset:64
	s_waitcnt lgkmcnt(3)
	v_mfma_f32_16x16x32_bf16 v[28:31], v[178:181], v[242:245], v[28:31]
	v_lshl_add_u64 v[124:125], s[18:19], 0, v[168:169]
	s_nop 0
	global_load_dwordx4 v[124:127], v[124:125], off offset:256
	v_mfma_f32_16x16x32_bf16 v[24:27], v[182:185], v[242:245], v[24:27]
	v_mfma_f32_16x16x32_bf16 v[20:23], v[186:189], v[242:245], v[20:23]
	s_waitcnt vmcnt(7)
	ds_write_b128 v250, v[128:131] offset:36864
	v_mfma_f32_16x16x32_bf16 v[16:19], v[190:193], v[242:245], v[16:19]
	ds_read_b128 v[198:201], v177 offset:2368
	s_waitcnt lgkmcnt(4)
	v_mfma_f32_16x16x32_bf16 v[8:11], v[178:181], v[246:249], v[8:11]
	ds_read_b128 v[178:181], v202 offset:36928
	v_mfma_f32_16x16x32_bf16 v[4:7], v[182:185], v[246:249], v[4:7]
	ds_read_b128 v[182:185], v202 offset:39232
	v_mfma_f32_16x16x32_bf16 v[0:3], v[186:189], v[246:249], v[0:3]
	ds_read_b128 v[186:189], v202 offset:41536
	s_add_u32 s18, s4, s20
	s_addc_u32 s19, s5, 0
	v_lshl_add_u64 v[128:129], s[18:19], 0, v[162:163]
	s_nop 0
	global_load_dwordx4 v[128:131], v[128:129], off offset:256
	v_mfma_f32_16x16x32_bf16 v[12:15], v[190:193], v[246:249], v[12:15]
	ds_read_b128 v[190:193], v202 offset:43840
	ds_read_b128 v[242:245], v177 offset:4672
	s_waitcnt lgkmcnt(4)
; DI f32x4 mfma16(bf16x8 a, bf16x8 b, f32x4 c) { return __builtin_amdgcn_mfma_f32_16x16x32_bf16(a, b, c, 0, 0, 0); }
; template <int MI, int NJ, bool SWAP, class AP, class BP>
; DI void gemm_main(f32x4 (&acc)[MI][NJ], const AP& ap, int a_kstep, const BP& bp, int b_kstep, int nk, bf16_t* smem) {
;     ...
;   auto gload = [&](int kt) {
;     const bf16_t* ab = ap.base + (size_t)kt * a_kstep; const bf16_t* bb = bp.base + (size_t)kt * b_kstep;
; #pragma unroll
;     for (int i = 0; i < CA; ++i) ra[i] = *(const u32x4*)(ab + pa[i]);
; #pragma unroll
;     for (int i = 0; i < CB; ++i) rb[i] = *(const u32x4*)(bb + pb[i]);
;   };
;   auto sstore = [&](int buf) {
;     bf16_t* As = smem + buf * L::STAGE; bf16_t* Bs = As + L::A_ELEMS;
; #pragma unroll
;     for (int i = 0; i < CA; ++i) { const int c = tid + NTHR * i; *(u32x4*)(As + (c >> 3) * LDT + (c & 7) * 8) = oka[i] ? ra[i] : (u32x4){0u, 0u, 0u, 0u}; }
; #pragma unroll
;     for (int i = 0; i < CB; ++i) { const int c = tid + NTHR * i; *(u32x4*)(Bs + (c >> 3) * LDT + (c & 7) * 8) = rb[i]; }
;   };
;   gload(0); sstore(0); gload(nk > 1 ? 1 : 0); __syncthreads();
; #pragma unroll 1
;   for (int kt = 0; kt < nk; ++kt) {
;     const int buf = kt & 1;
;     sstore(buf ^ 1);
;     gload(kt + 2 < nk ? kt + 2 : nk - 1);
;     __builtin_amdgcn_sched_barrier(0);
;     const bf16_t* As = smem + buf * L::STAGE + (wm * 16 * MI + l15) * LDT + quad * 8;
;     const bf16_t* Bs = smem + buf * L::STAGE + L::A_ELEMS + (wn * 16 * NJ + l15) * LDT + quad * 8;
; #pragma unroll
;     for (int ks = 0; ks < 2; ++ks) {
;       if (MI * NJ >= 32 && ks == 1) asm volatile("" ::: "memory");
;       bf16x8 b[NJ];
; #pragma unroll
;       for (int j = 0; j < NJ; ++j) b[j] = *(const bf16x8*)(Bs + j * 16 * LDT + ks * 32);
; #pragma unroll
;       for (int i = 0; i < MI; ++i) {
;         const bf16x8 a = *(const bf16x8*)(As + i * 16 * LDT + ks * 32);
; #pragma unroll
;         for (int j = 0; j < NJ; ++j) acc[i][j] = SWAP ? mfma16(b[j], a, acc[i][j]) : mfma16(a, b[j], acc[i][j]);
;       }
;     }
;     __syncthreads();
;   }
	v_mfma_f32_16x16x32_bf16 v[156:159], v[178:181], v[194:197], v[156:159]
	s_waitcnt vmcnt(7)
	ds_write_b128 v251, v[132:135] offset:36864
	s_waitcnt lgkmcnt(4)
	v_mfma_f32_16x16x32_bf16 v[152:155], v[182:185], v[194:197], v[152:155]
	s_waitcnt lgkmcnt(3)
	v_mfma_f32_16x16x32_bf16 v[148:151], v[186:189], v[194:197], v[148:151]
	s_waitcnt lgkmcnt(2)
	v_mfma_f32_16x16x32_bf16 v[144:147], v[190:193], v[194:197], v[144:147]
	ds_read_b128 v[246:249], v177 offset:6976
	v_mfma_f32_16x16x32_bf16 v[108:111], v[178:181], v[198:201], v[108:111]
	v_lshl_add_u64 v[132:133], s[18:19], 0, v[164:165]
	s_nop 0
	global_load_dwordx4 v[132:135], v[132:133], off offset:256
	v_mfma_f32_16x16x32_bf16 v[104:107], v[182:185], v[198:201], v[104:107]
	v_mfma_f32_16x16x32_bf16 v[100:103], v[186:189], v[198:201], v[100:103]
	s_waitcnt vmcnt(7)
	ds_write_b128 v252, v[136:139] offset:36864
	v_mfma_f32_16x16x32_bf16 v[96:99], v[190:193], v[198:201], v[96:99]
	ds_read_b128 v[194:197], v177 offset:9280
	s_waitcnt lgkmcnt(4)
	v_mfma_f32_16x16x32_bf16 v[92:95], v[178:181], v[242:245], v[92:95]
	v_mfma_f32_16x16x32_bf16 v[88:91], v[182:185], v[242:245], v[88:91]
	v_mfma_f32_16x16x32_bf16 v[84:87], v[186:189], v[242:245], v[84:87]
	v_lshl_add_u64 v[136:137], s[18:19], 0, v[166:167]
	s_nop 0
	global_load_dwordx4 v[136:139], v[136:137], off offset:256
	v_mfma_f32_16x16x32_bf16 v[80:83], v[190:193], v[242:245], v[80:83]
	ds_read_b128 v[198:201], v177 offset:11584
	s_waitcnt lgkmcnt(3)
	v_mfma_f32_16x16x32_bf16 v[76:79], v[178:181], v[246:249], v[76:79]
	s_waitcnt vmcnt(7)
	ds_write_b128 v253, v[140:143] offset:36864
	v_mfma_f32_16x16x32_bf16 v[72:75], v[182:185], v[246:249], v[72:75]
	v_mfma_f32_16x16x32_bf16 v[68:71], v[186:189], v[246:249], v[68:71]
	v_mfma_f32_16x16x32_bf16 v[64:67], v[190:193], v[246:249], v[64:67]
	ds_read_b128 v[242:245], v177 offset:13888
	s_waitcnt lgkmcnt(3)
	v_mfma_f32_16x16x32_bf16 v[60:63], v[178:181], v[194:197], v[60:63]
	v_lshl_add_u64 v[140:141], s[18:19], 0, v[168:169]
	s_nop 0
	global_load_dwordx4 v[140:143], v[140:141], off offset:256
	v_mfma_f32_16x16x32_bf16 v[56:59], v[182:185], v[194:197], v[56:59]
	v_mfma_f32_16x16x32_bf16 v[52:55], v[186:189], v[194:197], v[52:55]
	v_mfma_f32_16x16x32_bf16 v[48:51], v[190:193], v[194:197], v[48:51]
	ds_read_b128 v[246:249], v177 offset:16192
	s_waitcnt lgkmcnt(3)
	v_mfma_f32_16x16x32_bf16 v[44:47], v[178:181], v[198:201], v[44:47]
	v_mfma_f32_16x16x32_bf16 v[40:43], v[182:185], v[198:201], v[40:43]
	v_mfma_f32_16x16x32_bf16 v[36:39], v[186:189], v[198:201], v[36:39]
	v_mfma_f32_16x16x32_bf16 v[32:35], v[190:193], v[198:201], v[32:35]
	s_add_i32 s16, s16, 1
	s_and_b32 s98, s16, 1
	s_mul_i32 s98, s98, 0x12000
	v_add3_u32 v202, s98, v160, v176
	v_add3_u32 v177, s98, v171, v176
	s_cmp_lg_u32 s16, 44
	s_waitcnt lgkmcnt(0)
	s_barrier
	s_cbranch_scc0 .Lgm15_exit
	ds_read_b128 v[194:197], v177
	ds_read_b128 v[198:201], v177 offset:2304
	v_mfma_f32_16x16x32_bf16 v[28:31], v[178:181], v[242:245], v[28:31]
	v_mfma_f32_16x16x32_bf16 v[8:11], v[178:181], v[246:249], v[8:11]
	ds_read_b128 v[178:181], v202 offset:36864
	v_mfma_f32_16x16x32_bf16 v[24:27], v[182:185], v[242:245], v[24:27]
	v_mfma_f32_16x16x32_bf16 v[4:7], v[182:185], v[246:249], v[4:7]
	ds_read_b128 v[182:185], v202 offset:39168
	v_mfma_f32_16x16x32_bf16 v[20:23], v[186:189], v[242:245], v[20:23]
	v_mfma_f32_16x16x32_bf16 v[0:3], v[186:189], v[246:249], v[0:3]
	ds_read_b128 v[186:189], v202 offset:41472
	v_mfma_f32_16x16x32_bf16 v[16:19], v[190:193], v[242:245], v[16:19]
	v_mfma_f32_16x16x32_bf16 v[12:15], v[190:193], v[246:249], v[12:15]
	ds_read_b128 v[190:193], v202 offset:43776
	s_branch .Lgm15_main
